# load-segment tail: vmcnt and lgkmcnt waits merged into one s_waitcnt (on top of the segment trim)
# speedup vs baseline: 1.0052x; 1.0052x over previous
;     __host__ __device__ bool next(int i, Unit& u) const { if (!b.next(i >> 1, u)) return false; u.sel = i & 1; return true; }
; #define PG8_STAGE(bufoff, gbase, voff) do { _Pragma("unroll") for (int _i = 0; _i < 2; ++_i) \
;         __builtin_amdgcn_global_load_lds((const unsigned*)((const char*)(gbase) + (voff)[_i]), (PG8_LAS unsigned*)(lds + (bufoff) + ldsw + _i * 8192), 16, 0, 0); } while (0)
; #define PG8_BAR __builtin_amdgcn_s_barrier()
;     __host__ __device__ bool next(int i, Unit& u) const {
;         const long L = (long)i * G + c; if (L >= nwg) return false;
;         int wgid = (int)L; { const int q = nwg / NXCD, r = nwg % NXCD, xcd = wgid % NXCD, off = wgid / NXCD; wgid = (xcd < r ? xcd * (q + 1) : r * (q + 1) + (xcd - r) * q) + off; }
;         const int nig = WGM * nN, gid = wgid / nig, fm = gid * WGM, gsz = (nM - fm) < WGM ? (nM - fm) : WGM;
;         u.pm = fm + ((wgid % nig) % gsz); u.pn = (wgid % nig) / gsz; u.sel = 0; return true;
; template <class Epi, class Sched, bool ALIGN_EPI = false, bool SP2 = false>
; __device__ __forceinline__ void gemm_phase(PG8_LAS unsigned char* lds, const Gemm g, const Sched& S, const Epi& E) {
;     ...
;         const bool has_next = S.next(ui + 1, nxt);
;         const char* nA = has_next ? PG8_ABASE(nxt) : cA; const char* nB = has_next ? PG8_BBASE(nxt) : cB;
;         for (int t = 0; t < nt; t += 2) {
;             const bool last = (t == nt - 2);
;             const char* a1 = cA + (size_t)(t + 1) * kstepA;
;             const char* a2 = last ? nA : cA + (size_t)(t + 2) * kstepA; const char* b2 = last ? nB : cB + (size_t)(t + 2) * kstep;
;             const char* a3 = a2 + kstepA; const char* b3 = b2 + kstep;
;             if (last && has_next) S.a_ready(nxt);
;             if constexpr (SP2) {
;             PG8_LDB(B0, 0, 0); PG8_LDB(B1, 0, 1); PG8_SCHED; PG8_LDA(At, 0, 0); PG8_STAGE(PG8_SA(1, 1), a1 + hstep, voffA);
;             PG8_WAIT_V(8); PG8_WAIT_L(0); PG8_BAR; PG8_MMA(0, 0, At, B0); PG8_MMA(0, 1, At, B1); PG8_BAR; PG8_SCHED;
;             if constexpr (Epi::PREFETCH) { if (t == tpf) E.prefetch(cur, wid, lane); }
;             PG8_LDA(At, 0, 1); PG8_STAGE(PG8_SB(0, 0), b2, voffB); PG8_STAGE(PG8_SB(0, 1), b2 + hstep, voffB); PG8_STAGE(PG8_SA(0, 0), a2, voffA);
;             PG8_WAIT_V(8); PG8_WAIT_L(0); PG8_BAR; PG8_MMA(1, 0, At, B0); PG8_MMA(1, 1, At, B1); PG8_BAR; PG8_SCHED;
.LBB0_205:
	s_add_u32 s22, s22, 0x40080
	s_addc_u32 s23, s23, 0
	s_add_u32 s52, s24, 0x100
	s_addc_u32 s53, s25, 0
	s_mov_b32 s54, -2
	ds_read_b128 v[154:157], v150
	ds_read_b128 v[158:161], v150 offset:1024
	ds_read_b128 v[162:165], v150 offset:2048
	ds_read_b128 v[166:169], v150 offset:3072
	ds_read_b128 v[170:173], v151
	ds_read_b128 v[174:177], v151 offset:1024
	ds_read_b128 v[178:181], v151 offset:2048
	ds_read_b128 v[182:185], v151 offset:3072
	s_add_u32 s24, s22, 0xfffc0080
	s_addc_u32 s25, s23, -1
	s_cmp_eq_u32 s54, 12
	s_cselect_b32 s27, s15, s25
	s_cselect_b32 s26, s50, s24
	s_cselect_b32 s25, s13, s53
	s_cselect_b32 s24, s51, s52
	v_lshl_add_u64 v[218:219], s[22:23], 0, v[140:141]
	s_add_i32 m0, s37, 0xc000
	ds_read_b128 v[186:189], v152
	ds_read_b128 v[190:193], v152 offset:1024
	ds_read_b128 v[194:197], v152 offset:2048
	ds_read_b128 v[198:201], v152 offset:3072
	ds_read_b128 v[202:205], v152 offset:4096
	ds_read_b128 v[206:209], v152 offset:5120
	ds_read_b128 v[210:213], v152 offset:6144
	ds_read_b128 v[214:217], v152 offset:7168
	global_load_lds_dwordx4 v[218:219], off
	v_lshl_add_u64 v[218:219], s[22:23], 0, v[142:143]
	s_add_i32 m0, s37, 0xe000
	s_nop 0
	global_load_lds_dwordx4 v[218:219], off
	s_add_i32 s44, s44, 1
	s_mul_i32 s0, s44, s46
	s_mul_hi_u32 s1, s44, s33
	s_add_i32 s1, s1, s0
	s_mul_i32 s0, s44, s33
	s_add_u32 s16, s0, s87
	s_addc_u32 s17, s1, s35
	v_cmp_lt_i64_e64 s[0:1], s[16:17], v[144:145]
	s_ashr_i32 s12, s16, 31
	s_lshr_b32 s12, s12, 29
	s_add_i32 s12, s16, s12
	s_ashr_i32 s13, s12, 3
	s_and_b32 s12, s12, -8
	s_sub_i32 s12, s16, s12
	s_cmp_lt_i32 s12, 0
	s_cselect_b32 s14, s36, 0x160
	s_mul_i32 s12, s12, s14
	s_add_i32 s12, s12, s13
	s_mul_hi_i32 s13, s12, 0x2e8ba2e9
	s_lshr_b32 s14, s13, 31
	s_ashr_i32 s13, s13, 3
	s_add_i32 s13, s13, s14
	s_lshl_b32 s14, s13, 1
	s_mul_i32 s13, s13, 44
	s_sub_i32 s13, s12, s13
	s_lshr_b32 s12, s13, 1
	s_and_b32 s13, s13, 1
	s_add_i32 s14, s14, s13
	s_ashr_i32 s15, s14, 31
	s_lshl_b64 s[16:17], s[14:15], 19
	s_add_u32 s16, s28, s16
	s_addc_u32 s17, s29, s17
	s_and_b64 s[18:19], s[0:1], exec
	s_cselect_b32 s15, s17, s29
	s_cselect_b32 s50, s16, s28
	s_ashr_i32 s13, s12, 31
	s_lshl_b64 s[18:19], s[12:13], 19
	s_add_u32 s18, s30, s18
	s_addc_u32 s19, s31, s19
	s_and_b64 s[98:99], s[0:1], exec
	s_cselect_b32 s13, s19, s31
	s_cselect_b32 s51, s18, s30
	s_waitcnt vmcnt(8) lgkmcnt(0)
	s_barrier
	s_setprio 1
	v_mfma_f32_16x16x32_bf16 v[126:129], v[154:157], v[186:189], 0
	v_mfma_f32_16x16x32_bf16 v[122:125], v[162:165], v[186:189], 0
	v_mfma_f32_16x16x32_bf16 v[110:113], v[154:157], v[194:197], 0
	v_mfma_f32_16x16x32_bf16 v[106:109], v[162:165], v[194:197], 0
	v_mfma_f32_16x16x32_bf16 v[94:97], v[154:157], v[202:205], 0
	v_mfma_f32_16x16x32_bf16 v[90:93], v[162:165], v[202:205], 0
	v_mfma_f32_16x16x32_bf16 v[78:81], v[154:157], v[210:213], 0
	v_mfma_f32_16x16x32_bf16 v[74:77], v[162:165], v[210:213], 0
	v_mfma_f32_16x16x32_bf16 v[126:129], v[158:161], v[190:193], v[126:129]
	v_mfma_f32_16x16x32_bf16 v[122:125], v[166:169], v[190:193], v[122:125]
	v_mfma_f32_16x16x32_bf16 v[110:113], v[158:161], v[198:201], v[110:113]
	v_mfma_f32_16x16x32_bf16 v[106:109], v[166:169], v[198:201], v[106:109]
	v_mfma_f32_16x16x32_bf16 v[94:97], v[158:161], v[206:209], v[94:97]
	v_mfma_f32_16x16x32_bf16 v[90:93], v[166:169], v[206:209], v[90:93]
	v_mfma_f32_16x16x32_bf16 v[78:81], v[158:161], v[214:217], v[78:81]
	v_mfma_f32_16x16x32_bf16 v[74:77], v[166:169], v[214:217], v[74:77]
	v_mfma_f32_16x16x32_bf16 v[118:121], v[170:173], v[186:189], 0
	v_mfma_f32_16x16x32_bf16 v[114:117], v[178:181], v[186:189], 0
	v_mfma_f32_16x16x32_bf16 v[102:105], v[170:173], v[194:197], 0
	v_mfma_f32_16x16x32_bf16 v[98:101], v[178:181], v[194:197], 0
	v_mfma_f32_16x16x32_bf16 v[86:89], v[170:173], v[202:205], 0
	v_mfma_f32_16x16x32_bf16 v[82:85], v[178:181], v[202:205], 0
	v_mfma_f32_16x16x32_bf16 v[70:73], v[170:173], v[210:213], 0
	v_mfma_f32_16x16x32_bf16 v[66:69], v[178:181], v[210:213], 0
	v_mfma_f32_16x16x32_bf16 v[118:121], v[174:177], v[190:193], v[118:121]
	v_mfma_f32_16x16x32_bf16 v[114:117], v[182:185], v[190:193], v[114:117]
	v_mfma_f32_16x16x32_bf16 v[102:105], v[174:177], v[198:201], v[102:105]
	v_mfma_f32_16x16x32_bf16 v[98:101], v[182:185], v[198:201], v[98:101]
	v_mfma_f32_16x16x32_bf16 v[86:89], v[174:177], v[206:209], v[86:89]
	v_mfma_f32_16x16x32_bf16 v[82:85], v[182:185], v[206:209], v[82:85]
	v_mfma_f32_16x16x32_bf16 v[70:73], v[174:177], v[214:217], v[70:73]
	v_mfma_f32_16x16x32_bf16 v[66:69], v[182:185], v[214:217], v[66:69]
	s_setprio 0
	s_barrier
	s_add_i32 s55, s47, s34
	v_lshl_add_u64 v[218:219], s[24:25], 0, v[134:135]
	s_mov_b32 m0, s55
	ds_read_b128 v[186:189], v152 offset:16384
	ds_read_b128 v[190:193], v152 offset:17408
	ds_read_b128 v[194:197], v152 offset:18432
	ds_read_b128 v[198:201], v152 offset:19456
	ds_read_b128 v[202:205], v152 offset:20480
	ds_read_b128 v[206:209], v152 offset:21504
	ds_read_b128 v[210:213], v152 offset:22528
	ds_read_b128 v[214:217], v152 offset:23552
	global_load_lds_dwordx4 v[218:219], off
	s_add_i32 m0, s55, 0x2000
	s_add_u32 s56, s24, 0x40000
	v_lshl_add_u64 v[222:223], s[24:25], 0, v[130:131]
	s_addc_u32 s57, s25, 0
	s_add_i32 s55, s48, s34
	global_load_lds_dwordx4 v[222:223], off
	v_lshl_add_u64 v[224:225], s[56:57], 0, v[134:135]
	s_mov_b32 m0, s55
	v_lshl_add_u64 v[226:227], s[26:27], 0, v[132:133]
	global_load_lds_dwordx4 v[224:225], off
	v_lshl_add_u64 v[224:225], s[56:57], 0, v[130:131]
	s_add_i32 m0, s55, 0x2000
	s_nop 0
	global_load_lds_dwordx4 v[224:225], off
	v_lshl_add_u64 v[224:225], s[26:27], 0, v[136:137]
	s_mov_b32 m0, s37
	s_nop 0
	global_load_lds_dwordx4 v[224:225], off
	s_mov_b32 m0, s38
	s_nop 0
	global_load_lds_dwordx4 v[226:227], off
	s_waitcnt vmcnt(8) lgkmcnt(0)
	s_barrier
; #define PG8_STAGE(bufoff, gbase, voff) do { _Pragma("unroll") for (int _i = 0; _i < 2; ++_i) \
;         __builtin_amdgcn_global_load_lds((const unsigned*)((const char*)(gbase) + (voff)[_i]), (PG8_LAS unsigned*)(lds + (bufoff) + ldsw + _i * 8192), 16, 0, 0); } while (0)
; #define PG8_LDA(dst, b, h) do { _Pragma("unroll") for (int m = 0; m < 4; ++m) _Pragma("unroll") for (int k = 0; k < 2; ++k) dst[m][k] = *(const PG8_LAS bf16x8*)(lds + PG8_SA(b, h) + aoff + m * 2048 + k * 1024); } while (0)
; #define PG8_LDB(dst, b, h) do { _Pragma("unroll") for (int n = 0; n < 2; ++n) _Pragma("unroll") for (int k = 0; k < 2; ++k) dst[n][k] = *(const PG8_LAS bf16x8*)(lds + PG8_SB(b, h) + boff + n * 2048 + k * 1024); } while (0)
; #define PG8_MMA(ai, bj, At, Bt) do { __builtin_amdgcn_s_setprio(1); _Pragma("unroll") for (int m = 0; m < 4; ++m) _Pragma("unroll") for (int n = 0; n < 2; ++n) _Pragma("unroll") for (int k = 0; k < 2; ++k) \
;         acc[ai][bj][m][n] = __builtin_amdgcn_mfma_f32_16x16x32_bf16(Bt[n][k], At[m][k], acc[ai][bj][m][n], 0, 0, 0); __builtin_amdgcn_s_setprio(0); } while (0)
; #define PG8_WAIT_V(n) asm volatile("s_waitcnt vmcnt(" #n ")" ::: "memory")
; #define PG8_WAIT_L(n) asm volatile("s_waitcnt lgkmcnt(" #n ")" ::: "memory")
; #define PG8_BAR __builtin_amdgcn_s_barrier()
; #define PG8_SCHED __builtin_amdgcn_sched_barrier(0)
;     __device__ __forceinline__ void prefetch(const Unit& u, int wid, int lane) const { epi_prefetch(scr, ssq, bias + (size_t)(u.pm >> 5) * NGU + u.pn * BM, u, wid, lane); }
; template <class Epi, class Sched, bool ALIGN_EPI = false, bool SP2 = false>
; __device__ __forceinline__ void gemm_phase(PG8_LAS unsigned char* lds, const Gemm g, const Sched& S, const Epi& E) {
;     ...
;             PG8_LDB(B0, 0, 0); PG8_LDB(B1, 0, 1); PG8_SCHED; PG8_LDA(At, 0, 0); PG8_STAGE(PG8_SA(1, 1), a1 + hstep, voffA);
;             PG8_WAIT_V(8); PG8_WAIT_L(0); PG8_BAR; PG8_MMA(0, 0, At, B0); PG8_MMA(0, 1, At, B1); PG8_BAR; PG8_SCHED;
;             if constexpr (Epi::PREFETCH) { if (t == tpf) E.prefetch(cur, wid, lane); }
;             PG8_LDA(At, 0, 1); PG8_STAGE(PG8_SB(0, 0), b2, voffB); PG8_STAGE(PG8_SB(0, 1), b2 + hstep, voffB); PG8_STAGE(PG8_SA(0, 0), a2, voffA);
;             PG8_WAIT_V(8); PG8_WAIT_L(0); PG8_BAR; PG8_MMA(1, 0, At, B0); PG8_MMA(1, 1, At, B1); PG8_BAR; PG8_SCHED;
	s_setprio 1
	v_mfma_f32_16x16x32_bf16 v[62:65], v[154:157], v[186:189], 0
	v_mfma_f32_16x16x32_bf16 v[58:61], v[162:165], v[186:189], 0
	v_mfma_f32_16x16x32_bf16 v[46:49], v[154:157], v[194:197], 0
	v_mfma_f32_16x16x32_bf16 v[42:45], v[162:165], v[194:197], 0
	v_mfma_f32_16x16x32_bf16 v[30:33], v[154:157], v[202:205], 0
	v_mfma_f32_16x16x32_bf16 v[26:29], v[162:165], v[202:205], 0
	v_mfma_f32_16x16x32_bf16 v[14:17], v[154:157], v[210:213], 0
	v_mfma_f32_16x16x32_bf16 v[10:13], v[162:165], v[210:213], 0
	v_mfma_f32_16x16x32_bf16 v[62:65], v[158:161], v[190:193], v[62:65]
	v_mfma_f32_16x16x32_bf16 v[58:61], v[166:169], v[190:193], v[58:61]
	v_mfma_f32_16x16x32_bf16 v[46:49], v[158:161], v[198:201], v[46:49]
	v_mfma_f32_16x16x32_bf16 v[42:45], v[166:169], v[198:201], v[42:45]
	v_mfma_f32_16x16x32_bf16 v[30:33], v[158:161], v[206:209], v[30:33]
	v_mfma_f32_16x16x32_bf16 v[26:29], v[166:169], v[206:209], v[26:29]
	v_mfma_f32_16x16x32_bf16 v[14:17], v[158:161], v[214:217], v[14:17]
	v_mfma_f32_16x16x32_bf16 v[10:13], v[166:169], v[214:217], v[10:13]
	v_mfma_f32_16x16x32_bf16 v[54:57], v[170:173], v[186:189], 0
	v_mfma_f32_16x16x32_bf16 v[50:53], v[178:181], v[186:189], 0
	v_mfma_f32_16x16x32_bf16 v[38:41], v[170:173], v[194:197], 0
	v_mfma_f32_16x16x32_bf16 v[34:37], v[178:181], v[194:197], 0
	v_mfma_f32_16x16x32_bf16 v[22:25], v[170:173], v[202:205], 0
	v_mfma_f32_16x16x32_bf16 v[18:21], v[178:181], v[202:205], 0
	v_mfma_f32_16x16x32_bf16 v[6:9], v[170:173], v[210:213], 0
	v_mfma_f32_16x16x32_bf16 v[2:5], v[178:181], v[210:213], 0
	v_mfma_f32_16x16x32_bf16 v[54:57], v[174:177], v[190:193], v[54:57]
	v_mfma_f32_16x16x32_bf16 v[50:53], v[182:185], v[190:193], v[50:53]
	v_mfma_f32_16x16x32_bf16 v[38:41], v[174:177], v[198:201], v[38:41]
	v_mfma_f32_16x16x32_bf16 v[34:37], v[182:185], v[198:201], v[34:37]
	v_mfma_f32_16x16x32_bf16 v[22:25], v[174:177], v[206:209], v[22:25]
	v_mfma_f32_16x16x32_bf16 v[18:21], v[182:185], v[206:209], v[18:21]
	v_mfma_f32_16x16x32_bf16 v[6:9], v[174:177], v[214:217], v[6:9]
	v_mfma_f32_16x16x32_bf16 v[2:5], v[182:185], v[214:217], v[2:5]
	s_setprio 0
	s_barrier
	s_branch .Lpz1_mid
.LBB0_208:
	ds_read_b128 v[154:157], v150
	ds_read_b128 v[158:161], v150 offset:1024
	ds_read_b128 v[162:165], v150 offset:2048
	ds_read_b128 v[166:169], v150 offset:3072
	ds_read_b128 v[170:173], v151
	ds_read_b128 v[174:177], v151 offset:1024
	ds_read_b128 v[178:181], v151 offset:2048
	ds_read_b128 v[182:185], v151 offset:3072
	s_add_u32 s24, s22, 0xfffc0080
	s_addc_u32 s25, s23, -1
	s_cmp_eq_u32 s54, 12
	s_cselect_b32 s27, s15, s25
	s_cselect_b32 s26, s50, s24
	s_cselect_b32 s25, s13, s53
	s_cselect_b32 s24, s51, s52
	v_lshl_add_u64 v[218:219], s[22:23], 0, v[140:141]
	s_add_i32 m0, s37, 0xc000
	ds_read_b128 v[186:189], v152
	ds_read_b128 v[190:193], v152 offset:1024
	ds_read_b128 v[194:197], v152 offset:2048
	ds_read_b128 v[198:201], v152 offset:3072
	ds_read_b128 v[202:205], v152 offset:4096
	ds_read_b128 v[206:209], v152 offset:5120
	ds_read_b128 v[210:213], v152 offset:6144
	ds_read_b128 v[214:217], v152 offset:7168
	global_load_lds_dwordx4 v[218:219], off
	v_lshl_add_u64 v[218:219], s[22:23], 0, v[142:143]
	s_add_i32 m0, s37, 0xe000
	s_nop 0
	global_load_lds_dwordx4 v[218:219], off
	s_waitcnt vmcnt(8) lgkmcnt(0)
	s_barrier
	s_setprio 1
	v_mfma_f32_16x16x32_bf16 v[126:129], v[154:157], v[186:189], v[126:129]
	v_mfma_f32_16x16x32_bf16 v[122:125], v[162:165], v[186:189], v[122:125]
	v_mfma_f32_16x16x32_bf16 v[110:113], v[154:157], v[194:197], v[110:113]
	v_mfma_f32_16x16x32_bf16 v[106:109], v[162:165], v[194:197], v[106:109]
	v_mfma_f32_16x16x32_bf16 v[94:97], v[154:157], v[202:205], v[94:97]
	v_mfma_f32_16x16x32_bf16 v[90:93], v[162:165], v[202:205], v[90:93]
	v_mfma_f32_16x16x32_bf16 v[78:81], v[154:157], v[210:213], v[78:81]
	v_mfma_f32_16x16x32_bf16 v[74:77], v[162:165], v[210:213], v[74:77]
	v_mfma_f32_16x16x32_bf16 v[126:129], v[158:161], v[190:193], v[126:129]
	v_mfma_f32_16x16x32_bf16 v[122:125], v[166:169], v[190:193], v[122:125]
	v_mfma_f32_16x16x32_bf16 v[110:113], v[158:161], v[198:201], v[110:113]
	v_mfma_f32_16x16x32_bf16 v[106:109], v[166:169], v[198:201], v[106:109]
	v_mfma_f32_16x16x32_bf16 v[94:97], v[158:161], v[206:209], v[94:97]
	v_mfma_f32_16x16x32_bf16 v[90:93], v[166:169], v[206:209], v[90:93]
	v_mfma_f32_16x16x32_bf16 v[78:81], v[158:161], v[214:217], v[78:81]
	v_mfma_f32_16x16x32_bf16 v[74:77], v[166:169], v[214:217], v[74:77]
	v_mfma_f32_16x16x32_bf16 v[118:121], v[170:173], v[186:189], v[118:121]
	v_mfma_f32_16x16x32_bf16 v[114:117], v[178:181], v[186:189], v[114:117]
	v_mfma_f32_16x16x32_bf16 v[102:105], v[170:173], v[194:197], v[102:105]
	v_mfma_f32_16x16x32_bf16 v[98:101], v[178:181], v[194:197], v[98:101]
	v_mfma_f32_16x16x32_bf16 v[86:89], v[170:173], v[202:205], v[86:89]
	v_mfma_f32_16x16x32_bf16 v[82:85], v[178:181], v[202:205], v[82:85]
	v_mfma_f32_16x16x32_bf16 v[70:73], v[170:173], v[210:213], v[70:73]
	v_mfma_f32_16x16x32_bf16 v[66:69], v[178:181], v[210:213], v[66:69]
	v_mfma_f32_16x16x32_bf16 v[118:121], v[174:177], v[190:193], v[118:121]
	v_mfma_f32_16x16x32_bf16 v[114:117], v[182:185], v[190:193], v[114:117]
	v_mfma_f32_16x16x32_bf16 v[102:105], v[174:177], v[198:201], v[102:105]
	v_mfma_f32_16x16x32_bf16 v[98:101], v[182:185], v[198:201], v[98:101]
	v_mfma_f32_16x16x32_bf16 v[86:89], v[174:177], v[206:209], v[86:89]
	v_mfma_f32_16x16x32_bf16 v[82:85], v[182:185], v[206:209], v[82:85]
	v_mfma_f32_16x16x32_bf16 v[70:73], v[174:177], v[214:217], v[70:73]
	v_mfma_f32_16x16x32_bf16 v[66:69], v[182:185], v[214:217], v[66:69]
	s_setprio 0
	s_barrier
; #define PG8_STAGE(bufoff, gbase, voff) do { _Pragma("unroll") for (int _i = 0; _i < 2; ++_i) \
;         __builtin_amdgcn_global_load_lds((const unsigned*)((const char*)(gbase) + (voff)[_i]), (PG8_LAS unsigned*)(lds + (bufoff) + ldsw + _i * 8192), 16, 0, 0); } while (0)
; #define PG8_LDA(dst, b, h) do { _Pragma("unroll") for (int m = 0; m < 4; ++m) _Pragma("unroll") for (int k = 0; k < 2; ++k) dst[m][k] = *(const PG8_LAS bf16x8*)(lds + PG8_SA(b, h) + aoff + m * 2048 + k * 1024); } while (0)
; #define PG8_LDB(dst, b, h) do { _Pragma("unroll") for (int n = 0; n < 2; ++n) _Pragma("unroll") for (int k = 0; k < 2; ++k) dst[n][k] = *(const PG8_LAS bf16x8*)(lds + PG8_SB(b, h) + boff + n * 2048 + k * 1024); } while (0)
; #define PG8_MMA(ai, bj, At, Bt) do { __builtin_amdgcn_s_setprio(1); _Pragma("unroll") for (int m = 0; m < 4; ++m) _Pragma("unroll") for (int n = 0; n < 2; ++n) _Pragma("unroll") for (int k = 0; k < 2; ++k) \
;         acc[ai][bj][m][n] = __builtin_amdgcn_mfma_f32_16x16x32_bf16(Bt[n][k], At[m][k], acc[ai][bj][m][n], 0, 0, 0); __builtin_amdgcn_s_setprio(0); } while (0)
; #define PG8_WAIT_V(n) asm volatile("s_waitcnt vmcnt(" #n ")" ::: "memory")
; #define PG8_WAIT_L(n) asm volatile("s_waitcnt lgkmcnt(" #n ")" ::: "memory")
; #define PG8_BAR __builtin_amdgcn_s_barrier()
; #define PG8_SCHED __builtin_amdgcn_sched_barrier(0)
; template <class Epi, class Sched, bool ALIGN_EPI = false, bool SP2 = false>
; __device__ __forceinline__ void gemm_phase(PG8_LAS unsigned char* lds, const Gemm g, const Sched& S, const Epi& E) {
;     ...
;             PG8_LDA(At, 0, 1); PG8_STAGE(PG8_SB(0, 0), b2, voffB); PG8_STAGE(PG8_SB(0, 1), b2 + hstep, voffB); PG8_STAGE(PG8_SA(0, 0), a2, voffA);
;             PG8_WAIT_V(8); PG8_WAIT_L(0); PG8_BAR; PG8_MMA(1, 0, At, B0); PG8_MMA(1, 1, At, B1); PG8_BAR; PG8_SCHED;
;             PG8_LDB(B0, 1, 0); PG8_LDB(B1, 1, 1); PG8_SCHED; PG8_LDA(At, 1, 0); PG8_STAGE(PG8_SA(0, 1), a2 + hstep, voffA);
;             PG8_WAIT_V(8); PG8_WAIT_L(0); PG8_BAR; PG8_MMA(0, 0, At, B0); PG8_MMA(0, 1, At, B1); PG8_BAR; PG8_SCHED;
	s_add_i32 s55, s47, s34
	v_lshl_add_u64 v[218:219], s[24:25], 0, v[134:135]
	s_mov_b32 m0, s55
	ds_read_b128 v[186:189], v152 offset:16384
	ds_read_b128 v[190:193], v152 offset:17408
	ds_read_b128 v[194:197], v152 offset:18432
	ds_read_b128 v[198:201], v152 offset:19456
	ds_read_b128 v[202:205], v152 offset:20480
	ds_read_b128 v[206:209], v152 offset:21504
	ds_read_b128 v[210:213], v152 offset:22528
	ds_read_b128 v[214:217], v152 offset:23552
	global_load_lds_dwordx4 v[218:219], off
	s_add_i32 m0, s55, 0x2000
	s_add_u32 s56, s24, 0x40000
	v_lshl_add_u64 v[222:223], s[24:25], 0, v[130:131]
	s_addc_u32 s57, s25, 0
	s_add_i32 s55, s48, s34
	global_load_lds_dwordx4 v[222:223], off
	v_lshl_add_u64 v[224:225], s[56:57], 0, v[134:135]
	s_mov_b32 m0, s55
	v_lshl_add_u64 v[226:227], s[26:27], 0, v[132:133]
	global_load_lds_dwordx4 v[224:225], off
	v_lshl_add_u64 v[224:225], s[56:57], 0, v[130:131]
	s_add_i32 m0, s55, 0x2000
	s_nop 0
	global_load_lds_dwordx4 v[224:225], off
	v_lshl_add_u64 v[224:225], s[26:27], 0, v[136:137]
	s_mov_b32 m0, s37
	s_nop 0
	global_load_lds_dwordx4 v[224:225], off
	s_mov_b32 m0, s38
	s_nop 0
	global_load_lds_dwordx4 v[226:227], off
	s_waitcnt vmcnt(8) lgkmcnt(0)
	s_barrier
	s_setprio 1
	v_mfma_f32_16x16x32_bf16 v[62:65], v[154:157], v[186:189], v[62:65]
	v_mfma_f32_16x16x32_bf16 v[58:61], v[162:165], v[186:189], v[58:61]
	v_mfma_f32_16x16x32_bf16 v[46:49], v[154:157], v[194:197], v[46:49]
	v_mfma_f32_16x16x32_bf16 v[42:45], v[162:165], v[194:197], v[42:45]
	v_mfma_f32_16x16x32_bf16 v[30:33], v[154:157], v[202:205], v[30:33]
	v_mfma_f32_16x16x32_bf16 v[26:29], v[162:165], v[202:205], v[26:29]
	v_mfma_f32_16x16x32_bf16 v[14:17], v[154:157], v[210:213], v[14:17]
	v_mfma_f32_16x16x32_bf16 v[10:13], v[162:165], v[210:213], v[10:13]
	v_mfma_f32_16x16x32_bf16 v[62:65], v[158:161], v[190:193], v[62:65]
	v_mfma_f32_16x16x32_bf16 v[58:61], v[166:169], v[190:193], v[58:61]
	v_mfma_f32_16x16x32_bf16 v[46:49], v[158:161], v[198:201], v[46:49]
	v_mfma_f32_16x16x32_bf16 v[42:45], v[166:169], v[198:201], v[42:45]
	v_mfma_f32_16x16x32_bf16 v[30:33], v[158:161], v[206:209], v[30:33]
	v_mfma_f32_16x16x32_bf16 v[26:29], v[166:169], v[206:209], v[26:29]
	v_mfma_f32_16x16x32_bf16 v[14:17], v[158:161], v[214:217], v[14:17]
	v_mfma_f32_16x16x32_bf16 v[10:13], v[166:169], v[214:217], v[10:13]
	v_mfma_f32_16x16x32_bf16 v[54:57], v[170:173], v[186:189], v[54:57]
	v_mfma_f32_16x16x32_bf16 v[50:53], v[178:181], v[186:189], v[50:53]
	v_mfma_f32_16x16x32_bf16 v[38:41], v[170:173], v[194:197], v[38:41]
	v_mfma_f32_16x16x32_bf16 v[34:37], v[178:181], v[194:197], v[34:37]
	v_mfma_f32_16x16x32_bf16 v[22:25], v[170:173], v[202:205], v[22:25]
	v_mfma_f32_16x16x32_bf16 v[18:21], v[178:181], v[202:205], v[18:21]
	v_mfma_f32_16x16x32_bf16 v[6:9], v[170:173], v[210:213], v[6:9]
	v_mfma_f32_16x16x32_bf16 v[2:5], v[178:181], v[210:213], v[2:5]
	v_mfma_f32_16x16x32_bf16 v[54:57], v[174:177], v[190:193], v[54:57]
	v_mfma_f32_16x16x32_bf16 v[50:53], v[182:185], v[190:193], v[50:53]
	v_mfma_f32_16x16x32_bf16 v[38:41], v[174:177], v[198:201], v[38:41]
	v_mfma_f32_16x16x32_bf16 v[34:37], v[182:185], v[198:201], v[34:37]
	v_mfma_f32_16x16x32_bf16 v[22:25], v[174:177], v[206:209], v[22:25]
	v_mfma_f32_16x16x32_bf16 v[18:21], v[182:185], v[206:209], v[18:21]
	v_mfma_f32_16x16x32_bf16 v[6:9], v[174:177], v[214:217], v[6:9]
	v_mfma_f32_16x16x32_bf16 v[2:5], v[182:185], v[214:217], v[2:5]
	s_setprio 0
	s_barrier
.Lpz1_mid:
	s_add_i32 s55, 0, 0x18000
	v_add_u32_e32 v138, s55, v149
	s_add_i32 s56, 0, 0x1c000
	ds_read_b128 v[154:157], v138
	ds_read_b128 v[158:161], v138 offset:1024
	ds_read_b128 v[162:165], v138 offset:2048
	ds_read_b128 v[166:169], v138 offset:3072
	v_add_u32_e32 v138, s56, v149
	ds_read_b128 v[170:173], v138
	ds_read_b128 v[174:177], v138 offset:1024
	ds_read_b128 v[178:181], v138 offset:2048
	ds_read_b128 v[182:185], v138 offset:3072
	s_add_u32 s26, s26, 0x40000
	s_addc_u32 s27, s27, 0
	s_mov_b32 m0, s39
	v_lshl_add_u64 v[228:229], s[26:27], 0, v[136:137]
	ds_read_b128 v[186:189], v152 offset:32768
	ds_read_b128 v[190:193], v152 offset:33792
	ds_read_b128 v[194:197], v152 offset:34816
	ds_read_b128 v[198:201], v152 offset:35840
	ds_read_b128 v[202:205], v152 offset:36864
	ds_read_b128 v[206:209], v152 offset:37888
	ds_read_b128 v[210:213], v152 offset:38912
	ds_read_b128 v[214:217], v152 offset:39936
	global_load_lds_dwordx4 v[228:229], off
	v_lshl_add_u64 v[228:229], s[26:27], 0, v[132:133]
	s_mov_b32 m0, s40
	s_nop 0
	global_load_lds_dwordx4 v[228:229], off
	s_waitcnt vmcnt(8) lgkmcnt(0)
	s_barrier
; #define PG8_STAGE(bufoff, gbase, voff) do { _Pragma("unroll") for (int _i = 0; _i < 2; ++_i) \
;         __builtin_amdgcn_global_load_lds((const unsigned*)((const char*)(gbase) + (voff)[_i]), (PG8_LAS unsigned*)(lds + (bufoff) + ldsw + _i * 8192), 16, 0, 0); } while (0)
; #define PG8_LDA(dst, b, h) do { _Pragma("unroll") for (int m = 0; m < 4; ++m) _Pragma("unroll") for (int k = 0; k < 2; ++k) dst[m][k] = *(const PG8_LAS bf16x8*)(lds + PG8_SA(b, h) + aoff + m * 2048 + k * 1024); } while (0)
; #define PG8_LDB(dst, b, h) do { _Pragma("unroll") for (int n = 0; n < 2; ++n) _Pragma("unroll") for (int k = 0; k < 2; ++k) dst[n][k] = *(const PG8_LAS bf16x8*)(lds + PG8_SB(b, h) + boff + n * 2048 + k * 1024); } while (0)
; #define PG8_MMA(ai, bj, At, Bt) do { __builtin_amdgcn_s_setprio(1); _Pragma("unroll") for (int m = 0; m < 4; ++m) _Pragma("unroll") for (int n = 0; n < 2; ++n) _Pragma("unroll") for (int k = 0; k < 2; ++k) \
;         acc[ai][bj][m][n] = __builtin_amdgcn_mfma_f32_16x16x32_bf16(Bt[n][k], At[m][k], acc[ai][bj][m][n], 0, 0, 0); __builtin_amdgcn_s_setprio(0); } while (0)
; #define PG8_WAIT_V(n) asm volatile("s_waitcnt vmcnt(" #n ")" ::: "memory")
; #define PG8_WAIT_L(n) asm volatile("s_waitcnt lgkmcnt(" #n ")" ::: "memory")
; #define PG8_BAR __builtin_amdgcn_s_barrier()
; #define PG8_SCHED __builtin_amdgcn_sched_barrier(0)
; template <class Epi, class Sched, bool ALIGN_EPI = false, bool SP2 = false>
; __device__ __forceinline__ void gemm_phase(PG8_LAS unsigned char* lds, const Gemm g, const Sched& S, const Epi& E) {
;     ...
;             PG8_LDB(B0, 1, 0); PG8_LDB(B1, 1, 1); PG8_SCHED; PG8_LDA(At, 1, 0); PG8_STAGE(PG8_SA(0, 1), a2 + hstep, voffA);
;             PG8_WAIT_V(8); PG8_WAIT_L(0); PG8_BAR; PG8_MMA(0, 0, At, B0); PG8_MMA(0, 1, At, B1); PG8_BAR; PG8_SCHED;
;             PG8_LDA(At, 1, 1); PG8_STAGE(PG8_SB(1, 0), b3, voffB); PG8_STAGE(PG8_SB(1, 1), b3 + hstep, voffB); PG8_STAGE(PG8_SA(1, 0), a3, voffA);
;             PG8_WAIT_V(8); PG8_WAIT_L(0); PG8_BAR; PG8_MMA(1, 0, At, B0); PG8_MMA(1, 1, At, B1); PG8_BAR; PG8_SCHED;
;     ...
;         if constexpr (ALIGN_EPI) { if (wr == 0) PG8_BAR; }
	s_setprio 1
	v_mfma_f32_16x16x32_bf16 v[126:129], v[154:157], v[186:189], v[126:129]
	v_mfma_f32_16x16x32_bf16 v[122:125], v[162:165], v[186:189], v[122:125]
	v_mfma_f32_16x16x32_bf16 v[110:113], v[154:157], v[194:197], v[110:113]
	v_mfma_f32_16x16x32_bf16 v[106:109], v[162:165], v[194:197], v[106:109]
	v_mfma_f32_16x16x32_bf16 v[94:97], v[154:157], v[202:205], v[94:97]
	v_mfma_f32_16x16x32_bf16 v[90:93], v[162:165], v[202:205], v[90:93]
	v_mfma_f32_16x16x32_bf16 v[78:81], v[154:157], v[210:213], v[78:81]
	v_mfma_f32_16x16x32_bf16 v[74:77], v[162:165], v[210:213], v[74:77]
	v_mfma_f32_16x16x32_bf16 v[126:129], v[158:161], v[190:193], v[126:129]
	v_mfma_f32_16x16x32_bf16 v[122:125], v[166:169], v[190:193], v[122:125]
	v_mfma_f32_16x16x32_bf16 v[110:113], v[158:161], v[198:201], v[110:113]
	v_mfma_f32_16x16x32_bf16 v[106:109], v[166:169], v[198:201], v[106:109]
	v_mfma_f32_16x16x32_bf16 v[94:97], v[158:161], v[206:209], v[94:97]
	v_mfma_f32_16x16x32_bf16 v[90:93], v[166:169], v[206:209], v[90:93]
	v_mfma_f32_16x16x32_bf16 v[78:81], v[158:161], v[214:217], v[78:81]
	v_mfma_f32_16x16x32_bf16 v[74:77], v[166:169], v[214:217], v[74:77]
	v_mfma_f32_16x16x32_bf16 v[118:121], v[170:173], v[186:189], v[118:121]
	v_mfma_f32_16x16x32_bf16 v[114:117], v[178:181], v[186:189], v[114:117]
	v_mfma_f32_16x16x32_bf16 v[102:105], v[170:173], v[194:197], v[102:105]
	v_mfma_f32_16x16x32_bf16 v[98:101], v[178:181], v[194:197], v[98:101]
	v_mfma_f32_16x16x32_bf16 v[86:89], v[170:173], v[202:205], v[86:89]
	v_mfma_f32_16x16x32_bf16 v[82:85], v[178:181], v[202:205], v[82:85]
	v_mfma_f32_16x16x32_bf16 v[70:73], v[170:173], v[210:213], v[70:73]
	v_mfma_f32_16x16x32_bf16 v[66:69], v[178:181], v[210:213], v[66:69]
	v_mfma_f32_16x16x32_bf16 v[118:121], v[174:177], v[190:193], v[118:121]
	v_mfma_f32_16x16x32_bf16 v[114:117], v[182:185], v[190:193], v[114:117]
	v_mfma_f32_16x16x32_bf16 v[102:105], v[174:177], v[198:201], v[102:105]
	v_mfma_f32_16x16x32_bf16 v[98:101], v[182:185], v[198:201], v[98:101]
	v_mfma_f32_16x16x32_bf16 v[86:89], v[174:177], v[206:209], v[86:89]
	v_mfma_f32_16x16x32_bf16 v[82:85], v[182:185], v[206:209], v[82:85]
	v_mfma_f32_16x16x32_bf16 v[70:73], v[174:177], v[214:217], v[70:73]
	v_mfma_f32_16x16x32_bf16 v[66:69], v[182:185], v[214:217], v[66:69]
	s_setprio 0
	s_barrier
	s_add_i32 s26, s55, s34
	v_lshl_add_u64 v[218:219], v[218:219], 0, s[8:9]
	s_mov_b32 m0, s26
	ds_read_b128 v[186:189], v152 offset:49152
	ds_read_b128 v[190:193], v152 offset:50176
	ds_read_b128 v[194:197], v152 offset:51200
	ds_read_b128 v[198:201], v152 offset:52224
	ds_read_b128 v[202:205], v152 offset:53248
	ds_read_b128 v[206:209], v152 offset:54272
	ds_read_b128 v[210:213], v152 offset:55296
	ds_read_b128 v[214:217], v152 offset:56320
	global_load_lds_dwordx4 v[218:219], off
	s_add_i32 m0, s26, 0x2000
	s_add_u32 s24, s24, 0x40080
	v_lshl_add_u64 v[218:219], v[222:223], 0, s[8:9]
	s_addc_u32 s25, s25, 0
	s_add_i32 s26, s56, s34
	global_load_lds_dwordx4 v[218:219], off
	v_lshl_add_u64 v[218:219], s[24:25], 0, v[134:135]
	s_mov_b32 m0, s26
	s_nop 0
	global_load_lds_dwordx4 v[218:219], off
	v_lshl_add_u64 v[218:219], s[24:25], 0, v[130:131]
	s_add_i32 m0, s26, 0x2000
	s_nop 0
	global_load_lds_dwordx4 v[218:219], off
	v_lshl_add_u64 v[218:219], v[224:225], 0, s[8:9]
	s_mov_b32 m0, s42
	s_nop 0
	global_load_lds_dwordx4 v[218:219], off
	v_lshl_add_u64 v[218:219], v[226:227], 0, s[8:9]
	s_mov_b32 m0, s43
	s_nop 0
	global_load_lds_dwordx4 v[218:219], off
	s_waitcnt vmcnt(8) lgkmcnt(0)
	s_barrier
	s_setprio 1
	v_mfma_f32_16x16x32_bf16 v[62:65], v[154:157], v[186:189], v[62:65]
	v_mfma_f32_16x16x32_bf16 v[58:61], v[162:165], v[186:189], v[58:61]
	v_mfma_f32_16x16x32_bf16 v[46:49], v[154:157], v[194:197], v[46:49]
	v_mfma_f32_16x16x32_bf16 v[42:45], v[162:165], v[194:197], v[42:45]
	v_mfma_f32_16x16x32_bf16 v[30:33], v[154:157], v[202:205], v[30:33]
	v_mfma_f32_16x16x32_bf16 v[26:29], v[162:165], v[202:205], v[26:29]
	v_mfma_f32_16x16x32_bf16 v[14:17], v[154:157], v[210:213], v[14:17]
	v_mfma_f32_16x16x32_bf16 v[10:13], v[162:165], v[210:213], v[10:13]
	v_mfma_f32_16x16x32_bf16 v[62:65], v[158:161], v[190:193], v[62:65]
	v_mfma_f32_16x16x32_bf16 v[58:61], v[166:169], v[190:193], v[58:61]
	v_mfma_f32_16x16x32_bf16 v[46:49], v[158:161], v[198:201], v[46:49]
	v_mfma_f32_16x16x32_bf16 v[42:45], v[166:169], v[198:201], v[42:45]
	v_mfma_f32_16x16x32_bf16 v[30:33], v[158:161], v[206:209], v[30:33]
	v_mfma_f32_16x16x32_bf16 v[26:29], v[166:169], v[206:209], v[26:29]
	v_mfma_f32_16x16x32_bf16 v[14:17], v[158:161], v[214:217], v[14:17]
	v_mfma_f32_16x16x32_bf16 v[10:13], v[166:169], v[214:217], v[10:13]
	v_mfma_f32_16x16x32_bf16 v[54:57], v[170:173], v[186:189], v[54:57]
	v_mfma_f32_16x16x32_bf16 v[50:53], v[178:181], v[186:189], v[50:53]
	v_mfma_f32_16x16x32_bf16 v[38:41], v[170:173], v[194:197], v[38:41]
	v_mfma_f32_16x16x32_bf16 v[34:37], v[178:181], v[194:197], v[34:37]
	v_mfma_f32_16x16x32_bf16 v[22:25], v[170:173], v[202:205], v[22:25]
	v_mfma_f32_16x16x32_bf16 v[18:21], v[178:181], v[202:205], v[18:21]
	v_mfma_f32_16x16x32_bf16 v[6:9], v[170:173], v[210:213], v[6:9]
	v_mfma_f32_16x16x32_bf16 v[2:5], v[178:181], v[210:213], v[2:5]
	v_mfma_f32_16x16x32_bf16 v[54:57], v[174:177], v[190:193], v[54:57]
	v_mfma_f32_16x16x32_bf16 v[50:53], v[182:185], v[190:193], v[50:53]
	v_mfma_f32_16x16x32_bf16 v[38:41], v[174:177], v[198:201], v[38:41]
	v_mfma_f32_16x16x32_bf16 v[34:37], v[182:185], v[198:201], v[34:37]
	v_mfma_f32_16x16x32_bf16 v[22:25], v[174:177], v[206:209], v[22:25]
	v_mfma_f32_16x16x32_bf16 v[18:21], v[182:185], v[206:209], v[18:21]
	v_mfma_f32_16x16x32_bf16 v[6:9], v[174:177], v[214:217], v[6:9]
	v_mfma_f32_16x16x32_bf16 v[2:5], v[182:185], v[214:217], v[2:5]
	s_setprio 0
	s_barrier
	s_add_i32 s54, s54, 2
	s_add_u32 s22, s22, 0x100
	s_addc_u32 s23, s23, 0
	s_add_u32 s52, s52, 0x100
	s_addc_u32 s53, s53, 0
	s_cmp_gt_u32 s54, 13
	s_cbranch_scc0 .LBB0_208
	s_and_b64 vcc, exec, s[10:11]
	s_cbranch_vccz .LBB0_211
	s_barrier

; #define PG8_STAGE(bufoff, gbase, voff) do { _Pragma("unroll") for (int _i = 0; _i < 2; ++_i) \
;         __builtin_amdgcn_global_load_lds((const unsigned*)((const char*)(gbase) + (voff)[_i]), (PG8_LAS unsigned*)(lds + (bufoff) + ldsw + _i * 8192), 16, 0, 0); } while (0)
; #define PG8_LDA(dst, b, h) do { _Pragma("unroll") for (int m = 0; m < 4; ++m) _Pragma("unroll") for (int k = 0; k < 2; ++k) dst[m][k] = *(const PG8_LAS bf16x8*)(lds + PG8_SA(b, h) + aoff + m * 2048 + k * 1024); } while (0)
; #define PG8_LDB(dst, b, h) do { _Pragma("unroll") for (int n = 0; n < 2; ++n) _Pragma("unroll") for (int k = 0; k < 2; ++k) dst[n][k] = *(const PG8_LAS bf16x8*)(lds + PG8_SB(b, h) + boff + n * 2048 + k * 1024); } while (0)
; #define PG8_MMA(ai, bj, At, Bt) do { __builtin_amdgcn_s_setprio(1); _Pragma("unroll") for (int m = 0; m < 4; ++m) _Pragma("unroll") for (int n = 0; n < 2; ++n) _Pragma("unroll") for (int k = 0; k < 2; ++k) \
;         acc[ai][bj][m][n] = __builtin_amdgcn_mfma_f32_16x16x32_bf16(Bt[n][k], At[m][k], acc[ai][bj][m][n], 0, 0, 0); __builtin_amdgcn_s_setprio(0); } while (0)
; #define PG8_WAIT_V(n) asm volatile("s_waitcnt vmcnt(" #n ")" ::: "memory")
; template <class Epi, class Sched, bool ALIGN_EPI = false, bool SP2 = false>
; __device__ __forceinline__ void gemm_phase(PG8_LAS unsigned char* lds, const Gemm g, const Sched& S, const Epi& E) {
;     ...
;             const bool last = (t == nt - 2);
;             const char* a1 = cA + (size_t)(t + 1) * kstepA;
;             const char* a2 = last ? nA : cA + (size_t)(t + 2) * kstepA; const char* b2 = last ? nB : cB + (size_t)(t + 2) * kstep;
;             const char* a3 = a2 + kstepA; const char* b3 = b2 + kstep;
;             if (last && has_next) S.a_ready(nxt);
;             if constexpr (SP2) {
;             PG8_LDB(B0, 0, 0); PG8_LDB(B1, 0, 1); PG8_SCHED; PG8_LDA(At, 0, 0); PG8_STAGE(PG8_SA(1, 1), a1 + hstep, voffA);
;             PG8_WAIT_V(8); PG8_WAIT_L(0); PG8_BAR; PG8_MMA(0, 0, At, B0); PG8_MMA(0, 1, At, B1); PG8_BAR; PG8_SCHED;
;             if constexpr (Epi::PREFETCH) { if (t == tpf) E.prefetch(cur, wid, lane); }
;             PG8_LDA(At, 0, 1); PG8_STAGE(PG8_SB(0, 0), b2, voffB); PG8_STAGE(PG8_SB(0, 1), b2 + hstep, voffB); PG8_STAGE(PG8_SA(0, 0), a2, voffA);
;             PG8_WAIT_V(8); PG8_WAIT_L(0); PG8_BAR; PG8_MMA(1, 0, At, B0); PG8_MMA(1, 1, At, B1); PG8_BAR; PG8_SCHED;
.LBB0_288:
	s_add_u32 s39, s6, 0x100
	s_addc_u32 s40, s7, 0
	s_mov_b32 s41, -2
	ds_read_b128 v[130:133], v223
	ds_read_b128 v[134:137], v223 offset:1024
	ds_read_b128 v[138:141], v223 offset:2048
	ds_read_b128 v[142:145], v223 offset:3072
	ds_read_b128 v[164:167], v224
	ds_read_b128 v[168:171], v224 offset:1024
	ds_read_b128 v[172:175], v224 offset:2048
	ds_read_b128 v[176:179], v224 offset:3072
	s_add_u32 s0, s4, 0x200
	s_addc_u32 s1, s5, 0
	s_cmp_eq_u32 s41, 40
	s_cselect_b32 s37, s31, s1
	s_cselect_b32 s36, s30, s0
	s_cselect_b32 s7, s35, s40
	s_cselect_b32 s6, s34, s39
	v_lshl_add_u64 v[160:161], s[4:5], 0, v[156:157]
	s_add_i32 m0, s51, 0xc000
	ds_read_b128 v[180:183], v225
	ds_read_b128 v[184:187], v225 offset:1024
	ds_read_b128 v[188:191], v225 offset:2048
	ds_read_b128 v[192:195], v225 offset:3072
	ds_read_b128 v[196:199], v225 offset:4096
	ds_read_b128 v[200:203], v225 offset:5120
	ds_read_b128 v[204:207], v225 offset:6144
	ds_read_b128 v[208:211], v225 offset:7168
	global_load_lds_dwordx4 v[160:161], off
	v_lshl_add_u64 v[160:161], s[4:5], 0, v[158:159]
	s_add_i32 m0, s51, 0xe000
	s_nop 0
	global_load_lds_dwordx4 v[160:161], off
	s_waitcnt vmcnt(8) lgkmcnt(0)
	s_barrier
	s_setprio 1
	v_mfma_f32_16x16x32_bf16 v[126:129], v[130:133], v[180:183], 0
	v_mfma_f32_16x16x32_bf16 v[122:125], v[138:141], v[180:183], 0
	v_mfma_f32_16x16x32_bf16 v[110:113], v[130:133], v[188:191], 0
	v_mfma_f32_16x16x32_bf16 v[106:109], v[138:141], v[188:191], 0
	v_mfma_f32_16x16x32_bf16 v[94:97], v[130:133], v[196:199], 0
	v_mfma_f32_16x16x32_bf16 v[90:93], v[138:141], v[196:199], 0
	v_mfma_f32_16x16x32_bf16 v[78:81], v[130:133], v[204:207], 0
	v_mfma_f32_16x16x32_bf16 v[74:77], v[138:141], v[204:207], 0
	v_mfma_f32_16x16x32_bf16 v[126:129], v[134:137], v[184:187], v[126:129]
	v_mfma_f32_16x16x32_bf16 v[122:125], v[142:145], v[184:187], v[122:125]
	v_mfma_f32_16x16x32_bf16 v[110:113], v[134:137], v[192:195], v[110:113]
	v_mfma_f32_16x16x32_bf16 v[106:109], v[142:145], v[192:195], v[106:109]
	v_mfma_f32_16x16x32_bf16 v[94:97], v[134:137], v[200:203], v[94:97]
	v_mfma_f32_16x16x32_bf16 v[90:93], v[142:145], v[200:203], v[90:93]
	v_mfma_f32_16x16x32_bf16 v[78:81], v[134:137], v[208:211], v[78:81]
	v_mfma_f32_16x16x32_bf16 v[74:77], v[142:145], v[208:211], v[74:77]
	v_mfma_f32_16x16x32_bf16 v[118:121], v[164:167], v[180:183], 0
	v_mfma_f32_16x16x32_bf16 v[114:117], v[172:175], v[180:183], 0
	v_mfma_f32_16x16x32_bf16 v[102:105], v[164:167], v[188:191], 0
	v_mfma_f32_16x16x32_bf16 v[98:101], v[172:175], v[188:191], 0
	v_mfma_f32_16x16x32_bf16 v[86:89], v[164:167], v[196:199], 0
	v_mfma_f32_16x16x32_bf16 v[82:85], v[172:175], v[196:199], 0
	v_mfma_f32_16x16x32_bf16 v[70:73], v[164:167], v[204:207], 0
	v_mfma_f32_16x16x32_bf16 v[66:69], v[172:175], v[204:207], 0
	v_mfma_f32_16x16x32_bf16 v[118:121], v[168:171], v[184:187], v[118:121]
	v_mfma_f32_16x16x32_bf16 v[114:117], v[176:179], v[184:187], v[114:117]
	v_mfma_f32_16x16x32_bf16 v[102:105], v[168:171], v[192:195], v[102:105]
	v_mfma_f32_16x16x32_bf16 v[98:101], v[176:179], v[192:195], v[98:101]
	v_mfma_f32_16x16x32_bf16 v[86:89], v[168:171], v[200:203], v[86:89]
	v_mfma_f32_16x16x32_bf16 v[82:85], v[176:179], v[200:203], v[82:85]
	v_mfma_f32_16x16x32_bf16 v[70:73], v[168:171], v[208:211], v[70:73]
	v_mfma_f32_16x16x32_bf16 v[66:69], v[176:179], v[208:211], v[66:69]
	s_setprio 0
	s_barrier
	s_add_i32 s4, s68, s50
	v_lshl_add_u64 v[160:161], s[6:7], 0, v[148:149]
	s_mov_b32 m0, s4
	ds_read_b128 v[180:183], v225 offset:16384
	ds_read_b128 v[184:187], v225 offset:17408
	ds_read_b128 v[188:191], v225 offset:18432
	ds_read_b128 v[192:195], v225 offset:19456
	ds_read_b128 v[196:199], v225 offset:20480
	ds_read_b128 v[200:203], v225 offset:21504
	ds_read_b128 v[204:207], v225 offset:22528
	ds_read_b128 v[208:211], v225 offset:23552
	global_load_lds_dwordx4 v[160:161], off
	s_add_i32 m0, s4, 0x2000
	s_add_u32 s4, s6, 0xb0000
	v_lshl_add_u64 v[162:163], s[6:7], 0, v[152:153]
	s_addc_u32 s5, s7, 0
	s_add_i32 s42, s69, s50
	global_load_lds_dwordx4 v[162:163], off
	v_lshl_add_u64 v[212:213], s[4:5], 0, v[148:149]
	s_mov_b32 m0, s42
	v_lshl_add_u64 v[214:215], s[36:37], 0, v[150:151]
	global_load_lds_dwordx4 v[212:213], off
	v_lshl_add_u64 v[212:213], s[4:5], 0, v[152:153]
	s_add_i32 m0, s42, 0x2000
	s_nop 0
	global_load_lds_dwordx4 v[212:213], off
	v_lshl_add_u64 v[212:213], s[36:37], 0, v[146:147]
	s_mov_b32 m0, s51
	s_nop 0
	global_load_lds_dwordx4 v[212:213], off
	s_mov_b32 m0, s52
	s_nop 0
	global_load_lds_dwordx4 v[214:215], off
	s_waitcnt vmcnt(8) lgkmcnt(0)
	s_barrier
	s_setprio 1
	v_mfma_f32_16x16x32_bf16 v[62:65], v[130:133], v[180:183], 0
	v_mfma_f32_16x16x32_bf16 v[58:61], v[138:141], v[180:183], 0
	v_mfma_f32_16x16x32_bf16 v[46:49], v[130:133], v[188:191], 0
	v_mfma_f32_16x16x32_bf16 v[42:45], v[138:141], v[188:191], 0
	v_mfma_f32_16x16x32_bf16 v[30:33], v[130:133], v[196:199], 0
	v_mfma_f32_16x16x32_bf16 v[26:29], v[138:141], v[196:199], 0
	v_mfma_f32_16x16x32_bf16 v[14:17], v[130:133], v[204:207], 0
	v_mfma_f32_16x16x32_bf16 v[10:13], v[138:141], v[204:207], 0
	v_mfma_f32_16x16x32_bf16 v[62:65], v[134:137], v[184:187], v[62:65]
	v_mfma_f32_16x16x32_bf16 v[58:61], v[142:145], v[184:187], v[58:61]
	v_mfma_f32_16x16x32_bf16 v[46:49], v[134:137], v[192:195], v[46:49]
	v_mfma_f32_16x16x32_bf16 v[42:45], v[142:145], v[192:195], v[42:45]
	v_mfma_f32_16x16x32_bf16 v[30:33], v[134:137], v[200:203], v[30:33]
	v_mfma_f32_16x16x32_bf16 v[26:29], v[142:145], v[200:203], v[26:29]
	v_mfma_f32_16x16x32_bf16 v[14:17], v[134:137], v[208:211], v[14:17]
	v_mfma_f32_16x16x32_bf16 v[10:13], v[142:145], v[208:211], v[10:13]
	v_mfma_f32_16x16x32_bf16 v[54:57], v[164:167], v[180:183], 0
	v_mfma_f32_16x16x32_bf16 v[50:53], v[172:175], v[180:183], 0
	v_mfma_f32_16x16x32_bf16 v[38:41], v[164:167], v[188:191], 0
	v_mfma_f32_16x16x32_bf16 v[34:37], v[172:175], v[188:191], 0
	v_mfma_f32_16x16x32_bf16 v[22:25], v[164:167], v[196:199], 0
	v_mfma_f32_16x16x32_bf16 v[18:21], v[172:175], v[196:199], 0
	v_mfma_f32_16x16x32_bf16 v[6:9], v[164:167], v[204:207], 0
	v_mfma_f32_16x16x32_bf16 v[2:5], v[172:175], v[204:207], 0
	v_mfma_f32_16x16x32_bf16 v[54:57], v[168:171], v[184:187], v[54:57]
	v_mfma_f32_16x16x32_bf16 v[50:53], v[176:179], v[184:187], v[50:53]
	v_mfma_f32_16x16x32_bf16 v[38:41], v[168:171], v[192:195], v[38:41]
	v_mfma_f32_16x16x32_bf16 v[34:37], v[176:179], v[192:195], v[34:37]
	v_mfma_f32_16x16x32_bf16 v[22:25], v[168:171], v[200:203], v[22:25]
	v_mfma_f32_16x16x32_bf16 v[18:21], v[176:179], v[200:203], v[18:21]
	v_mfma_f32_16x16x32_bf16 v[6:9], v[168:171], v[208:211], v[6:9]
	v_mfma_f32_16x16x32_bf16 v[2:5], v[176:179], v[208:211], v[2:5]
	s_setprio 0
	s_barrier
	s_branch .Lpz2_mid
; #define PG8_STAGE(bufoff, gbase, voff) do { _Pragma("unroll") for (int _i = 0; _i < 2; ++_i) \
;         __builtin_amdgcn_global_load_lds((const unsigned*)((const char*)(gbase) + (voff)[_i]), (PG8_LAS unsigned*)(lds + (bufoff) + ldsw + _i * 8192), 16, 0, 0); } while (0)
; #define PG8_LDA(dst, b, h) do { _Pragma("unroll") for (int m = 0; m < 4; ++m) _Pragma("unroll") for (int k = 0; k < 2; ++k) dst[m][k] = *(const PG8_LAS bf16x8*)(lds + PG8_SA(b, h) + aoff + m * 2048 + k * 1024); } while (0)
; #define PG8_LDB(dst, b, h) do { _Pragma("unroll") for (int n = 0; n < 2; ++n) _Pragma("unroll") for (int k = 0; k < 2; ++k) dst[n][k] = *(const PG8_LAS bf16x8*)(lds + PG8_SB(b, h) + boff + n * 2048 + k * 1024); } while (0)
; #define PG8_MMA(ai, bj, At, Bt) do { __builtin_amdgcn_s_setprio(1); _Pragma("unroll") for (int m = 0; m < 4; ++m) _Pragma("unroll") for (int n = 0; n < 2; ++n) _Pragma("unroll") for (int k = 0; k < 2; ++k) \
;         acc[ai][bj][m][n] = __builtin_amdgcn_mfma_f32_16x16x32_bf16(Bt[n][k], At[m][k], acc[ai][bj][m][n], 0, 0, 0); __builtin_amdgcn_s_setprio(0); } while (0)
; #define PG8_WAIT_V(n) asm volatile("s_waitcnt vmcnt(" #n ")" ::: "memory")
; #define PG8_WAIT_L(n) asm volatile("s_waitcnt lgkmcnt(" #n ")" ::: "memory")
; #define PG8_BAR __builtin_amdgcn_s_barrier()
; #define PG8_SCHED __builtin_amdgcn_sched_barrier(0)
;     __device__ __forceinline__ void prefetch(const Unit& u, int wid, int lane) const { epi_prefetch(scr, ssq, bias + (size_t)(u.pm >> 5) * NGU + u.pn * BM, u, wid, lane); }
; template <class Epi, class Sched, bool ALIGN_EPI = false, bool SP2 = false>
; __device__ __forceinline__ void gemm_phase(PG8_LAS unsigned char* lds, const Gemm g, const Sched& S, const Epi& E) {
;     ...
;             PG8_LDB(B0, 0, 0); PG8_LDB(B1, 0, 1); PG8_SCHED; PG8_LDA(At, 0, 0); PG8_STAGE(PG8_SA(1, 1), a1 + hstep, voffA);
;             PG8_WAIT_V(8); PG8_WAIT_L(0); PG8_BAR; PG8_MMA(0, 0, At, B0); PG8_MMA(0, 1, At, B1); PG8_BAR; PG8_SCHED;
;             if constexpr (Epi::PREFETCH) { if (t == tpf) E.prefetch(cur, wid, lane); }
;             PG8_LDA(At, 0, 1); PG8_STAGE(PG8_SB(0, 0), b2, voffB); PG8_STAGE(PG8_SB(0, 1), b2 + hstep, voffB); PG8_STAGE(PG8_SA(0, 0), a2, voffA);
;             PG8_WAIT_V(8); PG8_WAIT_L(0); PG8_BAR; PG8_MMA(1, 0, At, B0); PG8_MMA(1, 1, At, B1); PG8_BAR; PG8_SCHED;
.LBB0_289:
	ds_read_b128 v[130:133], v223
	ds_read_b128 v[134:137], v223 offset:1024
	ds_read_b128 v[138:141], v223 offset:2048
	ds_read_b128 v[142:145], v223 offset:3072
	ds_read_b128 v[164:167], v224
	ds_read_b128 v[168:171], v224 offset:1024
	ds_read_b128 v[172:175], v224 offset:2048
	ds_read_b128 v[176:179], v224 offset:3072
	s_add_u32 s0, s4, 0x200
	s_addc_u32 s1, s5, 0
	s_cmp_eq_u32 s41, 40
	s_cselect_b32 s37, s31, s1
	s_cselect_b32 s36, s30, s0
	s_cselect_b32 s7, s35, s40
	s_cselect_b32 s6, s34, s39
	v_lshl_add_u64 v[160:161], s[4:5], 0, v[156:157]
	s_add_i32 m0, s51, 0xc000
	ds_read_b128 v[180:183], v225
	ds_read_b128 v[184:187], v225 offset:1024
	ds_read_b128 v[188:191], v225 offset:2048
	ds_read_b128 v[192:195], v225 offset:3072
	ds_read_b128 v[196:199], v225 offset:4096
	ds_read_b128 v[200:203], v225 offset:5120
	ds_read_b128 v[204:207], v225 offset:6144
	ds_read_b128 v[208:211], v225 offset:7168
	global_load_lds_dwordx4 v[160:161], off
	v_lshl_add_u64 v[160:161], s[4:5], 0, v[158:159]
	s_add_i32 m0, s51, 0xe000
	s_nop 0
	global_load_lds_dwordx4 v[160:161], off
	s_waitcnt vmcnt(8) lgkmcnt(0)
	s_barrier
	s_setprio 1
	v_mfma_f32_16x16x32_bf16 v[126:129], v[130:133], v[180:183], v[126:129]
	v_mfma_f32_16x16x32_bf16 v[122:125], v[138:141], v[180:183], v[122:125]
	v_mfma_f32_16x16x32_bf16 v[110:113], v[130:133], v[188:191], v[110:113]
	v_mfma_f32_16x16x32_bf16 v[106:109], v[138:141], v[188:191], v[106:109]
	v_mfma_f32_16x16x32_bf16 v[94:97], v[130:133], v[196:199], v[94:97]
	v_mfma_f32_16x16x32_bf16 v[90:93], v[138:141], v[196:199], v[90:93]
	v_mfma_f32_16x16x32_bf16 v[78:81], v[130:133], v[204:207], v[78:81]
	v_mfma_f32_16x16x32_bf16 v[74:77], v[138:141], v[204:207], v[74:77]
	v_mfma_f32_16x16x32_bf16 v[126:129], v[134:137], v[184:187], v[126:129]
	v_mfma_f32_16x16x32_bf16 v[122:125], v[142:145], v[184:187], v[122:125]
	v_mfma_f32_16x16x32_bf16 v[110:113], v[134:137], v[192:195], v[110:113]
	v_mfma_f32_16x16x32_bf16 v[106:109], v[142:145], v[192:195], v[106:109]
	v_mfma_f32_16x16x32_bf16 v[94:97], v[134:137], v[200:203], v[94:97]
	v_mfma_f32_16x16x32_bf16 v[90:93], v[142:145], v[200:203], v[90:93]
	v_mfma_f32_16x16x32_bf16 v[78:81], v[134:137], v[208:211], v[78:81]
	v_mfma_f32_16x16x32_bf16 v[74:77], v[142:145], v[208:211], v[74:77]
	v_mfma_f32_16x16x32_bf16 v[118:121], v[164:167], v[180:183], v[118:121]
	v_mfma_f32_16x16x32_bf16 v[114:117], v[172:175], v[180:183], v[114:117]
	v_mfma_f32_16x16x32_bf16 v[102:105], v[164:167], v[188:191], v[102:105]
	v_mfma_f32_16x16x32_bf16 v[98:101], v[172:175], v[188:191], v[98:101]
	v_mfma_f32_16x16x32_bf16 v[86:89], v[164:167], v[196:199], v[86:89]
	v_mfma_f32_16x16x32_bf16 v[82:85], v[172:175], v[196:199], v[82:85]
	v_mfma_f32_16x16x32_bf16 v[70:73], v[164:167], v[204:207], v[70:73]
	v_mfma_f32_16x16x32_bf16 v[66:69], v[172:175], v[204:207], v[66:69]
	v_mfma_f32_16x16x32_bf16 v[118:121], v[168:171], v[184:187], v[118:121]
	v_mfma_f32_16x16x32_bf16 v[114:117], v[176:179], v[184:187], v[114:117]
	v_mfma_f32_16x16x32_bf16 v[102:105], v[168:171], v[192:195], v[102:105]
	v_mfma_f32_16x16x32_bf16 v[98:101], v[176:179], v[192:195], v[98:101]
	v_mfma_f32_16x16x32_bf16 v[86:89], v[168:171], v[200:203], v[86:89]
	v_mfma_f32_16x16x32_bf16 v[82:85], v[176:179], v[200:203], v[82:85]
	v_mfma_f32_16x16x32_bf16 v[70:73], v[168:171], v[208:211], v[70:73]
	v_mfma_f32_16x16x32_bf16 v[66:69], v[176:179], v[208:211], v[66:69]
	s_setprio 0
	s_barrier
	s_add_i32 s4, s68, s50
	v_lshl_add_u64 v[160:161], s[6:7], 0, v[148:149]
	s_mov_b32 m0, s4
	ds_read_b128 v[180:183], v225 offset:16384
	ds_read_b128 v[184:187], v225 offset:17408
	ds_read_b128 v[188:191], v225 offset:18432
	ds_read_b128 v[192:195], v225 offset:19456
	ds_read_b128 v[196:199], v225 offset:20480
	ds_read_b128 v[200:203], v225 offset:21504
	ds_read_b128 v[204:207], v225 offset:22528
	ds_read_b128 v[208:211], v225 offset:23552
	global_load_lds_dwordx4 v[160:161], off
	s_add_i32 m0, s4, 0x2000
	s_add_u32 s4, s6, 0xb0000
	v_lshl_add_u64 v[162:163], s[6:7], 0, v[152:153]
	s_addc_u32 s5, s7, 0
	s_add_i32 s42, s69, s50
	global_load_lds_dwordx4 v[162:163], off
	v_lshl_add_u64 v[212:213], s[4:5], 0, v[148:149]
	s_mov_b32 m0, s42
	v_lshl_add_u64 v[214:215], s[36:37], 0, v[150:151]
	global_load_lds_dwordx4 v[212:213], off
	v_lshl_add_u64 v[212:213], s[4:5], 0, v[152:153]
	s_add_i32 m0, s42, 0x2000
	s_nop 0
	global_load_lds_dwordx4 v[212:213], off
	v_lshl_add_u64 v[212:213], s[36:37], 0, v[146:147]
	s_mov_b32 m0, s51
	s_nop 0
	global_load_lds_dwordx4 v[212:213], off
	s_mov_b32 m0, s52
	s_nop 0
	global_load_lds_dwordx4 v[214:215], off
	s_waitcnt vmcnt(8) lgkmcnt(0)
	s_barrier
	s_setprio 1
	v_mfma_f32_16x16x32_bf16 v[62:65], v[130:133], v[180:183], v[62:65]
	v_mfma_f32_16x16x32_bf16 v[58:61], v[138:141], v[180:183], v[58:61]
	v_mfma_f32_16x16x32_bf16 v[46:49], v[130:133], v[188:191], v[46:49]
	v_mfma_f32_16x16x32_bf16 v[42:45], v[138:141], v[188:191], v[42:45]
	v_mfma_f32_16x16x32_bf16 v[30:33], v[130:133], v[196:199], v[30:33]
	v_mfma_f32_16x16x32_bf16 v[26:29], v[138:141], v[196:199], v[26:29]
	v_mfma_f32_16x16x32_bf16 v[14:17], v[130:133], v[204:207], v[14:17]
	v_mfma_f32_16x16x32_bf16 v[10:13], v[138:141], v[204:207], v[10:13]
	v_mfma_f32_16x16x32_bf16 v[62:65], v[134:137], v[184:187], v[62:65]
	v_mfma_f32_16x16x32_bf16 v[58:61], v[142:145], v[184:187], v[58:61]
	v_mfma_f32_16x16x32_bf16 v[46:49], v[134:137], v[192:195], v[46:49]
	v_mfma_f32_16x16x32_bf16 v[42:45], v[142:145], v[192:195], v[42:45]
	v_mfma_f32_16x16x32_bf16 v[30:33], v[134:137], v[200:203], v[30:33]
	v_mfma_f32_16x16x32_bf16 v[26:29], v[142:145], v[200:203], v[26:29]
	v_mfma_f32_16x16x32_bf16 v[14:17], v[134:137], v[208:211], v[14:17]
	v_mfma_f32_16x16x32_bf16 v[10:13], v[142:145], v[208:211], v[10:13]
	v_mfma_f32_16x16x32_bf16 v[54:57], v[164:167], v[180:183], v[54:57]
	v_mfma_f32_16x16x32_bf16 v[50:53], v[172:175], v[180:183], v[50:53]
	v_mfma_f32_16x16x32_bf16 v[38:41], v[164:167], v[188:191], v[38:41]
	v_mfma_f32_16x16x32_bf16 v[34:37], v[172:175], v[188:191], v[34:37]
	v_mfma_f32_16x16x32_bf16 v[22:25], v[164:167], v[196:199], v[22:25]
	v_mfma_f32_16x16x32_bf16 v[18:21], v[172:175], v[196:199], v[18:21]
	v_mfma_f32_16x16x32_bf16 v[6:9], v[164:167], v[204:207], v[6:9]
	v_mfma_f32_16x16x32_bf16 v[2:5], v[172:175], v[204:207], v[2:5]
	v_mfma_f32_16x16x32_bf16 v[54:57], v[168:171], v[184:187], v[54:57]
	v_mfma_f32_16x16x32_bf16 v[50:53], v[176:179], v[184:187], v[50:53]
	v_mfma_f32_16x16x32_bf16 v[38:41], v[168:171], v[192:195], v[38:41]
	v_mfma_f32_16x16x32_bf16 v[34:37], v[176:179], v[192:195], v[34:37]
	v_mfma_f32_16x16x32_bf16 v[22:25], v[168:171], v[200:203], v[22:25]
	v_mfma_f32_16x16x32_bf16 v[18:21], v[176:179], v[200:203], v[18:21]
	v_mfma_f32_16x16x32_bf16 v[6:9], v[168:171], v[208:211], v[6:9]
	v_mfma_f32_16x16x32_bf16 v[2:5], v[176:179], v[208:211], v[2:5]
	s_setprio 0
	s_barrier
; #define PG8_STAGE(bufoff, gbase, voff) do { _Pragma("unroll") for (int _i = 0; _i < 2; ++_i) \
;         __builtin_amdgcn_global_load_lds((const unsigned*)((const char*)(gbase) + (voff)[_i]), (PG8_LAS unsigned*)(lds + (bufoff) + ldsw + _i * 8192), 16, 0, 0); } while (0)
; #define PG8_LDA(dst, b, h) do { _Pragma("unroll") for (int m = 0; m < 4; ++m) _Pragma("unroll") for (int k = 0; k < 2; ++k) dst[m][k] = *(const PG8_LAS bf16x8*)(lds + PG8_SA(b, h) + aoff + m * 2048 + k * 1024); } while (0)
; #define PG8_LDB(dst, b, h) do { _Pragma("unroll") for (int n = 0; n < 2; ++n) _Pragma("unroll") for (int k = 0; k < 2; ++k) dst[n][k] = *(const PG8_LAS bf16x8*)(lds + PG8_SB(b, h) + boff + n * 2048 + k * 1024); } while (0)
; #define PG8_MMA(ai, bj, At, Bt) do { __builtin_amdgcn_s_setprio(1); _Pragma("unroll") for (int m = 0; m < 4; ++m) _Pragma("unroll") for (int n = 0; n < 2; ++n) _Pragma("unroll") for (int k = 0; k < 2; ++k) \
;         acc[ai][bj][m][n] = __builtin_amdgcn_mfma_f32_16x16x32_bf16(Bt[n][k], At[m][k], acc[ai][bj][m][n], 0, 0, 0); __builtin_amdgcn_s_setprio(0); } while (0)
; #define PG8_WAIT_V(n) asm volatile("s_waitcnt vmcnt(" #n ")" ::: "memory")
; #define PG8_WAIT_L(n) asm volatile("s_waitcnt lgkmcnt(" #n ")" ::: "memory")
; #define PG8_BAR __builtin_amdgcn_s_barrier()
; #define PG8_SCHED __builtin_amdgcn_sched_barrier(0)
; template <class Epi, class Sched, bool ALIGN_EPI = false, bool SP2 = false>
; __device__ __forceinline__ void gemm_phase(PG8_LAS unsigned char* lds, const Gemm g, const Sched& S, const Epi& E) {
;     ...
;             PG8_LDB(B0, 1, 0); PG8_LDB(B1, 1, 1); PG8_SCHED; PG8_LDA(At, 1, 0); PG8_STAGE(PG8_SA(0, 1), a2 + hstep, voffA);
;             PG8_WAIT_V(8); PG8_WAIT_L(0); PG8_BAR; PG8_MMA(0, 0, At, B0); PG8_MMA(0, 1, At, B1); PG8_BAR; PG8_SCHED;
.Lpz2_mid:
	s_add_i32 s42, 0, 0x18000
	s_add_i32 s43, 0, 0x1c000
	v_add_u32_e32 v142, s42, v222
	v_add_u32_e32 v154, s43, v222
	ds_read_b128 v[130:133], v142
	ds_read_b128 v[134:137], v142 offset:1024
	ds_read_b128 v[138:141], v142 offset:2048
	ds_read_b128 v[142:145], v142 offset:3072
	ds_read_b128 v[164:167], v154
	ds_read_b128 v[168:171], v154 offset:1024
	ds_read_b128 v[172:175], v154 offset:2048
	ds_read_b128 v[176:179], v154 offset:3072
	s_add_u32 s4, s36, 0xb0000
	s_addc_u32 s5, s37, 0
	s_mov_b32 m0, s53
	v_lshl_add_u64 v[216:217], s[4:5], 0, v[146:147]
	ds_read_b128 v[180:183], v225 offset:32768
	ds_read_b128 v[184:187], v225 offset:33792
	ds_read_b128 v[188:191], v225 offset:34816
	ds_read_b128 v[192:195], v225 offset:35840
	ds_read_b128 v[196:199], v225 offset:36864
	ds_read_b128 v[200:203], v225 offset:37888
	ds_read_b128 v[204:207], v225 offset:38912
	ds_read_b128 v[208:211], v225 offset:39936
	global_load_lds_dwordx4 v[216:217], off
	v_lshl_add_u64 v[216:217], s[4:5], 0, v[150:151]
	s_mov_b32 m0, s54
	s_nop 0
	global_load_lds_dwordx4 v[216:217], off
	s_waitcnt vmcnt(8) lgkmcnt(0)
	s_barrier
	s_setprio 1
	v_mfma_f32_16x16x32_bf16 v[126:129], v[130:133], v[180:183], v[126:129]
	v_mfma_f32_16x16x32_bf16 v[122:125], v[138:141], v[180:183], v[122:125]
	v_mfma_f32_16x16x32_bf16 v[110:113], v[130:133], v[188:191], v[110:113]
	v_mfma_f32_16x16x32_bf16 v[106:109], v[138:141], v[188:191], v[106:109]
	v_mfma_f32_16x16x32_bf16 v[94:97], v[130:133], v[196:199], v[94:97]
	v_mfma_f32_16x16x32_bf16 v[90:93], v[138:141], v[196:199], v[90:93]
	v_mfma_f32_16x16x32_bf16 v[78:81], v[130:133], v[204:207], v[78:81]
	v_mfma_f32_16x16x32_bf16 v[74:77], v[138:141], v[204:207], v[74:77]
	v_mfma_f32_16x16x32_bf16 v[126:129], v[134:137], v[184:187], v[126:129]
	v_mfma_f32_16x16x32_bf16 v[122:125], v[142:145], v[184:187], v[122:125]
	v_mfma_f32_16x16x32_bf16 v[110:113], v[134:137], v[192:195], v[110:113]
	v_mfma_f32_16x16x32_bf16 v[106:109], v[142:145], v[192:195], v[106:109]
	v_mfma_f32_16x16x32_bf16 v[94:97], v[134:137], v[200:203], v[94:97]
	v_mfma_f32_16x16x32_bf16 v[90:93], v[142:145], v[200:203], v[90:93]
	v_mfma_f32_16x16x32_bf16 v[78:81], v[134:137], v[208:211], v[78:81]
	v_mfma_f32_16x16x32_bf16 v[74:77], v[142:145], v[208:211], v[74:77]
	v_mfma_f32_16x16x32_bf16 v[118:121], v[164:167], v[180:183], v[118:121]
	v_mfma_f32_16x16x32_bf16 v[114:117], v[172:175], v[180:183], v[114:117]
	v_mfma_f32_16x16x32_bf16 v[102:105], v[164:167], v[188:191], v[102:105]
	v_mfma_f32_16x16x32_bf16 v[98:101], v[172:175], v[188:191], v[98:101]
	v_mfma_f32_16x16x32_bf16 v[86:89], v[164:167], v[196:199], v[86:89]
	v_mfma_f32_16x16x32_bf16 v[82:85], v[172:175], v[196:199], v[82:85]
	v_mfma_f32_16x16x32_bf16 v[70:73], v[164:167], v[204:207], v[70:73]
	v_mfma_f32_16x16x32_bf16 v[66:69], v[172:175], v[204:207], v[66:69]
	v_mfma_f32_16x16x32_bf16 v[118:121], v[168:171], v[184:187], v[118:121]
	v_mfma_f32_16x16x32_bf16 v[114:117], v[176:179], v[184:187], v[114:117]
	v_mfma_f32_16x16x32_bf16 v[102:105], v[168:171], v[192:195], v[102:105]
	v_mfma_f32_16x16x32_bf16 v[98:101], v[176:179], v[192:195], v[98:101]
	v_mfma_f32_16x16x32_bf16 v[86:89], v[168:171], v[200:203], v[86:89]
	v_mfma_f32_16x16x32_bf16 v[82:85], v[176:179], v[200:203], v[82:85]
	v_mfma_f32_16x16x32_bf16 v[70:73], v[168:171], v[208:211], v[70:73]
	v_mfma_f32_16x16x32_bf16 v[66:69], v[176:179], v[208:211], v[66:69]
	s_setprio 0
	s_barrier
; #define PG8_STAGE(bufoff, gbase, voff) do { _Pragma("unroll") for (int _i = 0; _i < 2; ++_i) \
;         __builtin_amdgcn_global_load_lds((const unsigned*)((const char*)(gbase) + (voff)[_i]), (PG8_LAS unsigned*)(lds + (bufoff) + ldsw + _i * 8192), 16, 0, 0); } while (0)
; #define PG8_LDA(dst, b, h) do { _Pragma("unroll") for (int m = 0; m < 4; ++m) _Pragma("unroll") for (int k = 0; k < 2; ++k) dst[m][k] = *(const PG8_LAS bf16x8*)(lds + PG8_SA(b, h) + aoff + m * 2048 + k * 1024); } while (0)
; #define PG8_MMA(ai, bj, At, Bt) do { __builtin_amdgcn_s_setprio(1); _Pragma("unroll") for (int m = 0; m < 4; ++m) _Pragma("unroll") for (int n = 0; n < 2; ++n) _Pragma("unroll") for (int k = 0; k < 2; ++k) \
;         acc[ai][bj][m][n] = __builtin_amdgcn_mfma_f32_16x16x32_bf16(Bt[n][k], At[m][k], acc[ai][bj][m][n], 0, 0, 0); __builtin_amdgcn_s_setprio(0); } while (0)
; #define PG8_WAIT_V(n) asm volatile("s_waitcnt vmcnt(" #n ")" ::: "memory")
; #define PG8_WAIT_L(n) asm volatile("s_waitcnt lgkmcnt(" #n ")" ::: "memory")
; #define PG8_BAR __builtin_amdgcn_s_barrier()
; #define PG8_SCHED __builtin_amdgcn_sched_barrier(0)
; template <class Epi, class Sched, bool ALIGN_EPI = false, bool SP2 = false>
; __device__ __forceinline__ void gemm_phase(PG8_LAS unsigned char* lds, const Gemm g, const Sched& S, const Epi& E) {
;     ...
;             PG8_LDA(At, 1, 1); PG8_STAGE(PG8_SB(1, 0), b3, voffB); PG8_STAGE(PG8_SB(1, 1), b3 + hstep, voffB); PG8_STAGE(PG8_SA(1, 0), a3, voffA);
;             PG8_WAIT_V(8); PG8_WAIT_L(0); PG8_BAR; PG8_MMA(1, 0, At, B0); PG8_MMA(1, 1, At, B1); PG8_BAR; PG8_SCHED;
;     ...
;         }
;         if constexpr (ALIGN_EPI) { if (wr == 0) PG8_BAR; }
	s_add_i32 s4, s42, s50
	v_lshl_add_u64 v[160:161], v[160:161], 0, s[22:23]
	s_mov_b32 m0, s4
	ds_read_b128 v[180:183], v225 offset:49152
	ds_read_b128 v[184:187], v225 offset:50176
	ds_read_b128 v[188:191], v225 offset:51200
	ds_read_b128 v[192:195], v225 offset:52224
	ds_read_b128 v[196:199], v225 offset:53248
	ds_read_b128 v[200:203], v225 offset:54272
	ds_read_b128 v[204:207], v225 offset:55296
	ds_read_b128 v[208:211], v225 offset:56320
	global_load_lds_dwordx4 v[160:161], off
	s_add_i32 m0, s4, 0x2000
	s_add_u32 s4, s6, 0xb0080
	v_lshl_add_u64 v[160:161], v[162:163], 0, s[22:23]
	s_addc_u32 s5, s7, 0
	s_add_i32 s6, s43, s50
	global_load_lds_dwordx4 v[160:161], off
	v_lshl_add_u64 v[160:161], s[4:5], 0, v[148:149]
	s_mov_b32 m0, s6
	s_nop 0
	global_load_lds_dwordx4 v[160:161], off
	v_lshl_add_u64 v[160:161], s[4:5], 0, v[152:153]
	s_add_i32 m0, s6, 0x2000
	s_nop 0
	global_load_lds_dwordx4 v[160:161], off
	v_lshl_add_u64 v[160:161], v[212:213], 0, s[24:25]
	s_mov_b32 m0, s63
	s_nop 0
	global_load_lds_dwordx4 v[160:161], off
	v_lshl_add_u64 v[160:161], v[214:215], 0, s[24:25]
	s_mov_b32 m0, s64
	s_nop 0
	global_load_lds_dwordx4 v[160:161], off
	s_waitcnt vmcnt(8) lgkmcnt(0)
	s_barrier
	s_setprio 1
	v_mfma_f32_16x16x32_bf16 v[62:65], v[130:133], v[180:183], v[62:65]
	v_mfma_f32_16x16x32_bf16 v[58:61], v[138:141], v[180:183], v[58:61]
	v_mfma_f32_16x16x32_bf16 v[46:49], v[130:133], v[188:191], v[46:49]
	v_mfma_f32_16x16x32_bf16 v[42:45], v[138:141], v[188:191], v[42:45]
	v_mfma_f32_16x16x32_bf16 v[30:33], v[130:133], v[196:199], v[30:33]
	v_mfma_f32_16x16x32_bf16 v[26:29], v[138:141], v[196:199], v[26:29]
	v_mfma_f32_16x16x32_bf16 v[14:17], v[130:133], v[204:207], v[14:17]
	v_mfma_f32_16x16x32_bf16 v[10:13], v[138:141], v[204:207], v[10:13]
	v_mfma_f32_16x16x32_bf16 v[62:65], v[134:137], v[184:187], v[62:65]
	v_mfma_f32_16x16x32_bf16 v[58:61], v[142:145], v[184:187], v[58:61]
	v_mfma_f32_16x16x32_bf16 v[46:49], v[134:137], v[192:195], v[46:49]
	v_mfma_f32_16x16x32_bf16 v[42:45], v[142:145], v[192:195], v[42:45]
	v_mfma_f32_16x16x32_bf16 v[30:33], v[134:137], v[200:203], v[30:33]
	v_mfma_f32_16x16x32_bf16 v[26:29], v[142:145], v[200:203], v[26:29]
	v_mfma_f32_16x16x32_bf16 v[14:17], v[134:137], v[208:211], v[14:17]
	v_mfma_f32_16x16x32_bf16 v[10:13], v[142:145], v[208:211], v[10:13]
	v_mfma_f32_16x16x32_bf16 v[54:57], v[164:167], v[180:183], v[54:57]
	v_mfma_f32_16x16x32_bf16 v[50:53], v[172:175], v[180:183], v[50:53]
	v_mfma_f32_16x16x32_bf16 v[38:41], v[164:167], v[188:191], v[38:41]
	v_mfma_f32_16x16x32_bf16 v[34:37], v[172:175], v[188:191], v[34:37]
	v_mfma_f32_16x16x32_bf16 v[22:25], v[164:167], v[196:199], v[22:25]
	v_mfma_f32_16x16x32_bf16 v[18:21], v[172:175], v[196:199], v[18:21]
	v_mfma_f32_16x16x32_bf16 v[6:9], v[164:167], v[204:207], v[6:9]
	v_mfma_f32_16x16x32_bf16 v[2:5], v[172:175], v[204:207], v[2:5]
	v_mfma_f32_16x16x32_bf16 v[54:57], v[168:171], v[184:187], v[54:57]
	v_mfma_f32_16x16x32_bf16 v[50:53], v[176:179], v[184:187], v[50:53]
	v_mfma_f32_16x16x32_bf16 v[38:41], v[168:171], v[192:195], v[38:41]
	v_mfma_f32_16x16x32_bf16 v[34:37], v[176:179], v[192:195], v[34:37]
	v_mfma_f32_16x16x32_bf16 v[22:25], v[168:171], v[200:203], v[22:25]
	v_mfma_f32_16x16x32_bf16 v[18:21], v[176:179], v[200:203], v[18:21]
	v_mfma_f32_16x16x32_bf16 v[6:9], v[168:171], v[208:211], v[6:9]
	v_mfma_f32_16x16x32_bf16 v[2:5], v[176:179], v[208:211], v[2:5]
	s_setprio 0
	s_barrier
	s_add_i32 s41, s41, 2
	s_add_u32 s39, s39, 0x100
	s_addc_u32 s40, s40, 0
	s_cmp_gt_u32 s41, 41
	s_mov_b64 s[4:5], s[0:1]
	s_cbranch_scc0 .LBB0_289
	s_and_b64 vcc, exec, s[26:27]
	s_cbranch_vccz .LBB0_292
	s_barrier

;     __host__ __device__ bool next(int i, Unit& u) const { if (!b.next(i >> 1, u)) return false; u.sel = i & 1; return true; }
; #define PG8_STAGE(bufoff, gbase, voff) do { _Pragma("unroll") for (int _i = 0; _i < 2; ++_i) \
;         __builtin_amdgcn_global_load_lds((const unsigned*)((const char*)(gbase) + (voff)[_i]), (PG8_LAS unsigned*)(lds + (bufoff) + ldsw + _i * 8192), 16, 0, 0); } while (0)
; #define PG8_LDA(dst, b, h) do { _Pragma("unroll") for (int m = 0; m < 4; ++m) _Pragma("unroll") for (int k = 0; k < 2; ++k) dst[m][k] = *(const PG8_LAS bf16x8*)(lds + PG8_SA(b, h) + aoff + m * 2048 + k * 1024); } while (0)
; #define PG8_WAIT_V(n) asm volatile("s_waitcnt vmcnt(" #n ")" ::: "memory")
;     __host__ __device__ bool next(int i, Unit& u) const {
;         const long L = (long)i * G + c; if (L >= nwg) return false;
;         int wgid = (int)L; { const int q = nwg / NXCD, r = nwg % NXCD, xcd = wgid % NXCD, off = wgid / NXCD; wgid = (xcd < r ? xcd * (q + 1) : r * (q + 1) + (xcd - r) * q) + off; }
;         const int nig = WGM * nN, gid = wgid / nig, fm = gid * WGM, gsz = (nM - fm) < WGM ? (nM - fm) : WGM;
;         u.pm = fm + ((wgid % nig) % gsz); u.pn = (wgid % nig) / gsz; u.sel = 0; return true;
; template <class Epi, class Sched, bool ALIGN_EPI = false, bool SP2 = false>
; __device__ __forceinline__ void gemm_phase(PG8_LAS unsigned char* lds, const Gemm g, const Sched& S, const Epi& E) {
;     ...
;         const bool has_next = S.next(ui + 1, nxt);
;         const char* nA = has_next ? PG8_ABASE(nxt) : cA; const char* nB = has_next ? PG8_BBASE(nxt) : cB;
;         for (int t = 0; t < nt; t += 2) {
;             const bool last = (t == nt - 2);
;             const char* a1 = cA + (size_t)(t + 1) * kstepA;
;             const char* a2 = last ? nA : cA + (size_t)(t + 2) * kstepA; const char* b2 = last ? nB : cB + (size_t)(t + 2) * kstep;
;             const char* a3 = a2 + kstepA; const char* b3 = b2 + kstep;
;             if (last && has_next) S.a_ready(nxt);
;             if constexpr (SP2) {
;             PG8_LDB(B0, 0, 0); PG8_LDB(B1, 0, 1); PG8_SCHED; PG8_LDA(At, 0, 0); PG8_STAGE(PG8_SA(1, 1), a1 + hstep, voffA);
;             PG8_WAIT_V(8); PG8_WAIT_L(0); PG8_BAR; PG8_MMA(0, 0, At, B0); PG8_MMA(0, 1, At, B1); PG8_BAR; PG8_SCHED;
;             if constexpr (Epi::PREFETCH) { if (t == tpf) E.prefetch(cur, wid, lane); }
.LBB0_435:
	s_ashr_i32 s5, s4, 31
	s_lshl_b32 s8, s6, 8
	s_lshl_b64 s[28:29], s[4:5], 14
	s_ashr_i32 s5, s4, 5
	s_ashr_i32 s9, s8, 31
	s_add_u32 s52, s14, s28
	s_mul_hi_i32 s54, s5, 0x6800
	s_mulk_i32 s5, 0x6800
	s_addc_u32 s53, s88, s29
	s_add_u32 s5, s77, s5
	s_addc_u32 s55, s78, s54
	s_lshl_b64 s[28:29], s[8:9], 2
	s_add_u32 s54, s5, s28
	s_addc_u32 s55, s55, s29
	s_add_u32 s5, s56, 0x100
	v_lshl_add_u64 v[196:197], s[10:11], 0, v[188:189]
	v_lshl_add_u64 v[198:199], s[10:11], 0, v[190:191]
	s_addc_u32 s9, s57, 0
	s_mov_b32 s28, 0
	s_mov_b64 s[56:57], 0
	ds_read_b128 v[162:165], v208
	ds_read_b128 v[166:169], v208 offset:1024
	ds_read_b128 v[170:173], v208 offset:2048
	ds_read_b128 v[174:177], v208 offset:3072
	ds_read_b128 v[146:149], v209
	ds_read_b128 v[150:153], v209 offset:1024
	ds_read_b128 v[154:157], v209 offset:2048
	ds_read_b128 v[158:161], v209 offset:3072
	v_lshl_add_u64 v[42:43], v[196:197], 0, s[56:57]
	s_add_i32 m0, s69, 0xc000
	ds_read_b128 v[212:215], v210
	ds_read_b128 v[216:219], v210 offset:1024
	ds_read_b128 v[222:225], v210 offset:2048
	ds_read_b128 v[226:229], v210 offset:3072
	ds_read_b128 v[230:233], v210 offset:4096
	ds_read_b128 v[234:237], v210 offset:5120
	ds_read_b128 v[238:241], v210 offset:6144
	ds_read_b128 v[242:245], v210 offset:7168
	global_load_lds_dwordx4 v[42:43], off
	v_lshl_add_u64 v[42:43], v[198:199], 0, s[56:57]
	s_add_i32 m0, s69, 0xe000
	s_nop 0
	global_load_lds_dwordx4 v[42:43], off
	s_add_i32 s15, s15, 1
	s_mul_i32 s2, s15, s86
	s_mul_hi_u32 s3, s15, s33
	s_add_i32 s3, s3, s2
	s_mul_i32 s2, s15, s33
	v_readlane_b32 s98, v254, 12
	s_add_u32 s100, s2, s98
	s_addc_u32 s101, s3, s87
	v_cmp_lt_i64_e64 s[2:3], s[100:101], v[192:193]
	s_ashr_i32 s98, s100, 31
	s_lshr_b32 s98, s98, 29
	s_add_i32 s98, s100, s98
	s_ashr_i32 s7, s98, 3
	s_and_b32 s98, s98, -8
	s_sub_i32 s98, s100, s98
	s_cmp_lt_i32 s98, 0
	s_movk_i32 s100, 0x1a1
	s_cselect_b32 s100, s100, 0x1a0
	s_mul_i32 s98, s98, s100
	s_add_i32 s98, s98, s7
	s_mul_hi_i32 s7, s98, 0x4ec4ec4f
	s_lshr_b32 s100, s7, 31
	s_ashr_i32 s7, s7, 4
	s_add_i32 s7, s7, s100
	s_lshl_b32 s100, s7, 1
	s_mul_i32 s7, s7, 52
	s_sub_i32 s98, s98, s7
	s_lshr_b32 s44, s98, 1
	s_and_b32 s98, s98, 1
	s_add_i32 s46, s100, s98
	s_ashr_i32 s47, s46, 31
	s_lshl_b64 s[100:101], s[46:47], 19
	s_add_u32 s48, s64, s100
	s_addc_u32 s49, s65, s101
	s_and_b64 s[100:101], s[2:3], exec
	s_cselect_b32 s7, s49, s65
	s_cselect_b32 s31, s48, s64
	s_ashr_i32 s45, s44, 31
	s_lshl_b64 s[100:101], s[44:45], 19
	s_add_u32 s50, s66, s100
	s_addc_u32 s51, s67, s101
	s_and_b64 s[100:101], s[2:3], exec
	s_cselect_b32 s45, s51, s67
	s_cselect_b32 s47, s50, s66
	s_waitcnt vmcnt(8) lgkmcnt(0)
	s_barrier
	s_setprio 1
	v_mfma_f32_16x16x32_bf16 v[42:45], v[162:165], v[212:215], 0
	v_mfma_f32_16x16x32_bf16 v[46:49], v[170:173], v[212:215], 0
	v_mfma_f32_16x16x32_bf16 v[50:53], v[162:165], v[222:225], 0
	v_mfma_f32_16x16x32_bf16 v[54:57], v[170:173], v[222:225], 0
	v_mfma_f32_16x16x32_bf16 v[110:113], v[162:165], v[230:233], 0
	v_mfma_f32_16x16x32_bf16 v[106:109], v[170:173], v[230:233], 0
	v_mfma_f32_16x16x32_bf16 v[94:97], v[162:165], v[238:241], 0
	v_mfma_f32_16x16x32_bf16 v[90:93], v[170:173], v[238:241], 0
	v_mfma_f32_16x16x32_bf16 v[42:45], v[166:169], v[216:219], v[42:45]
	v_mfma_f32_16x16x32_bf16 v[46:49], v[174:177], v[216:219], v[46:49]
	v_mfma_f32_16x16x32_bf16 v[50:53], v[166:169], v[226:229], v[50:53]
	v_mfma_f32_16x16x32_bf16 v[54:57], v[174:177], v[226:229], v[54:57]
	v_mfma_f32_16x16x32_bf16 v[110:113], v[166:169], v[234:237], v[110:113]
	v_mfma_f32_16x16x32_bf16 v[106:109], v[174:177], v[234:237], v[106:109]
	v_mfma_f32_16x16x32_bf16 v[94:97], v[166:169], v[242:245], v[94:97]
	v_mfma_f32_16x16x32_bf16 v[90:93], v[174:177], v[242:245], v[90:93]
	v_mfma_f32_16x16x32_bf16 v[122:125], v[146:149], v[212:215], 0
	v_mfma_f32_16x16x32_bf16 v[134:137], v[150:153], v[216:219], v[122:125]
	v_mfma_f32_16x16x32_bf16 v[122:125], v[154:157], v[212:215], 0
	v_mfma_f32_16x16x32_bf16 v[118:121], v[146:149], v[222:225], 0
	v_mfma_f32_16x16x32_bf16 v[114:117], v[154:157], v[222:225], 0
	v_mfma_f32_16x16x32_bf16 v[102:105], v[146:149], v[230:233], 0
	v_mfma_f32_16x16x32_bf16 v[98:101], v[154:157], v[230:233], 0
	v_mfma_f32_16x16x32_bf16 v[86:89], v[146:149], v[238:241], 0
	v_mfma_f32_16x16x32_bf16 v[82:85], v[154:157], v[238:241], 0
	v_mfma_f32_16x16x32_bf16 v[130:133], v[158:161], v[216:219], v[122:125]
	v_mfma_f32_16x16x32_bf16 v[118:121], v[150:153], v[226:229], v[118:121]
	v_mfma_f32_16x16x32_bf16 v[114:117], v[158:161], v[226:229], v[114:117]
	v_mfma_f32_16x16x32_bf16 v[102:105], v[150:153], v[234:237], v[102:105]
	v_mfma_f32_16x16x32_bf16 v[98:101], v[158:161], v[234:237], v[98:101]
	v_mfma_f32_16x16x32_bf16 v[86:89], v[150:153], v[242:245], v[86:89]
	v_mfma_f32_16x16x32_bf16 v[82:85], v[158:161], v[242:245], v[82:85]
	s_setprio 0
	s_barrier
	s_cmp_lg_u32 s63, s28
	s_cbranch_scc1 .Lpz3_a
	v_mov_b32_e32 v186, v207
	s_add_i32 m0, s62, 0x20000
	v_lshl_add_u64 v[122:123], s[52:53], 0, v[186:187]
	s_mov_b64 s[58:59], 0x400
	global_load_lds_dwordx4 v186, s[52:53]
	v_lshl_add_u64 v[122:123], v[122:123], 0, s[58:59]
	s_add_i32 m0, s62, 0x20400
	s_andn2_b64 vcc, exec, s[40:41]
	global_load_lds_dwordx4 v[122:123], off
	s_cbranch_vccnz .Lpz3_a
	v_lshl_add_u64 v[122:123], s[54:55], 0, v[186:187]
	s_mov_b32 m0, s30
	s_nop 0
	global_load_lds_dwordx4 v[122:123], off
	s_branch .Lpz3_a
; #define PG8_STAGE(bufoff, gbase, voff) do { _Pragma("unroll") for (int _i = 0; _i < 2; ++_i) \
;         __builtin_amdgcn_global_load_lds((const unsigned*)((const char*)(gbase) + (voff)[_i]), (PG8_LAS unsigned*)(lds + (bufoff) + ldsw + _i * 8192), 16, 0, 0); } while (0)
; #define PG8_LDA(dst, b, h) do { _Pragma("unroll") for (int m = 0; m < 4; ++m) _Pragma("unroll") for (int k = 0; k < 2; ++k) dst[m][k] = *(const PG8_LAS bf16x8*)(lds + PG8_SA(b, h) + aoff + m * 2048 + k * 1024); } while (0)
; #define PG8_LDB(dst, b, h) do { _Pragma("unroll") for (int n = 0; n < 2; ++n) _Pragma("unroll") for (int k = 0; k < 2; ++k) dst[n][k] = *(const PG8_LAS bf16x8*)(lds + PG8_SB(b, h) + boff + n * 2048 + k * 1024); } while (0)
; #define PG8_MMA(ai, bj, At, Bt) do { __builtin_amdgcn_s_setprio(1); _Pragma("unroll") for (int m = 0; m < 4; ++m) _Pragma("unroll") for (int n = 0; n < 2; ++n) _Pragma("unroll") for (int k = 0; k < 2; ++k) \
;         acc[ai][bj][m][n] = __builtin_amdgcn_mfma_f32_16x16x32_bf16(Bt[n][k], At[m][k], acc[ai][bj][m][n], 0, 0, 0); __builtin_amdgcn_s_setprio(0); } while (0)
; #define PG8_WAIT_V(n) asm volatile("s_waitcnt vmcnt(" #n ")" ::: "memory")
; template <class Epi, class Sched, bool ALIGN_EPI = false, bool SP2 = false>
; __device__ __forceinline__ void gemm_phase(PG8_LAS unsigned char* lds, const Gemm g, const Sched& S, const Epi& E) {
;     ...
;             const bool last = (t == nt - 2);
;             const char* a1 = cA + (size_t)(t + 1) * kstepA;
;             const char* a2 = last ? nA : cA + (size_t)(t + 2) * kstepA; const char* b2 = last ? nB : cB + (size_t)(t + 2) * kstep;
;             const char* a3 = a2 + kstepA; const char* b3 = b2 + kstep;
;             if (last && has_next) S.a_ready(nxt);
;             if constexpr (SP2) {
;             PG8_LDB(B0, 0, 0); PG8_LDB(B1, 0, 1); PG8_SCHED; PG8_LDA(At, 0, 0); PG8_STAGE(PG8_SA(1, 1), a1 + hstep, voffA);
;             PG8_WAIT_V(8); PG8_WAIT_L(0); PG8_BAR; PG8_MMA(0, 0, At, B0); PG8_MMA(0, 1, At, B1); PG8_BAR; PG8_SCHED;
;             if constexpr (Epi::PREFETCH) { if (t == tpf) E.prefetch(cur, wid, lane); }
;             PG8_LDA(At, 0, 1); PG8_STAGE(PG8_SB(0, 0), b2, voffB); PG8_STAGE(PG8_SB(0, 1), b2 + hstep, voffB); PG8_STAGE(PG8_SA(0, 0), a2, voffA);
;             PG8_WAIT_V(8); PG8_WAIT_L(0); PG8_BAR; PG8_MMA(1, 0, At, B0); PG8_MMA(1, 1, At, B1); PG8_BAR; PG8_SCHED;
.Lpz3_a:
	s_add_u32 s29, s10, s56
	s_addc_u32 s58, s11, s57
	s_add_u32 s29, s29, 0x100
	s_addc_u32 s58, s58, 0
	s_add_u32 vcc_lo, s5, s56
	s_addc_u32 s59, s9, s57
	s_cmpk_eq_i32 s56, 0x700
	s_cselect_b32 s61, s7, s58
	s_cselect_b32 s59, s45, s59
	s_cselect_b32 s58, s47, vcc_lo
	s_mov_b32 m0, s70
	s_cselect_b32 s60, s31, s29
	v_lshl_add_u64 v[204:205], s[58:59], 0, v[180:181]
	s_add_u32 vcc_lo, s58, 0x40000
	ds_read_b128 v[122:125], v210 offset:16384
	ds_read_b128 v[126:129], v210 offset:17408
	ds_read_b128 v[138:141], v210 offset:18432
	ds_read_b128 v[142:145], v210 offset:19456
	ds_read_b128 v[212:215], v210 offset:20480
	ds_read_b128 v[216:219], v210 offset:21504
	ds_read_b128 v[222:225], v210 offset:22528
	ds_read_b128 v[226:229], v210 offset:23552
	global_load_lds_dwordx4 v[204:205], off
	v_lshl_add_u64 v[246:247], s[58:59], 0, v[184:185]
	s_mov_b32 m0, s71
	s_addc_u32 vcc_hi, s59, 0
	global_load_lds_dwordx4 v[246:247], off
	v_lshl_add_u64 v[230:231], vcc, 0, v[180:181]
	s_mov_b32 m0, s72
	v_lshl_add_u64 v[248:249], s[60:61], 0, v[178:179]
	global_load_lds_dwordx4 v[230:231], off
	v_lshl_add_u64 v[230:231], vcc, 0, v[184:185]
	s_mov_b32 m0, s73
	v_lshl_add_u64 v[250:251], s[60:61], 0, v[182:183]
	global_load_lds_dwordx4 v[230:231], off
	s_mov_b32 m0, s69
	s_nop 0
	global_load_lds_dwordx4 v[248:249], off
	s_mov_b32 m0, s74
	s_nop 0
	global_load_lds_dwordx4 v[250:251], off
	s_waitcnt vmcnt(8) lgkmcnt(0)
	s_barrier
	s_setprio 1
	v_mfma_f32_16x16x32_bf16 v[78:81], v[162:165], v[122:125], 0
	v_mfma_f32_16x16x32_bf16 v[74:77], v[170:173], v[122:125], 0
	v_mfma_f32_16x16x32_bf16 v[62:65], v[162:165], v[138:141], 0
	v_mfma_f32_16x16x32_bf16 v[58:61], v[170:173], v[138:141], 0
	v_mfma_f32_16x16x32_bf16 v[30:33], v[162:165], v[212:215], 0
	v_mfma_f32_16x16x32_bf16 v[26:29], v[170:173], v[212:215], 0
	v_mfma_f32_16x16x32_bf16 v[14:17], v[162:165], v[222:225], 0
	v_mfma_f32_16x16x32_bf16 v[10:13], v[170:173], v[222:225], 0
	v_mfma_f32_16x16x32_bf16 v[78:81], v[166:169], v[126:129], v[78:81]
	v_mfma_f32_16x16x32_bf16 v[74:77], v[174:177], v[126:129], v[74:77]
	v_mfma_f32_16x16x32_bf16 v[62:65], v[166:169], v[142:145], v[62:65]
	v_mfma_f32_16x16x32_bf16 v[58:61], v[174:177], v[142:145], v[58:61]
	v_mfma_f32_16x16x32_bf16 v[30:33], v[166:169], v[216:219], v[30:33]
	v_mfma_f32_16x16x32_bf16 v[26:29], v[174:177], v[216:219], v[26:29]
	v_mfma_f32_16x16x32_bf16 v[14:17], v[166:169], v[226:229], v[14:17]
	v_mfma_f32_16x16x32_bf16 v[10:13], v[174:177], v[226:229], v[10:13]
	v_mfma_f32_16x16x32_bf16 v[70:73], v[146:149], v[122:125], 0
	v_mfma_f32_16x16x32_bf16 v[66:69], v[154:157], v[122:125], 0
	v_mfma_f32_16x16x32_bf16 v[38:41], v[146:149], v[138:141], 0
	v_mfma_f32_16x16x32_bf16 v[34:37], v[154:157], v[138:141], 0
	v_mfma_f32_16x16x32_bf16 v[22:25], v[146:149], v[212:215], 0
	v_mfma_f32_16x16x32_bf16 v[18:21], v[154:157], v[212:215], 0
	v_mfma_f32_16x16x32_bf16 v[6:9], v[146:149], v[222:225], 0
	v_mfma_f32_16x16x32_bf16 v[2:5], v[154:157], v[222:225], 0
	v_mfma_f32_16x16x32_bf16 v[70:73], v[150:153], v[126:129], v[70:73]
	v_mfma_f32_16x16x32_bf16 v[66:69], v[158:161], v[126:129], v[66:69]
	v_mfma_f32_16x16x32_bf16 v[38:41], v[150:153], v[142:145], v[38:41]
	v_mfma_f32_16x16x32_bf16 v[34:37], v[158:161], v[142:145], v[34:37]
	v_mfma_f32_16x16x32_bf16 v[22:25], v[150:153], v[216:219], v[22:25]
	v_mfma_f32_16x16x32_bf16 v[18:21], v[158:161], v[216:219], v[18:21]
	v_mfma_f32_16x16x32_bf16 v[6:9], v[150:153], v[226:229], v[6:9]
	v_mfma_f32_16x16x32_bf16 v[2:5], v[158:161], v[226:229], v[2:5]
	s_setprio 0
	s_barrier
	s_branch .Lpz3_mid
.LBB0_438:
	s_add_u32 s29, s10, s56
	s_addc_u32 s58, s11, s57
	s_add_u32 s29, s29, 0x100
	s_addc_u32 s58, s58, 0
	s_add_u32 vcc_lo, s5, s56
	s_addc_u32 s59, s9, s57
	s_cmpk_eq_i32 s56, 0x700
	s_cselect_b32 s61, s7, s58
	s_cselect_b32 s59, s45, s59
	s_cselect_b32 s58, s47, vcc_lo
	s_mov_b32 m0, s70
	s_cselect_b32 s60, s31, s29
	v_lshl_add_u64 v[204:205], s[58:59], 0, v[180:181]
	s_add_u32 vcc_lo, s58, 0x40000
	ds_read_b128 v[122:125], v210 offset:16384
	ds_read_b128 v[126:129], v210 offset:17408
	ds_read_b128 v[138:141], v210 offset:18432
	ds_read_b128 v[142:145], v210 offset:19456
	ds_read_b128 v[212:215], v210 offset:20480
	ds_read_b128 v[216:219], v210 offset:21504
	ds_read_b128 v[222:225], v210 offset:22528
	ds_read_b128 v[226:229], v210 offset:23552
	global_load_lds_dwordx4 v[204:205], off
	v_lshl_add_u64 v[246:247], s[58:59], 0, v[184:185]
	s_mov_b32 m0, s71
	s_addc_u32 vcc_hi, s59, 0
	global_load_lds_dwordx4 v[246:247], off
	v_lshl_add_u64 v[230:231], vcc, 0, v[180:181]
	s_mov_b32 m0, s72
	v_lshl_add_u64 v[248:249], s[60:61], 0, v[178:179]
	global_load_lds_dwordx4 v[230:231], off
	v_lshl_add_u64 v[230:231], vcc, 0, v[184:185]
	s_mov_b32 m0, s73
	v_lshl_add_u64 v[250:251], s[60:61], 0, v[182:183]
	global_load_lds_dwordx4 v[230:231], off
	s_mov_b32 m0, s69
	s_nop 0
	global_load_lds_dwordx4 v[248:249], off
	s_mov_b32 m0, s74
	s_nop 0
	global_load_lds_dwordx4 v[250:251], off
	s_waitcnt vmcnt(8) lgkmcnt(0)
	s_barrier
; #define PG8_STAGE(bufoff, gbase, voff) do { _Pragma("unroll") for (int _i = 0; _i < 2; ++_i) \
;         __builtin_amdgcn_global_load_lds((const unsigned*)((const char*)(gbase) + (voff)[_i]), (PG8_LAS unsigned*)(lds + (bufoff) + ldsw + _i * 8192), 16, 0, 0); } while (0)
; #define PG8_LDA(dst, b, h) do { _Pragma("unroll") for (int m = 0; m < 4; ++m) _Pragma("unroll") for (int k = 0; k < 2; ++k) dst[m][k] = *(const PG8_LAS bf16x8*)(lds + PG8_SA(b, h) + aoff + m * 2048 + k * 1024); } while (0)
; #define PG8_LDB(dst, b, h) do { _Pragma("unroll") for (int n = 0; n < 2; ++n) _Pragma("unroll") for (int k = 0; k < 2; ++k) dst[n][k] = *(const PG8_LAS bf16x8*)(lds + PG8_SB(b, h) + boff + n * 2048 + k * 1024); } while (0)
; #define PG8_MMA(ai, bj, At, Bt) do { __builtin_amdgcn_s_setprio(1); _Pragma("unroll") for (int m = 0; m < 4; ++m) _Pragma("unroll") for (int n = 0; n < 2; ++n) _Pragma("unroll") for (int k = 0; k < 2; ++k) \
;         acc[ai][bj][m][n] = __builtin_amdgcn_mfma_f32_16x16x32_bf16(Bt[n][k], At[m][k], acc[ai][bj][m][n], 0, 0, 0); __builtin_amdgcn_s_setprio(0); } while (0)
; #define PG8_WAIT_V(n) asm volatile("s_waitcnt vmcnt(" #n ")" ::: "memory")
; #define PG8_WAIT_L(n) asm volatile("s_waitcnt lgkmcnt(" #n ")" ::: "memory")
; #define PG8_BAR __builtin_amdgcn_s_barrier()
; #define PG8_SCHED __builtin_amdgcn_sched_barrier(0)
; template <class Epi, class Sched, bool ALIGN_EPI = false, bool SP2 = false>
; __device__ __forceinline__ void gemm_phase(PG8_LAS unsigned char* lds, const Gemm g, const Sched& S, const Epi& E) {
;     ...
;             PG8_WAIT_V(8); PG8_WAIT_L(0); PG8_BAR; PG8_MMA(1, 0, At, B0); PG8_MMA(1, 1, At, B1); PG8_BAR; PG8_SCHED;
;             PG8_LDB(B0, 1, 0); PG8_LDB(B1, 1, 1); PG8_SCHED; PG8_LDA(At, 1, 0); PG8_STAGE(PG8_SA(0, 1), a2 + hstep, voffA);
;             PG8_WAIT_V(8); PG8_WAIT_L(0); PG8_BAR; PG8_MMA(0, 0, At, B0); PG8_MMA(0, 1, At, B1); PG8_BAR; PG8_SCHED;
	s_setprio 1
	v_mfma_f32_16x16x32_bf16 v[78:81], v[162:165], v[122:125], v[78:81]
	v_mfma_f32_16x16x32_bf16 v[74:77], v[170:173], v[122:125], v[74:77]
	v_mfma_f32_16x16x32_bf16 v[62:65], v[162:165], v[138:141], v[62:65]
	v_mfma_f32_16x16x32_bf16 v[58:61], v[170:173], v[138:141], v[58:61]
	v_mfma_f32_16x16x32_bf16 v[30:33], v[162:165], v[212:215], v[30:33]
	v_mfma_f32_16x16x32_bf16 v[26:29], v[170:173], v[212:215], v[26:29]
	v_mfma_f32_16x16x32_bf16 v[14:17], v[162:165], v[222:225], v[14:17]
	v_mfma_f32_16x16x32_bf16 v[10:13], v[170:173], v[222:225], v[10:13]
	v_mfma_f32_16x16x32_bf16 v[78:81], v[166:169], v[126:129], v[78:81]
	v_mfma_f32_16x16x32_bf16 v[74:77], v[174:177], v[126:129], v[74:77]
	v_mfma_f32_16x16x32_bf16 v[62:65], v[166:169], v[142:145], v[62:65]
	v_mfma_f32_16x16x32_bf16 v[58:61], v[174:177], v[142:145], v[58:61]
	v_mfma_f32_16x16x32_bf16 v[30:33], v[166:169], v[216:219], v[30:33]
	v_mfma_f32_16x16x32_bf16 v[26:29], v[174:177], v[216:219], v[26:29]
	v_mfma_f32_16x16x32_bf16 v[14:17], v[166:169], v[226:229], v[14:17]
	v_mfma_f32_16x16x32_bf16 v[10:13], v[174:177], v[226:229], v[10:13]
	v_mfma_f32_16x16x32_bf16 v[70:73], v[146:149], v[122:125], v[70:73]
	v_mfma_f32_16x16x32_bf16 v[66:69], v[154:157], v[122:125], v[66:69]
	v_mfma_f32_16x16x32_bf16 v[38:41], v[146:149], v[138:141], v[38:41]
	v_mfma_f32_16x16x32_bf16 v[34:37], v[154:157], v[138:141], v[34:37]
	v_mfma_f32_16x16x32_bf16 v[22:25], v[146:149], v[212:215], v[22:25]
	v_mfma_f32_16x16x32_bf16 v[18:21], v[154:157], v[212:215], v[18:21]
	v_mfma_f32_16x16x32_bf16 v[6:9], v[146:149], v[222:225], v[6:9]
	v_mfma_f32_16x16x32_bf16 v[2:5], v[154:157], v[222:225], v[2:5]
	v_mfma_f32_16x16x32_bf16 v[70:73], v[150:153], v[126:129], v[70:73]
	v_mfma_f32_16x16x32_bf16 v[66:69], v[158:161], v[126:129], v[66:69]
	v_mfma_f32_16x16x32_bf16 v[38:41], v[150:153], v[142:145], v[38:41]
	v_mfma_f32_16x16x32_bf16 v[34:37], v[158:161], v[142:145], v[34:37]
	v_mfma_f32_16x16x32_bf16 v[22:25], v[150:153], v[216:219], v[22:25]
	v_mfma_f32_16x16x32_bf16 v[18:21], v[158:161], v[216:219], v[18:21]
	v_mfma_f32_16x16x32_bf16 v[6:9], v[150:153], v[226:229], v[6:9]
	v_mfma_f32_16x16x32_bf16 v[2:5], v[158:161], v[226:229], v[2:5]
	s_setprio 0
	s_barrier
.Lpz3_mid:
	s_add_i32 s29, 0, 0x18000
	v_add_u32_e32 v122, s29, v203
	s_add_i32 vcc_lo, 0, 0x1c000
	ds_read_b128 v[146:149], v122
	ds_read_b128 v[150:153], v122 offset:1024
	ds_read_b128 v[154:157], v122 offset:2048
	ds_read_b128 v[158:161], v122 offset:3072
	v_add_u32_e32 v122, vcc_lo, v203
	ds_read_b128 v[162:165], v122
	ds_read_b128 v[166:169], v122 offset:1024
	ds_read_b128 v[170:173], v122 offset:2048
	ds_read_b128 v[174:177], v122 offset:3072
	s_add_u32 s60, s60, 0x40000
	s_addc_u32 s61, s61, 0
	s_mov_b32 m0, s75
	v_lshl_add_u64 v[122:123], s[60:61], 0, v[178:179]
	ds_read_b128 v[212:215], v210 offset:32768
	ds_read_b128 v[216:219], v210 offset:33792
	ds_read_b128 v[222:225], v210 offset:34816
	ds_read_b128 v[226:229], v210 offset:35840
	ds_read_b128 v[230:233], v210 offset:36864
	ds_read_b128 v[234:237], v210 offset:37888
	ds_read_b128 v[238:241], v210 offset:38912
	ds_read_b128 v[242:245], v210 offset:39936
	global_load_lds_dwordx4 v[122:123], off
	v_lshl_add_u64 v[122:123], s[60:61], 0, v[182:183]
	s_mov_b32 m0, s76
	s_nop 0
	global_load_lds_dwordx4 v[122:123], off
	s_waitcnt vmcnt(8) lgkmcnt(0)
	s_barrier
	s_setprio 1
	v_mfma_f32_16x16x32_bf16 v[42:45], v[146:149], v[212:215], v[42:45]
	v_mfma_f32_16x16x32_bf16 v[142:145], v[150:153], v[216:219], v[42:45]
	v_mfma_f32_16x16x32_bf16 v[42:45], v[154:157], v[212:215], v[46:49]
	v_mfma_f32_16x16x32_bf16 v[138:141], v[158:161], v[216:219], v[42:45]
	v_mfma_f32_16x16x32_bf16 v[42:45], v[146:149], v[222:225], v[50:53]
	v_mfma_f32_16x16x32_bf16 v[126:129], v[150:153], v[226:229], v[42:45]
	v_mfma_f32_16x16x32_bf16 v[42:45], v[154:157], v[222:225], v[54:57]
	v_mfma_f32_16x16x32_bf16 v[122:125], v[158:161], v[226:229], v[42:45]
	v_mfma_f32_16x16x32_bf16 v[42:45], v[146:149], v[230:233], v[110:113]
	v_mfma_f32_16x16x32_bf16 v[110:113], v[150:153], v[234:237], v[42:45]
	v_mfma_f32_16x16x32_bf16 v[42:45], v[154:157], v[230:233], v[106:109]
	v_mfma_f32_16x16x32_bf16 v[106:109], v[158:161], v[234:237], v[42:45]
	v_mfma_f32_16x16x32_bf16 v[42:45], v[146:149], v[238:241], v[94:97]
	v_mfma_f32_16x16x32_bf16 v[94:97], v[150:153], v[242:245], v[42:45]
	v_mfma_f32_16x16x32_bf16 v[42:45], v[154:157], v[238:241], v[90:93]
	v_mfma_f32_16x16x32_bf16 v[90:93], v[158:161], v[242:245], v[42:45]
	v_mfma_f32_16x16x32_bf16 v[42:45], v[162:165], v[212:215], v[134:137]
	v_mfma_f32_16x16x32_bf16 v[134:137], v[166:169], v[216:219], v[42:45]
	v_mfma_f32_16x16x32_bf16 v[42:45], v[170:173], v[212:215], v[130:133]
	v_mfma_f32_16x16x32_bf16 v[130:133], v[174:177], v[216:219], v[42:45]
	v_mfma_f32_16x16x32_bf16 v[42:45], v[162:165], v[222:225], v[118:121]
	v_mfma_f32_16x16x32_bf16 v[118:121], v[166:169], v[226:229], v[42:45]
	v_mfma_f32_16x16x32_bf16 v[42:45], v[170:173], v[222:225], v[114:117]
	v_mfma_f32_16x16x32_bf16 v[114:117], v[174:177], v[226:229], v[42:45]
	v_mfma_f32_16x16x32_bf16 v[42:45], v[162:165], v[230:233], v[102:105]
	v_mfma_f32_16x16x32_bf16 v[102:105], v[166:169], v[234:237], v[42:45]
	v_mfma_f32_16x16x32_bf16 v[42:45], v[170:173], v[230:233], v[98:101]
	v_mfma_f32_16x16x32_bf16 v[98:101], v[174:177], v[234:237], v[42:45]
	v_mfma_f32_16x16x32_bf16 v[42:45], v[162:165], v[238:241], v[86:89]
	v_mfma_f32_16x16x32_bf16 v[86:89], v[166:169], v[242:245], v[42:45]
	v_mfma_f32_16x16x32_bf16 v[42:45], v[170:173], v[238:241], v[82:85]
	v_mfma_f32_16x16x32_bf16 v[82:85], v[174:177], v[242:245], v[42:45]
	s_setprio 0
	s_barrier
; #define PG8_STAGE(bufoff, gbase, voff) do { _Pragma("unroll") for (int _i = 0; _i < 2; ++_i) \
;         __builtin_amdgcn_global_load_lds((const unsigned*)((const char*)(gbase) + (voff)[_i]), (PG8_LAS unsigned*)(lds + (bufoff) + ldsw + _i * 8192), 16, 0, 0); } while (0)
; #define PG8_LDA(dst, b, h) do { _Pragma("unroll") for (int m = 0; m < 4; ++m) _Pragma("unroll") for (int k = 0; k < 2; ++k) dst[m][k] = *(const PG8_LAS bf16x8*)(lds + PG8_SA(b, h) + aoff + m * 2048 + k * 1024); } while (0)
; #define PG8_MMA(ai, bj, At, Bt) do { __builtin_amdgcn_s_setprio(1); _Pragma("unroll") for (int m = 0; m < 4; ++m) _Pragma("unroll") for (int n = 0; n < 2; ++n) _Pragma("unroll") for (int k = 0; k < 2; ++k) \
;         acc[ai][bj][m][n] = __builtin_amdgcn_mfma_f32_16x16x32_bf16(Bt[n][k], At[m][k], acc[ai][bj][m][n], 0, 0, 0); __builtin_amdgcn_s_setprio(0); } while (0)
; #define PG8_WAIT_V(n) asm volatile("s_waitcnt vmcnt(" #n ")" ::: "memory")
; #define PG8_WAIT_L(n) asm volatile("s_waitcnt lgkmcnt(" #n ")" ::: "memory")
; #define PG8_BAR __builtin_amdgcn_s_barrier()
; #define PG8_SCHED __builtin_amdgcn_sched_barrier(0)
; template <class Epi, class Sched, bool ALIGN_EPI = false, bool SP2 = false>
; __device__ __forceinline__ void gemm_phase(PG8_LAS unsigned char* lds, const Gemm g, const Sched& S, const Epi& E) {
;     ...
;         for (int t = 0; t < nt; t += 2) {
;             const bool last = (t == nt - 2);
;             const char* a1 = cA + (size_t)(t + 1) * kstepA;
;             const char* a2 = last ? nA : cA + (size_t)(t + 2) * kstepA; const char* b2 = last ? nB : cB + (size_t)(t + 2) * kstep;
;     ...
;             PG8_LDA(At, 1, 1); PG8_STAGE(PG8_SB(1, 0), b3, voffB); PG8_STAGE(PG8_SB(1, 1), b3 + hstep, voffB); PG8_STAGE(PG8_SA(1, 0), a3, voffA);
;             PG8_WAIT_V(8); PG8_WAIT_L(0); PG8_BAR; PG8_MMA(1, 0, At, B0); PG8_MMA(1, 1, At, B1); PG8_BAR; PG8_SCHED;
	s_add_i32 s29, s29, s68
	v_lshl_add_u64 v[204:205], v[204:205], 0, s[38:39]
	s_mov_b32 m0, s29
	s_nop 1
	ds_read_b128 v[42:45], v210 offset:49152
	ds_read_b128 v[46:49], v210 offset:50176
	ds_read_b128 v[50:53], v210 offset:51200
	ds_read_b128 v[54:57], v210 offset:52224
	ds_read_b128 v[212:215], v210 offset:53248
	ds_read_b128 v[216:219], v210 offset:54272
	ds_read_b128 v[222:225], v210 offset:55296
	ds_read_b128 v[226:229], v210 offset:56320
	global_load_lds_dwordx4 v[204:205], off
	s_add_i32 m0, s29, 0x2000
	s_add_u32 s58, s58, 0x40080
	v_lshl_add_u64 v[204:205], v[246:247], 0, s[38:39]
	s_addc_u32 s59, s59, 0
	s_add_i32 s29, vcc_lo, s68
	global_load_lds_dwordx4 v[204:205], off
	v_lshl_add_u64 v[204:205], s[58:59], 0, v[180:181]
	s_mov_b32 m0, s29
	s_nop 0
	global_load_lds_dwordx4 v[204:205], off
	v_lshl_add_u64 v[204:205], s[58:59], 0, v[184:185]
	s_add_i32 m0, s29, 0x2000
	s_nop 0
	global_load_lds_dwordx4 v[204:205], off
	v_lshl_add_u64 v[204:205], v[248:249], 0, s[38:39]
	s_mov_b32 m0, s81
	s_nop 0
	global_load_lds_dwordx4 v[204:205], off
	v_lshl_add_u64 v[204:205], v[250:251], 0, s[38:39]
	s_mov_b32 m0, s82
	s_nop 0
	global_load_lds_dwordx4 v[204:205], off
	s_waitcnt vmcnt(8) lgkmcnt(0)
	s_barrier
	s_setprio 1
	v_mfma_f32_16x16x32_bf16 v[78:81], v[146:149], v[42:45], v[78:81]
	v_mfma_f32_16x16x32_bf16 v[74:77], v[154:157], v[42:45], v[74:77]
	v_mfma_f32_16x16x32_bf16 v[62:65], v[146:149], v[50:53], v[62:65]
	v_mfma_f32_16x16x32_bf16 v[58:61], v[154:157], v[50:53], v[58:61]
	v_mfma_f32_16x16x32_bf16 v[30:33], v[146:149], v[212:215], v[30:33]
	v_mfma_f32_16x16x32_bf16 v[26:29], v[154:157], v[212:215], v[26:29]
	v_mfma_f32_16x16x32_bf16 v[14:17], v[146:149], v[222:225], v[14:17]
	v_mfma_f32_16x16x32_bf16 v[10:13], v[154:157], v[222:225], v[10:13]
	v_mfma_f32_16x16x32_bf16 v[78:81], v[150:153], v[46:49], v[78:81]
	v_mfma_f32_16x16x32_bf16 v[74:77], v[158:161], v[46:49], v[74:77]
	v_mfma_f32_16x16x32_bf16 v[62:65], v[150:153], v[54:57], v[62:65]
	v_mfma_f32_16x16x32_bf16 v[58:61], v[158:161], v[54:57], v[58:61]
	v_mfma_f32_16x16x32_bf16 v[30:33], v[150:153], v[216:219], v[30:33]
	v_mfma_f32_16x16x32_bf16 v[26:29], v[158:161], v[216:219], v[26:29]
	v_mfma_f32_16x16x32_bf16 v[14:17], v[150:153], v[226:229], v[14:17]
	v_mfma_f32_16x16x32_bf16 v[10:13], v[158:161], v[226:229], v[10:13]
	v_mfma_f32_16x16x32_bf16 v[70:73], v[162:165], v[42:45], v[70:73]
	v_mfma_f32_16x16x32_bf16 v[42:45], v[170:173], v[42:45], v[66:69]
	v_mfma_f32_16x16x32_bf16 v[38:41], v[162:165], v[50:53], v[38:41]
	v_mfma_f32_16x16x32_bf16 v[34:37], v[170:173], v[50:53], v[34:37]
	v_mfma_f32_16x16x32_bf16 v[22:25], v[162:165], v[212:215], v[22:25]
	v_mfma_f32_16x16x32_bf16 v[18:21], v[170:173], v[212:215], v[18:21]
	v_mfma_f32_16x16x32_bf16 v[6:9], v[162:165], v[222:225], v[6:9]
	v_mfma_f32_16x16x32_bf16 v[2:5], v[170:173], v[222:225], v[2:5]
	v_mfma_f32_16x16x32_bf16 v[70:73], v[166:169], v[46:49], v[70:73]
	v_mfma_f32_16x16x32_bf16 v[66:69], v[174:177], v[46:49], v[42:45]
	v_mfma_f32_16x16x32_bf16 v[38:41], v[166:169], v[54:57], v[38:41]
	v_mfma_f32_16x16x32_bf16 v[34:37], v[174:177], v[54:57], v[34:37]
	v_mfma_f32_16x16x32_bf16 v[22:25], v[166:169], v[216:219], v[22:25]
	v_mfma_f32_16x16x32_bf16 v[18:21], v[174:177], v[216:219], v[18:21]
	v_mfma_f32_16x16x32_bf16 v[6:9], v[166:169], v[226:229], v[6:9]
	v_mfma_f32_16x16x32_bf16 v[2:5], v[174:177], v[226:229], v[2:5]
	s_setprio 0
	s_barrier
	s_add_i32 s29, s28, 2
	s_add_u32 s56, s56, 0x100
	s_addc_u32 s57, s57, 0
	s_cmp_gt_u32 s28, 13
	s_mov_b32 s28, s29
	s_cbranch_scc1 .LBB0_442
; #define PG8_STAGE(bufoff, gbase, voff) do { _Pragma("unroll") for (int _i = 0; _i < 2; ++_i) \
;         __builtin_amdgcn_global_load_lds((const unsigned*)((const char*)(gbase) + (voff)[_i]), (PG8_LAS unsigned*)(lds + (bufoff) + ldsw + _i * 8192), 16, 0, 0); } while (0)
; #define PG8_LDA(dst, b, h) do { _Pragma("unroll") for (int m = 0; m < 4; ++m) _Pragma("unroll") for (int k = 0; k < 2; ++k) dst[m][k] = *(const PG8_LAS bf16x8*)(lds + PG8_SA(b, h) + aoff + m * 2048 + k * 1024); } while (0)
; #define PG8_LDB(dst, b, h) do { _Pragma("unroll") for (int n = 0; n < 2; ++n) _Pragma("unroll") for (int k = 0; k < 2; ++k) dst[n][k] = *(const PG8_LAS bf16x8*)(lds + PG8_SB(b, h) + boff + n * 2048 + k * 1024); } while (0)
; #define PG8_MMA(ai, bj, At, Bt) do { __builtin_amdgcn_s_setprio(1); _Pragma("unroll") for (int m = 0; m < 4; ++m) _Pragma("unroll") for (int n = 0; n < 2; ++n) _Pragma("unroll") for (int k = 0; k < 2; ++k) \
;         acc[ai][bj][m][n] = __builtin_amdgcn_mfma_f32_16x16x32_bf16(Bt[n][k], At[m][k], acc[ai][bj][m][n], 0, 0, 0); __builtin_amdgcn_s_setprio(0); } while (0)
; #define PG8_WAIT_V(n) asm volatile("s_waitcnt vmcnt(" #n ")" ::: "memory")
; #define PG8_WAIT_L(n) asm volatile("s_waitcnt lgkmcnt(" #n ")" ::: "memory")
; #define PG8_BAR __builtin_amdgcn_s_barrier()
; #define PG8_SCHED __builtin_amdgcn_sched_barrier(0)
;     __device__ __forceinline__ void prefetch(const Unit& u, int wid, int lane) const { epi_prefetch(scr, ssq, bias + (size_t)(u.pm >> 5) * NGU + u.pn * BM, u, wid, lane); }
;     __device__ __forceinline__ void prefetch(const Unit& u, int wid, int lane) const { epi_prefetch(scr, ssq, bias + (size_t)(u.pm >> 5) * DIN + u.pn * BM, u, wid, lane); }
; template <class Epi, class Sched, bool ALIGN_EPI = false, bool SP2 = false>
; __device__ __forceinline__ void gemm_phase(PG8_LAS unsigned char* lds, const Gemm g, const Sched& S, const Epi& E) {
;     ...
;             PG8_LDB(B0, 0, 0); PG8_LDB(B1, 0, 1); PG8_SCHED; PG8_LDA(At, 0, 0); PG8_STAGE(PG8_SA(1, 1), a1 + hstep, voffA);
;             PG8_WAIT_V(8); PG8_WAIT_L(0); PG8_BAR; PG8_MMA(0, 0, At, B0); PG8_MMA(0, 1, At, B1); PG8_BAR; PG8_SCHED;
;             if constexpr (Epi::PREFETCH) { if (t == tpf) E.prefetch(cur, wid, lane); }
.LBB0_439:
	ds_read_b128 v[162:165], v208
	ds_read_b128 v[166:169], v208 offset:1024
	ds_read_b128 v[170:173], v208 offset:2048
	ds_read_b128 v[174:177], v208 offset:3072
	ds_read_b128 v[146:149], v209
	ds_read_b128 v[150:153], v209 offset:1024
	ds_read_b128 v[154:157], v209 offset:2048
	ds_read_b128 v[158:161], v209 offset:3072
	v_lshl_add_u64 v[42:43], v[196:197], 0, s[56:57]
	s_add_i32 m0, s69, 0xc000
	ds_read_b128 v[212:215], v210
	ds_read_b128 v[216:219], v210 offset:1024
	ds_read_b128 v[222:225], v210 offset:2048
	ds_read_b128 v[226:229], v210 offset:3072
	ds_read_b128 v[230:233], v210 offset:4096
	ds_read_b128 v[234:237], v210 offset:5120
	ds_read_b128 v[238:241], v210 offset:6144
	ds_read_b128 v[242:245], v210 offset:7168
	global_load_lds_dwordx4 v[42:43], off
	v_lshl_add_u64 v[42:43], v[198:199], 0, s[56:57]
	s_add_i32 m0, s69, 0xe000
	s_nop 0
	global_load_lds_dwordx4 v[42:43], off
	s_waitcnt vmcnt(8) lgkmcnt(0)
	s_barrier
	s_setprio 1
	v_mfma_f32_16x16x32_bf16 v[42:45], v[162:165], v[212:215], v[142:145]
	v_mfma_f32_16x16x32_bf16 v[46:49], v[170:173], v[212:215], v[138:141]
	v_mfma_f32_16x16x32_bf16 v[50:53], v[162:165], v[222:225], v[126:129]
	v_mfma_f32_16x16x32_bf16 v[54:57], v[170:173], v[222:225], v[122:125]
	v_mfma_f32_16x16x32_bf16 v[110:113], v[162:165], v[230:233], v[110:113]
	v_mfma_f32_16x16x32_bf16 v[106:109], v[170:173], v[230:233], v[106:109]
	v_mfma_f32_16x16x32_bf16 v[94:97], v[162:165], v[238:241], v[94:97]
	v_mfma_f32_16x16x32_bf16 v[90:93], v[170:173], v[238:241], v[90:93]
	v_mfma_f32_16x16x32_bf16 v[42:45], v[166:169], v[216:219], v[42:45]
	v_mfma_f32_16x16x32_bf16 v[46:49], v[174:177], v[216:219], v[46:49]
	v_mfma_f32_16x16x32_bf16 v[50:53], v[166:169], v[226:229], v[50:53]
	v_mfma_f32_16x16x32_bf16 v[54:57], v[174:177], v[226:229], v[54:57]
	v_mfma_f32_16x16x32_bf16 v[110:113], v[166:169], v[234:237], v[110:113]
	v_mfma_f32_16x16x32_bf16 v[106:109], v[174:177], v[234:237], v[106:109]
	v_mfma_f32_16x16x32_bf16 v[94:97], v[166:169], v[242:245], v[94:97]
	v_mfma_f32_16x16x32_bf16 v[90:93], v[174:177], v[242:245], v[90:93]
	v_mfma_f32_16x16x32_bf16 v[122:125], v[146:149], v[212:215], v[134:137]
	v_mfma_f32_16x16x32_bf16 v[134:137], v[150:153], v[216:219], v[122:125]
	v_mfma_f32_16x16x32_bf16 v[122:125], v[154:157], v[212:215], v[130:133]
	v_mfma_f32_16x16x32_bf16 v[118:121], v[146:149], v[222:225], v[118:121]
	v_mfma_f32_16x16x32_bf16 v[114:117], v[154:157], v[222:225], v[114:117]
	v_mfma_f32_16x16x32_bf16 v[102:105], v[146:149], v[230:233], v[102:105]
	v_mfma_f32_16x16x32_bf16 v[98:101], v[154:157], v[230:233], v[98:101]
	v_mfma_f32_16x16x32_bf16 v[86:89], v[146:149], v[238:241], v[86:89]
	v_mfma_f32_16x16x32_bf16 v[82:85], v[154:157], v[238:241], v[82:85]
	v_mfma_f32_16x16x32_bf16 v[130:133], v[158:161], v[216:219], v[122:125]
	v_mfma_f32_16x16x32_bf16 v[118:121], v[150:153], v[226:229], v[118:121]
	v_mfma_f32_16x16x32_bf16 v[114:117], v[158:161], v[226:229], v[114:117]
	v_mfma_f32_16x16x32_bf16 v[102:105], v[150:153], v[234:237], v[102:105]
	v_mfma_f32_16x16x32_bf16 v[98:101], v[158:161], v[234:237], v[98:101]
	v_mfma_f32_16x16x32_bf16 v[86:89], v[150:153], v[242:245], v[86:89]
	v_mfma_f32_16x16x32_bf16 v[82:85], v[158:161], v[242:245], v[82:85]
	s_setprio 0
	s_barrier
	s_cmp_lg_u32 s63, s28
	s_cbranch_scc1 .LBB0_438
	v_mov_b32_e32 v186, v207
	s_add_i32 m0, s62, 0x20000
	v_lshl_add_u64 v[122:123], s[52:53], 0, v[186:187]
	s_mov_b64 s[58:59], 0x400
	global_load_lds_dwordx4 v186, s[52:53]
	v_lshl_add_u64 v[122:123], v[122:123], 0, s[58:59]
	s_add_i32 m0, s62, 0x20400
	s_andn2_b64 vcc, exec, s[40:41]
	global_load_lds_dwordx4 v[122:123], off
	s_cbranch_vccnz .LBB0_438
	v_lshl_add_u64 v[122:123], s[54:55], 0, v[186:187]
	s_mov_b32 m0, s30
	s_nop 0
	global_load_lds_dwordx4 v[122:123], off
	s_branch .LBB0_438

; #define PG8_STAGE(bufoff, gbase, voff) do { _Pragma("unroll") for (int _i = 0; _i < 2; ++_i) \
;         __builtin_amdgcn_global_load_lds((const unsigned*)((const char*)(gbase) + (voff)[_i]), (PG8_LAS unsigned*)(lds + (bufoff) + ldsw + _i * 8192), 16, 0, 0); } while (0)
; #define PG8_LDA(dst, b, h) do { _Pragma("unroll") for (int m = 0; m < 4; ++m) _Pragma("unroll") for (int k = 0; k < 2; ++k) dst[m][k] = *(const PG8_LAS bf16x8*)(lds + PG8_SA(b, h) + aoff + m * 2048 + k * 1024); } while (0)
; #define PG8_LDB(dst, b, h) do { _Pragma("unroll") for (int n = 0; n < 2; ++n) _Pragma("unroll") for (int k = 0; k < 2; ++k) dst[n][k] = *(const PG8_LAS bf16x8*)(lds + PG8_SB(b, h) + boff + n * 2048 + k * 1024); } while (0)
; #define PG8_MMA(ai, bj, At, Bt) do { __builtin_amdgcn_s_setprio(1); _Pragma("unroll") for (int m = 0; m < 4; ++m) _Pragma("unroll") for (int n = 0; n < 2; ++n) _Pragma("unroll") for (int k = 0; k < 2; ++k) \
;         acc[ai][bj][m][n] = __builtin_amdgcn_mfma_f32_16x16x32_bf16(Bt[n][k], At[m][k], acc[ai][bj][m][n], 0, 0, 0); __builtin_amdgcn_s_setprio(0); } while (0)
; #define PG8_WAIT_V(n) asm volatile("s_waitcnt vmcnt(" #n ")" ::: "memory")
; template <class Epi, class Sched, bool ALIGN_EPI = false, bool SP2 = false>
; __device__ __forceinline__ void gemm_phase(PG8_LAS unsigned char* lds, const Gemm g, const Sched& S, const Epi& E) {
;     ...
;             const bool last = (t == nt - 2);
;             const char* a1 = cA + (size_t)(t + 1) * kstepA;
;             const char* a2 = last ? nA : cA + (size_t)(t + 2) * kstepA; const char* b2 = last ? nB : cB + (size_t)(t + 2) * kstep;
;             const char* a3 = a2 + kstepA; const char* b3 = b2 + kstep;
;             if (last && has_next) S.a_ready(nxt);
;             if constexpr (SP2) {
;             PG8_LDB(B0, 0, 0); PG8_LDB(B1, 0, 1); PG8_SCHED; PG8_LDA(At, 0, 0); PG8_STAGE(PG8_SA(1, 1), a1 + hstep, voffA);
;             PG8_WAIT_V(8); PG8_WAIT_L(0); PG8_BAR; PG8_MMA(0, 0, At, B0); PG8_MMA(0, 1, At, B1); PG8_BAR; PG8_SCHED;
;             if constexpr (Epi::PREFETCH) { if (t == tpf) E.prefetch(cur, wid, lane); }
;             PG8_LDA(At, 0, 1); PG8_STAGE(PG8_SB(0, 0), b2, voffB); PG8_STAGE(PG8_SB(0, 1), b2 + hstep, voffB); PG8_STAGE(PG8_SA(0, 0), a2, voffA);
;             PG8_WAIT_V(8); PG8_WAIT_L(0); PG8_BAR; PG8_MMA(1, 0, At, B0); PG8_MMA(1, 1, At, B1); PG8_BAR; PG8_SCHED;
.LBB0_723:
	v_add_u32_e32 v2, s67, v177
	ds_read_b128 v[134:137], v2
	ds_read_b128 v[138:141], v2 offset:1024
	ds_read_b128 v[142:145], v2 offset:2048
	ds_read_b128 v[146:149], v2 offset:3072
	v_add_u32_e32 v2, s68, v177
	ds_read_b128 v[150:153], v2
	ds_read_b128 v[170:173], v2 offset:1024
	ds_read_b128 v[180:183], v2 offset:2048
	ds_read_b128 v[184:187], v2 offset:3072
	s_add_u32 s28, s0, 0xfffc0080
	s_addc_u32 s29, s1, -1
	s_cmp_eq_u32 s43, 12
	s_cselect_b32 s37, s23, s29
	s_cselect_b32 s36, s39, s28
	s_cselect_b32 s29, s21, s42
	s_cselect_b32 s28, s40, s41
	v_lshl_add_u64 v[4:5], s[0:1], 0, v[162:163]
	s_add_i32 m0, s31, 0xc000
	ds_read_b128 v[188:191], v178
	ds_read_b128 v[192:195], v178 offset:1024
	ds_read_b128 v[196:199], v178 offset:2048
	ds_read_b128 v[200:203], v178 offset:3072
	ds_read_b128 v[204:207], v178 offset:4096
	ds_read_b128 v[208:211], v178 offset:5120
	ds_read_b128 v[212:215], v178 offset:6144
	ds_read_b128 v[216:219], v178 offset:7168
	global_load_lds_dwordx4 v[4:5], off
	v_lshl_add_u64 v[4:5], s[0:1], 0, v[164:165]
	s_add_i32 m0, s31, 0xe000
	s_nop 0
	global_load_lds_dwordx4 v[4:5], off
	s_waitcnt vmcnt(8) lgkmcnt(0)
	s_barrier
	s_setprio 1
	v_mfma_f32_16x16x32_bf16 v[130:133], v[134:137], v[188:191], v[130:133]
	v_mfma_f32_16x16x32_bf16 v[126:129], v[142:145], v[188:191], v[126:129]
	v_mfma_f32_16x16x32_bf16 v[122:125], v[134:137], v[196:199], v[122:125]
	v_mfma_f32_16x16x32_bf16 v[118:121], v[142:145], v[196:199], v[118:121]
	v_mfma_f32_16x16x32_bf16 v[114:117], v[134:137], v[204:207], v[114:117]
	v_mfma_f32_16x16x32_bf16 v[110:113], v[142:145], v[204:207], v[110:113]
	v_mfma_f32_16x16x32_bf16 v[106:109], v[134:137], v[212:215], v[106:109]
	v_mfma_f32_16x16x32_bf16 v[102:105], v[142:145], v[212:215], v[102:105]
	v_mfma_f32_16x16x32_bf16 v[130:133], v[138:141], v[192:195], v[130:133]
	v_mfma_f32_16x16x32_bf16 v[126:129], v[146:149], v[192:195], v[126:129]
	v_mfma_f32_16x16x32_bf16 v[122:125], v[138:141], v[200:203], v[122:125]
	v_mfma_f32_16x16x32_bf16 v[118:121], v[146:149], v[200:203], v[118:121]
	v_mfma_f32_16x16x32_bf16 v[114:117], v[138:141], v[208:211], v[114:117]
	v_mfma_f32_16x16x32_bf16 v[110:113], v[146:149], v[208:211], v[110:113]
	v_mfma_f32_16x16x32_bf16 v[106:109], v[138:141], v[216:219], v[106:109]
	v_mfma_f32_16x16x32_bf16 v[102:105], v[146:149], v[216:219], v[102:105]
	v_mfma_f32_16x16x32_bf16 v[98:101], v[150:153], v[188:191], v[98:101]
	v_mfma_f32_16x16x32_bf16 v[94:97], v[180:183], v[188:191], v[94:97]
	v_mfma_f32_16x16x32_bf16 v[90:93], v[150:153], v[196:199], v[90:93]
	v_mfma_f32_16x16x32_bf16 v[86:89], v[180:183], v[196:199], v[86:89]
	v_mfma_f32_16x16x32_bf16 v[82:85], v[150:153], v[204:207], v[82:85]
	v_mfma_f32_16x16x32_bf16 v[78:81], v[180:183], v[204:207], v[78:81]
	v_mfma_f32_16x16x32_bf16 v[74:77], v[150:153], v[212:215], v[74:77]
	v_mfma_f32_16x16x32_bf16 v[70:73], v[180:183], v[212:215], v[70:73]
	v_mfma_f32_16x16x32_bf16 v[98:101], v[170:173], v[192:195], v[98:101]
	v_mfma_f32_16x16x32_bf16 v[94:97], v[184:187], v[192:195], v[94:97]
	v_mfma_f32_16x16x32_bf16 v[90:93], v[170:173], v[200:203], v[90:93]
	v_mfma_f32_16x16x32_bf16 v[86:89], v[184:187], v[200:203], v[86:89]
	v_mfma_f32_16x16x32_bf16 v[82:85], v[170:173], v[208:211], v[82:85]
	v_mfma_f32_16x16x32_bf16 v[78:81], v[184:187], v[208:211], v[78:81]
	v_mfma_f32_16x16x32_bf16 v[74:77], v[170:173], v[216:219], v[74:77]
	v_mfma_f32_16x16x32_bf16 v[70:73], v[184:187], v[216:219], v[70:73]
	s_setprio 0
	s_barrier
	s_add_i32 s71, s67, s48
	v_lshl_add_u64 v[174:175], s[28:29], 0, v[156:157]
	s_mov_b32 m0, s71
	ds_read_b128 v[188:191], v178 offset:16384
	ds_read_b128 v[192:195], v178 offset:17408
	ds_read_b128 v[196:199], v178 offset:18432
	ds_read_b128 v[200:203], v178 offset:19456
	ds_read_b128 v[204:207], v178 offset:20480
	ds_read_b128 v[208:211], v178 offset:21504
	ds_read_b128 v[212:215], v178 offset:22528
	ds_read_b128 v[216:219], v178 offset:23552
	global_load_lds_dwordx4 v[174:175], off
	s_add_i32 m0, s71, 0x2000
	s_add_u32 s72, s28, 0x40000
	v_lshl_add_u64 v[222:223], s[28:29], 0, v[160:161]
	s_addc_u32 s73, s29, 0
	s_add_i32 s71, s68, s48
	global_load_lds_dwordx4 v[222:223], off
	v_lshl_add_u64 v[4:5], s[72:73], 0, v[156:157]
	s_mov_b32 m0, s71
	v_lshl_add_u64 v[224:225], s[36:37], 0, v[154:155]
	global_load_lds_dwordx4 v[4:5], off
	v_lshl_add_u64 v[4:5], s[72:73], 0, v[160:161]
	s_add_i32 m0, s71, 0x2000
	v_lshl_add_u64 v[226:227], s[36:37], 0, v[158:159]
	global_load_lds_dwordx4 v[4:5], off
	s_mov_b32 m0, s31
	s_nop 0
	global_load_lds_dwordx4 v[224:225], off
	s_mov_b32 m0, s35
	s_nop 0
	global_load_lds_dwordx4 v[226:227], off
	s_waitcnt vmcnt(8) lgkmcnt(0)
	s_barrier
; #define PG8_STAGE(bufoff, gbase, voff) do { _Pragma("unroll") for (int _i = 0; _i < 2; ++_i) \
;         __builtin_amdgcn_global_load_lds((const unsigned*)((const char*)(gbase) + (voff)[_i]), (PG8_LAS unsigned*)(lds + (bufoff) + ldsw + _i * 8192), 16, 0, 0); } while (0)
; #define PG8_LDA(dst, b, h) do { _Pragma("unroll") for (int m = 0; m < 4; ++m) _Pragma("unroll") for (int k = 0; k < 2; ++k) dst[m][k] = *(const PG8_LAS bf16x8*)(lds + PG8_SA(b, h) + aoff + m * 2048 + k * 1024); } while (0)
; #define PG8_LDB(dst, b, h) do { _Pragma("unroll") for (int n = 0; n < 2; ++n) _Pragma("unroll") for (int k = 0; k < 2; ++k) dst[n][k] = *(const PG8_LAS bf16x8*)(lds + PG8_SB(b, h) + boff + n * 2048 + k * 1024); } while (0)
; #define PG8_MMA(ai, bj, At, Bt) do { __builtin_amdgcn_s_setprio(1); _Pragma("unroll") for (int m = 0; m < 4; ++m) _Pragma("unroll") for (int n = 0; n < 2; ++n) _Pragma("unroll") for (int k = 0; k < 2; ++k) \
;         acc[ai][bj][m][n] = __builtin_amdgcn_mfma_f32_16x16x32_bf16(Bt[n][k], At[m][k], acc[ai][bj][m][n], 0, 0, 0); __builtin_amdgcn_s_setprio(0); } while (0)
; #define PG8_WAIT_V(n) asm volatile("s_waitcnt vmcnt(" #n ")" ::: "memory")
; #define PG8_WAIT_L(n) asm volatile("s_waitcnt lgkmcnt(" #n ")" ::: "memory")
; #define PG8_BAR __builtin_amdgcn_s_barrier()
; #define PG8_SCHED __builtin_amdgcn_sched_barrier(0)
; template <class Epi, class Sched, bool ALIGN_EPI = false, bool SP2 = false>
; __device__ __forceinline__ void gemm_phase(PG8_LAS unsigned char* lds, const Gemm g, const Sched& S, const Epi& E) {
;     ...
;             PG8_WAIT_V(8); PG8_WAIT_L(0); PG8_BAR; PG8_MMA(1, 0, At, B0); PG8_MMA(1, 1, At, B1); PG8_BAR; PG8_SCHED;
;             PG8_LDB(B0, 1, 0); PG8_LDB(B1, 1, 1); PG8_SCHED; PG8_LDA(At, 1, 0); PG8_STAGE(PG8_SA(0, 1), a2 + hstep, voffA);
;             PG8_WAIT_V(8); PG8_WAIT_L(0); PG8_BAR; PG8_MMA(0, 0, At, B0); PG8_MMA(0, 1, At, B1); PG8_BAR; PG8_SCHED;
	s_setprio 1
	v_mfma_f32_16x16x32_bf16 v[66:69], v[134:137], v[188:191], v[66:69]
	v_mfma_f32_16x16x32_bf16 v[62:65], v[142:145], v[188:191], v[62:65]
	v_mfma_f32_16x16x32_bf16 v[58:61], v[134:137], v[196:199], v[58:61]
	v_mfma_f32_16x16x32_bf16 v[54:57], v[142:145], v[196:199], v[54:57]
	v_mfma_f32_16x16x32_bf16 v[50:53], v[134:137], v[204:207], v[50:53]
	v_mfma_f32_16x16x32_bf16 v[46:49], v[142:145], v[204:207], v[46:49]
	v_mfma_f32_16x16x32_bf16 v[42:45], v[134:137], v[212:215], v[42:45]
	v_mfma_f32_16x16x32_bf16 v[38:41], v[142:145], v[212:215], v[38:41]
	v_mfma_f32_16x16x32_bf16 v[66:69], v[138:141], v[192:195], v[66:69]
	v_mfma_f32_16x16x32_bf16 v[62:65], v[146:149], v[192:195], v[62:65]
	v_mfma_f32_16x16x32_bf16 v[58:61], v[138:141], v[200:203], v[58:61]
	v_mfma_f32_16x16x32_bf16 v[54:57], v[146:149], v[200:203], v[54:57]
	v_mfma_f32_16x16x32_bf16 v[50:53], v[138:141], v[208:211], v[50:53]
	v_mfma_f32_16x16x32_bf16 v[46:49], v[146:149], v[208:211], v[46:49]
	v_mfma_f32_16x16x32_bf16 v[42:45], v[138:141], v[216:219], v[42:45]
	v_mfma_f32_16x16x32_bf16 v[38:41], v[146:149], v[216:219], v[38:41]
	v_mfma_f32_16x16x32_bf16 v[34:37], v[150:153], v[188:191], v[34:37]
	v_mfma_f32_16x16x32_bf16 v[30:33], v[180:183], v[188:191], v[30:33]
	v_mfma_f32_16x16x32_bf16 v[26:29], v[150:153], v[196:199], v[26:29]
	v_mfma_f32_16x16x32_bf16 v[22:25], v[180:183], v[196:199], v[22:25]
	v_mfma_f32_16x16x32_bf16 v[18:21], v[150:153], v[204:207], v[18:21]
	v_mfma_f32_16x16x32_bf16 v[14:17], v[180:183], v[204:207], v[14:17]
	v_mfma_f32_16x16x32_bf16 v[10:13], v[150:153], v[212:215], v[10:13]
	v_mfma_f32_16x16x32_bf16 v[4:7], v[180:183], v[212:215], v[6:9]
	v_mfma_f32_16x16x32_bf16 v[34:37], v[170:173], v[192:195], v[34:37]
	v_mfma_f32_16x16x32_bf16 v[30:33], v[184:187], v[192:195], v[30:33]
	v_mfma_f32_16x16x32_bf16 v[26:29], v[170:173], v[200:203], v[26:29]
	v_mfma_f32_16x16x32_bf16 v[22:25], v[184:187], v[200:203], v[22:25]
	v_mfma_f32_16x16x32_bf16 v[18:21], v[170:173], v[208:211], v[18:21]
	v_mfma_f32_16x16x32_bf16 v[14:17], v[184:187], v[208:211], v[14:17]
	v_mfma_f32_16x16x32_bf16 v[10:13], v[170:173], v[216:219], v[10:13]
	v_mfma_f32_16x16x32_bf16 v[4:7], v[184:187], v[216:219], v[4:7]
	s_setprio 0
	s_barrier
	s_add_i32 s71, 0, 0x18000
	v_add_u32_e32 v2, s71, v177
	s_add_i32 s72, 0, 0x1c000
	ds_read_b128 v[134:137], v2
	ds_read_b128 v[138:141], v2 offset:1024
	ds_read_b128 v[142:145], v2 offset:2048
	ds_read_b128 v[146:149], v2 offset:3072
	v_add_u32_e32 v2, s72, v177
	ds_read_b128 v[150:153], v2
	ds_read_b128 v[170:173], v2 offset:1024
	ds_read_b128 v[180:183], v2 offset:2048
	ds_read_b128 v[184:187], v2 offset:3072
	s_add_u32 s36, s36, 0x40000
	s_addc_u32 s37, s37, 0
	s_mov_b32 m0, s49
	v_lshl_add_u64 v[8:9], s[36:37], 0, v[154:155]
	ds_read_b128 v[188:191], v178 offset:32768
	ds_read_b128 v[192:195], v178 offset:33792
	ds_read_b128 v[196:199], v178 offset:34816
	ds_read_b128 v[200:203], v178 offset:35840
	ds_read_b128 v[204:207], v178 offset:36864
	ds_read_b128 v[208:211], v178 offset:37888
	ds_read_b128 v[212:215], v178 offset:38912
	ds_read_b128 v[216:219], v178 offset:39936
	global_load_lds_dwordx4 v[8:9], off
	v_lshl_add_u64 v[8:9], s[36:37], 0, v[158:159]
	s_mov_b32 m0, s50
	s_nop 0
	global_load_lds_dwordx4 v[8:9], off
	s_waitcnt vmcnt(8) lgkmcnt(0)
	s_barrier
	s_setprio 1
	v_mfma_f32_16x16x32_bf16 v[130:133], v[134:137], v[188:191], v[130:133]
	v_mfma_f32_16x16x32_bf16 v[126:129], v[142:145], v[188:191], v[126:129]
	v_mfma_f32_16x16x32_bf16 v[122:125], v[134:137], v[196:199], v[122:125]
	v_mfma_f32_16x16x32_bf16 v[118:121], v[142:145], v[196:199], v[118:121]
	v_mfma_f32_16x16x32_bf16 v[114:117], v[134:137], v[204:207], v[114:117]
	v_mfma_f32_16x16x32_bf16 v[110:113], v[142:145], v[204:207], v[110:113]
	v_mfma_f32_16x16x32_bf16 v[106:109], v[134:137], v[212:215], v[106:109]
	v_mfma_f32_16x16x32_bf16 v[102:105], v[142:145], v[212:215], v[102:105]
	v_mfma_f32_16x16x32_bf16 v[130:133], v[138:141], v[192:195], v[130:133]
	v_mfma_f32_16x16x32_bf16 v[126:129], v[146:149], v[192:195], v[126:129]
	v_mfma_f32_16x16x32_bf16 v[122:125], v[138:141], v[200:203], v[122:125]
	v_mfma_f32_16x16x32_bf16 v[118:121], v[146:149], v[200:203], v[118:121]
	v_mfma_f32_16x16x32_bf16 v[114:117], v[138:141], v[208:211], v[114:117]
	v_mfma_f32_16x16x32_bf16 v[110:113], v[146:149], v[208:211], v[110:113]
	v_mfma_f32_16x16x32_bf16 v[106:109], v[138:141], v[216:219], v[106:109]
	v_mfma_f32_16x16x32_bf16 v[102:105], v[146:149], v[216:219], v[102:105]
	v_mfma_f32_16x16x32_bf16 v[98:101], v[150:153], v[188:191], v[98:101]
	v_mfma_f32_16x16x32_bf16 v[94:97], v[180:183], v[188:191], v[94:97]
	v_mfma_f32_16x16x32_bf16 v[90:93], v[150:153], v[196:199], v[90:93]
	v_mfma_f32_16x16x32_bf16 v[86:89], v[180:183], v[196:199], v[86:89]
	v_mfma_f32_16x16x32_bf16 v[82:85], v[150:153], v[204:207], v[82:85]
	v_mfma_f32_16x16x32_bf16 v[78:81], v[180:183], v[204:207], v[78:81]
	v_mfma_f32_16x16x32_bf16 v[74:77], v[150:153], v[212:215], v[74:77]
	v_mfma_f32_16x16x32_bf16 v[70:73], v[180:183], v[212:215], v[70:73]
	v_mfma_f32_16x16x32_bf16 v[98:101], v[170:173], v[192:195], v[98:101]
	v_mfma_f32_16x16x32_bf16 v[94:97], v[184:187], v[192:195], v[94:97]
	v_mfma_f32_16x16x32_bf16 v[90:93], v[170:173], v[200:203], v[90:93]
	v_mfma_f32_16x16x32_bf16 v[86:89], v[184:187], v[200:203], v[86:89]
	v_mfma_f32_16x16x32_bf16 v[82:85], v[170:173], v[208:211], v[82:85]
	v_mfma_f32_16x16x32_bf16 v[78:81], v[184:187], v[208:211], v[78:81]
	v_mfma_f32_16x16x32_bf16 v[74:77], v[170:173], v[216:219], v[74:77]
	v_mfma_f32_16x16x32_bf16 v[70:73], v[184:187], v[216:219], v[70:73]
	s_setprio 0
	s_barrier
; #define PG8_STAGE(bufoff, gbase, voff) do { _Pragma("unroll") for (int _i = 0; _i < 2; ++_i) \
;         __builtin_amdgcn_global_load_lds((const unsigned*)((const char*)(gbase) + (voff)[_i]), (PG8_LAS unsigned*)(lds + (bufoff) + ldsw + _i * 8192), 16, 0, 0); } while (0)
; #define PG8_LDA(dst, b, h) do { _Pragma("unroll") for (int m = 0; m < 4; ++m) _Pragma("unroll") for (int k = 0; k < 2; ++k) dst[m][k] = *(const PG8_LAS bf16x8*)(lds + PG8_SA(b, h) + aoff + m * 2048 + k * 1024); } while (0)
; #define PG8_MMA(ai, bj, At, Bt) do { __builtin_amdgcn_s_setprio(1); _Pragma("unroll") for (int m = 0; m < 4; ++m) _Pragma("unroll") for (int n = 0; n < 2; ++n) _Pragma("unroll") for (int k = 0; k < 2; ++k) \
;         acc[ai][bj][m][n] = __builtin_amdgcn_mfma_f32_16x16x32_bf16(Bt[n][k], At[m][k], acc[ai][bj][m][n], 0, 0, 0); __builtin_amdgcn_s_setprio(0); } while (0)
; #define PG8_WAIT_V(n) asm volatile("s_waitcnt vmcnt(" #n ")" ::: "memory")
; #define PG8_WAIT_L(n) asm volatile("s_waitcnt lgkmcnt(" #n ")" ::: "memory")
; #define PG8_BAR __builtin_amdgcn_s_barrier()
; #define PG8_SCHED __builtin_amdgcn_sched_barrier(0)
; template <class Epi, class Sched, bool ALIGN_EPI = false, bool SP2 = false>
; __device__ __forceinline__ void gemm_phase(PG8_LAS unsigned char* lds, const Gemm g, const Sched& S, const Epi& E) {
;     ...
;             PG8_LDA(At, 1, 1); PG8_STAGE(PG8_SB(1, 0), b3, voffB); PG8_STAGE(PG8_SB(1, 1), b3 + hstep, voffB); PG8_STAGE(PG8_SA(1, 0), a3, voffA);
;             PG8_WAIT_V(8); PG8_WAIT_L(0); PG8_BAR; PG8_MMA(1, 0, At, B0); PG8_MMA(1, 1, At, B1); PG8_BAR; PG8_SCHED;
;     ...
;         }
;         if constexpr (ALIGN_EPI) { if (wr == 0) PG8_BAR; }
	s_add_i32 s36, s71, s48
	v_lshl_add_u64 v[8:9], v[174:175], 0, s[14:15]
	s_mov_b32 m0, s36
	ds_read_b128 v[188:191], v178 offset:49152
	ds_read_b128 v[192:195], v178 offset:50176
	ds_read_b128 v[196:199], v178 offset:51200
	ds_read_b128 v[200:203], v178 offset:52224
	ds_read_b128 v[204:207], v178 offset:53248
	ds_read_b128 v[208:211], v178 offset:54272
	ds_read_b128 v[212:215], v178 offset:55296
	ds_read_b128 v[216:219], v178 offset:56320
	global_load_lds_dwordx4 v[8:9], off
	s_add_i32 m0, s36, 0x2000
	s_add_u32 s28, s28, 0x40080
	v_lshl_add_u64 v[8:9], v[222:223], 0, s[14:15]
	s_addc_u32 s29, s29, 0
	s_add_i32 s36, s72, s48
	global_load_lds_dwordx4 v[8:9], off
	v_lshl_add_u64 v[8:9], s[28:29], 0, v[156:157]
	s_mov_b32 m0, s36
	s_nop 0
	global_load_lds_dwordx4 v[8:9], off
	v_lshl_add_u64 v[8:9], s[28:29], 0, v[160:161]
	s_add_i32 m0, s36, 0x2000
	s_nop 0
	global_load_lds_dwordx4 v[8:9], off
	v_lshl_add_u64 v[8:9], v[224:225], 0, s[14:15]
	s_mov_b32 m0, s58
	s_nop 0
	global_load_lds_dwordx4 v[8:9], off
	v_lshl_add_u64 v[8:9], v[226:227], 0, s[14:15]
	s_mov_b32 m0, s59
	s_nop 0
	global_load_lds_dwordx4 v[8:9], off
	s_waitcnt vmcnt(8) lgkmcnt(0)
	s_barrier
	s_setprio 1
	v_mfma_f32_16x16x32_bf16 v[66:69], v[134:137], v[188:191], v[66:69]
	v_mfma_f32_16x16x32_bf16 v[62:65], v[142:145], v[188:191], v[62:65]
	v_mfma_f32_16x16x32_bf16 v[58:61], v[134:137], v[196:199], v[58:61]
	v_mfma_f32_16x16x32_bf16 v[54:57], v[142:145], v[196:199], v[54:57]
	v_mfma_f32_16x16x32_bf16 v[50:53], v[134:137], v[204:207], v[50:53]
	v_mfma_f32_16x16x32_bf16 v[46:49], v[142:145], v[204:207], v[46:49]
	v_mfma_f32_16x16x32_bf16 v[42:45], v[134:137], v[212:215], v[42:45]
	v_mfma_f32_16x16x32_bf16 v[38:41], v[142:145], v[212:215], v[38:41]
	v_mfma_f32_16x16x32_bf16 v[66:69], v[138:141], v[192:195], v[66:69]
	v_mfma_f32_16x16x32_bf16 v[62:65], v[146:149], v[192:195], v[62:65]
	v_mfma_f32_16x16x32_bf16 v[58:61], v[138:141], v[200:203], v[58:61]
	v_mfma_f32_16x16x32_bf16 v[54:57], v[146:149], v[200:203], v[54:57]
	v_mfma_f32_16x16x32_bf16 v[50:53], v[138:141], v[208:211], v[50:53]
	v_mfma_f32_16x16x32_bf16 v[46:49], v[146:149], v[208:211], v[46:49]
	v_mfma_f32_16x16x32_bf16 v[42:45], v[138:141], v[216:219], v[42:45]
	v_mfma_f32_16x16x32_bf16 v[38:41], v[146:149], v[216:219], v[38:41]
	v_mfma_f32_16x16x32_bf16 v[34:37], v[150:153], v[188:191], v[34:37]
	v_mfma_f32_16x16x32_bf16 v[30:33], v[180:183], v[188:191], v[30:33]
	v_mfma_f32_16x16x32_bf16 v[26:29], v[150:153], v[196:199], v[26:29]
	v_mfma_f32_16x16x32_bf16 v[22:25], v[180:183], v[196:199], v[22:25]
	v_mfma_f32_16x16x32_bf16 v[18:21], v[150:153], v[204:207], v[18:21]
	v_mfma_f32_16x16x32_bf16 v[14:17], v[180:183], v[204:207], v[14:17]
	v_mfma_f32_16x16x32_bf16 v[8:11], v[150:153], v[212:215], v[10:13]
	v_mfma_f32_16x16x32_bf16 v[4:7], v[180:183], v[212:215], v[4:7]
	v_mfma_f32_16x16x32_bf16 v[34:37], v[170:173], v[192:195], v[34:37]
	v_mfma_f32_16x16x32_bf16 v[30:33], v[184:187], v[192:195], v[30:33]
	v_mfma_f32_16x16x32_bf16 v[26:29], v[170:173], v[200:203], v[26:29]
	v_mfma_f32_16x16x32_bf16 v[22:25], v[184:187], v[200:203], v[22:25]
	v_mfma_f32_16x16x32_bf16 v[18:21], v[170:173], v[208:211], v[18:21]
	v_mfma_f32_16x16x32_bf16 v[14:17], v[184:187], v[208:211], v[14:17]
	v_mfma_f32_16x16x32_bf16 v[10:13], v[170:173], v[216:219], v[8:11]
	v_mfma_f32_16x16x32_bf16 v[6:9], v[184:187], v[216:219], v[4:7]
	s_setprio 0
	s_barrier
	s_add_i32 s43, s43, 2
	s_add_u32 s0, s0, 0x100
	s_addc_u32 s1, s1, 0
	s_add_u32 s41, s41, 0x100
	s_addc_u32 s42, s42, 0
	s_cmp_gt_u32 s43, 13
	s_cbranch_scc0 .LBB0_723
	s_and_b64 vcc, exec, s[16:17]
	s_cbranch_vccz .LBB0_726
	s_barrier

;     __host__ __device__ bool next(int i, Unit& u) const { if (!b.next(i >> 1, u)) return false; u.sel = i & 1; return true; }
; #define PG8_STAGE(bufoff, gbase, voff) do { _Pragma("unroll") for (int _i = 0; _i < 2; ++_i) \
;         __builtin_amdgcn_global_load_lds((const unsigned*)((const char*)(gbase) + (voff)[_i]), (PG8_LAS unsigned*)(lds + (bufoff) + ldsw + _i * 8192), 16, 0, 0); } while (0)
; #define PG8_LDA(dst, b, h) do { _Pragma("unroll") for (int m = 0; m < 4; ++m) _Pragma("unroll") for (int k = 0; k < 2; ++k) dst[m][k] = *(const PG8_LAS bf16x8*)(lds + PG8_SA(b, h) + aoff + m * 2048 + k * 1024); } while (0)
; #define PG8_LDB(dst, b, h) do { _Pragma("unroll") for (int n = 0; n < 2; ++n) _Pragma("unroll") for (int k = 0; k < 2; ++k) dst[n][k] = *(const PG8_LAS bf16x8*)(lds + PG8_SB(b, h) + boff + n * 2048 + k * 1024); } while (0)
; #define PG8_WAIT_V(n) asm volatile("s_waitcnt vmcnt(" #n ")" ::: "memory")
; #define PG8_BAR __builtin_amdgcn_s_barrier()
; template <class Epi, class Sched, bool ALIGN_EPI = false, bool SP2 = false>
; __device__ __forceinline__ void gemm_phase(PG8_LAS unsigned char* lds, const Gemm g, const Sched& S, const Epi& E) {
;     ...
;         const bool has_next = S.next(ui + 1, nxt);
;         const char* nA = has_next ? PG8_ABASE(nxt) : cA; const char* nB = has_next ? PG8_BBASE(nxt) : cB;
;         for (int t = 0; t < nt; t += 2) {
;             const bool last = (t == nt - 2);
;             const char* a1 = cA + (size_t)(t + 1) * kstepA;
;             const char* a2 = last ? nA : cA + (size_t)(t + 2) * kstepA; const char* b2 = last ? nB : cB + (size_t)(t + 2) * kstep;
;             const char* a3 = a2 + kstepA; const char* b3 = b2 + kstep;
;             if (last && has_next) S.a_ready(nxt);
;             if constexpr (SP2) {
;             PG8_LDB(B0, 0, 0); PG8_LDB(B1, 0, 1); PG8_SCHED; PG8_LDA(At, 0, 0); PG8_STAGE(PG8_SA(1, 1), a1 + hstep, voffA);
;             PG8_WAIT_V(8); PG8_WAIT_L(0); PG8_BAR; PG8_MMA(0, 0, At, B0); PG8_MMA(0, 1, At, B1); PG8_BAR; PG8_SCHED;
;             if constexpr (Epi::PREFETCH) { if (t == tpf) E.prefetch(cur, wid, lane); }
;             PG8_LDA(At, 0, 1); PG8_STAGE(PG8_SB(0, 0), b2, voffB); PG8_STAGE(PG8_SB(0, 1), b2 + hstep, voffB); PG8_STAGE(PG8_SA(0, 0), a2, voffA);
;             PG8_WAIT_V(8); PG8_WAIT_L(0); PG8_BAR; PG8_MMA(1, 0, At, B0); PG8_MMA(1, 1, At, B1); PG8_BAR; PG8_SCHED;
.LBB0_837:
	s_ashr_i32 s29, s28, 31
	s_lshl_b64 s[30:31], s[28:29], 19
	s_add_u32 s30, s46, s30
	s_addc_u32 s31, s47, s31
	s_and_b64 s[34:35], s[2:3], exec
	s_cselect_b32 s1, s31, s5
	s_cselect_b32 s29, s30, s4
	s_ashr_i32 s27, s26, 31
	s_lshl_b64 s[34:35], s[26:27], 19
	s_add_u32 s34, s48, s34
	s_addc_u32 s35, s49, s35
	s_and_b64 s[36:37], s[2:3], exec
	s_cselect_b32 s27, s35, s7
	s_cselect_b32 s38, s34, s6
	s_add_u32 s4, s4, 0x40080
	s_addc_u32 s5, s5, 0
	s_add_u32 s39, s6, 0x100
	s_addc_u32 s40, s7, 0
	s_mov_b32 s41, -2
	s_waitcnt lgkmcnt(0)
	ds_read_b128 v[50:53], v214
	ds_read_b128 v[54:57], v214 offset:1024
	ds_read_b128 v[66:69], v214 offset:2048
	ds_read_b128 v[70:73], v214 offset:3072
	ds_read_b128 v[146:149], v215
	ds_read_b128 v[150:153], v215 offset:1024
	ds_read_b128 v[172:175], v215 offset:2048
	ds_read_b128 v[176:179], v215 offset:3072
	s_add_u32 s6, s4, 0xfffc0080
	s_addc_u32 s7, s5, -1
	s_cmp_eq_u32 s41, 12
	s_cselect_b32 s37, s1, s7
	s_cselect_b32 s36, s29, s6
	s_cselect_b32 s7, s27, s40
	s_cselect_b32 s6, s38, s39
	v_lshl_add_u64 v[218:219], s[4:5], 0, v[164:165]
	s_add_i32 m0, s51, 0xc000
	ds_read_b128 v[180:183], v216
	ds_read_b128 v[184:187], v216 offset:1024
	ds_read_b128 v[188:191], v216 offset:2048
	ds_read_b128 v[192:195], v216 offset:3072
	ds_read_b128 v[196:199], v216 offset:4096
	ds_read_b128 v[200:203], v216 offset:5120
	ds_read_b128 v[204:207], v216 offset:6144
	ds_read_b128 v[208:211], v216 offset:7168
	global_load_lds_dwordx4 v[218:219], off
	v_lshl_add_u64 v[218:219], s[4:5], 0, v[166:167]
	s_add_i32 m0, s51, 0xe000
	s_nop 0
	global_load_lds_dwordx4 v[218:219], off
	s_waitcnt vmcnt(8) lgkmcnt(0)
	s_barrier
	s_setprio 1
	v_mfma_f32_16x16x32_bf16 v[142:145], v[50:53], v[180:183], 0
	v_mfma_f32_16x16x32_bf16 v[138:141], v[66:69], v[180:183], 0
	v_mfma_f32_16x16x32_bf16 v[126:129], v[50:53], v[188:191], 0
	v_mfma_f32_16x16x32_bf16 v[122:125], v[66:69], v[188:191], 0
	v_mfma_f32_16x16x32_bf16 v[110:113], v[50:53], v[196:199], 0
	v_mfma_f32_16x16x32_bf16 v[106:109], v[66:69], v[196:199], 0
	v_mfma_f32_16x16x32_bf16 v[94:97], v[50:53], v[204:207], 0
	v_mfma_f32_16x16x32_bf16 v[90:93], v[66:69], v[204:207], 0
	v_mfma_f32_16x16x32_bf16 v[142:145], v[54:57], v[184:187], v[142:145]
	v_mfma_f32_16x16x32_bf16 v[138:141], v[70:73], v[184:187], v[138:141]
	v_mfma_f32_16x16x32_bf16 v[126:129], v[54:57], v[192:195], v[126:129]
	v_mfma_f32_16x16x32_bf16 v[122:125], v[70:73], v[192:195], v[122:125]
	v_mfma_f32_16x16x32_bf16 v[110:113], v[54:57], v[200:203], v[110:113]
	v_mfma_f32_16x16x32_bf16 v[106:109], v[70:73], v[200:203], v[106:109]
	v_mfma_f32_16x16x32_bf16 v[94:97], v[54:57], v[208:211], v[94:97]
	v_mfma_f32_16x16x32_bf16 v[90:93], v[70:73], v[208:211], v[90:93]
	v_mfma_f32_16x16x32_bf16 v[134:137], v[146:149], v[180:183], 0
	v_mfma_f32_16x16x32_bf16 v[130:133], v[172:175], v[180:183], 0
	v_mfma_f32_16x16x32_bf16 v[118:121], v[146:149], v[188:191], 0
	v_mfma_f32_16x16x32_bf16 v[114:117], v[172:175], v[188:191], 0
	v_mfma_f32_16x16x32_bf16 v[102:105], v[146:149], v[196:199], 0
	v_mfma_f32_16x16x32_bf16 v[98:101], v[172:175], v[196:199], 0
	v_mfma_f32_16x16x32_bf16 v[86:89], v[146:149], v[204:207], 0
	v_mfma_f32_16x16x32_bf16 v[82:85], v[172:175], v[204:207], 0
	v_mfma_f32_16x16x32_bf16 v[134:137], v[150:153], v[184:187], v[134:137]
	v_mfma_f32_16x16x32_bf16 v[130:133], v[176:179], v[184:187], v[130:133]
	v_mfma_f32_16x16x32_bf16 v[118:121], v[150:153], v[192:195], v[118:121]
	v_mfma_f32_16x16x32_bf16 v[114:117], v[176:179], v[192:195], v[114:117]
	v_mfma_f32_16x16x32_bf16 v[102:105], v[150:153], v[200:203], v[102:105]
	v_mfma_f32_16x16x32_bf16 v[98:101], v[176:179], v[200:203], v[98:101]
	v_mfma_f32_16x16x32_bf16 v[86:89], v[150:153], v[208:211], v[86:89]
	v_mfma_f32_16x16x32_bf16 v[82:85], v[176:179], v[208:211], v[82:85]
	s_setprio 0
	s_barrier
	s_add_i32 s42, s68, s50
	v_lshl_add_u64 v[218:219], s[6:7], 0, v[156:157]
	s_mov_b32 m0, s42
	ds_read_b128 v[180:183], v216 offset:16384
	ds_read_b128 v[184:187], v216 offset:17408
	ds_read_b128 v[188:191], v216 offset:18432
	ds_read_b128 v[192:195], v216 offset:19456
	ds_read_b128 v[196:199], v216 offset:20480
	ds_read_b128 v[200:203], v216 offset:21504
	ds_read_b128 v[204:207], v216 offset:22528
	ds_read_b128 v[208:211], v216 offset:23552
	global_load_lds_dwordx4 v[218:219], off
	s_add_i32 m0, s42, 0x2000
	s_add_u32 s42, s6, 0x40000
	v_lshl_add_u64 v[222:223], s[6:7], 0, v[160:161]
	s_addc_u32 s43, s7, 0
	s_add_i32 s44, s69, s50
	global_load_lds_dwordx4 v[222:223], off
	v_lshl_add_u64 v[224:225], s[42:43], 0, v[156:157]
	s_mov_b32 m0, s44
	v_lshl_add_u64 v[226:227], s[36:37], 0, v[158:159]
	global_load_lds_dwordx4 v[224:225], off
	v_lshl_add_u64 v[224:225], s[42:43], 0, v[160:161]
	s_add_i32 m0, s44, 0x2000
	s_nop 0
	global_load_lds_dwordx4 v[224:225], off
	v_lshl_add_u64 v[224:225], s[36:37], 0, v[154:155]
	s_mov_b32 m0, s51
	s_nop 0
	global_load_lds_dwordx4 v[224:225], off
	s_mov_b32 m0, s52
	s_nop 0
	global_load_lds_dwordx4 v[226:227], off
	s_waitcnt vmcnt(8) lgkmcnt(0)
	s_barrier
; #define PG8_STAGE(bufoff, gbase, voff) do { _Pragma("unroll") for (int _i = 0; _i < 2; ++_i) \
;         __builtin_amdgcn_global_load_lds((const unsigned*)((const char*)(gbase) + (voff)[_i]), (PG8_LAS unsigned*)(lds + (bufoff) + ldsw + _i * 8192), 16, 0, 0); } while (0)
; #define PG8_LDA(dst, b, h) do { _Pragma("unroll") for (int m = 0; m < 4; ++m) _Pragma("unroll") for (int k = 0; k < 2; ++k) dst[m][k] = *(const PG8_LAS bf16x8*)(lds + PG8_SA(b, h) + aoff + m * 2048 + k * 1024); } while (0)
; #define PG8_LDB(dst, b, h) do { _Pragma("unroll") for (int n = 0; n < 2; ++n) _Pragma("unroll") for (int k = 0; k < 2; ++k) dst[n][k] = *(const PG8_LAS bf16x8*)(lds + PG8_SB(b, h) + boff + n * 2048 + k * 1024); } while (0)
; #define PG8_MMA(ai, bj, At, Bt) do { __builtin_amdgcn_s_setprio(1); _Pragma("unroll") for (int m = 0; m < 4; ++m) _Pragma("unroll") for (int n = 0; n < 2; ++n) _Pragma("unroll") for (int k = 0; k < 2; ++k) \
;         acc[ai][bj][m][n] = __builtin_amdgcn_mfma_f32_16x16x32_bf16(Bt[n][k], At[m][k], acc[ai][bj][m][n], 0, 0, 0); __builtin_amdgcn_s_setprio(0); } while (0)
; #define PG8_WAIT_V(n) asm volatile("s_waitcnt vmcnt(" #n ")" ::: "memory")
; #define PG8_WAIT_L(n) asm volatile("s_waitcnt lgkmcnt(" #n ")" ::: "memory")
; #define PG8_BAR __builtin_amdgcn_s_barrier()
; #define PG8_SCHED __builtin_amdgcn_sched_barrier(0)
;     __device__ __forceinline__ void prefetch(const Unit& u, int wid, int lane) const { epi_prefetch(scr, ssq, bias + (size_t)(u.pm >> 5) * NGU + u.pn * BM, u, wid, lane); }
; template <class Epi, class Sched, bool ALIGN_EPI = false, bool SP2 = false>
; __device__ __forceinline__ void gemm_phase(PG8_LAS unsigned char* lds, const Gemm g, const Sched& S, const Epi& E) {
;     ...
;             PG8_LDB(B0, 0, 0); PG8_LDB(B1, 0, 1); PG8_SCHED; PG8_LDA(At, 0, 0); PG8_STAGE(PG8_SA(1, 1), a1 + hstep, voffA);
;             PG8_WAIT_V(8); PG8_WAIT_L(0); PG8_BAR; PG8_MMA(0, 0, At, B0); PG8_MMA(0, 1, At, B1); PG8_BAR; PG8_SCHED;
;             if constexpr (Epi::PREFETCH) { if (t == tpf) E.prefetch(cur, wid, lane); }
;             PG8_LDA(At, 0, 1); PG8_STAGE(PG8_SB(0, 0), b2, voffB); PG8_STAGE(PG8_SB(0, 1), b2 + hstep, voffB); PG8_STAGE(PG8_SA(0, 0), a2, voffA);
;             PG8_WAIT_V(8); PG8_WAIT_L(0); PG8_BAR; PG8_MMA(1, 0, At, B0); PG8_MMA(1, 1, At, B1); PG8_BAR; PG8_SCHED;
	s_setprio 1
	v_mfma_f32_16x16x32_bf16 v[78:81], v[50:53], v[180:183], 0
	v_mfma_f32_16x16x32_bf16 v[74:77], v[66:69], v[180:183], 0
	v_mfma_f32_16x16x32_bf16 v[46:49], v[50:53], v[188:191], 0
	v_mfma_f32_16x16x32_bf16 v[42:45], v[66:69], v[188:191], 0
	v_mfma_f32_16x16x32_bf16 v[30:33], v[50:53], v[196:199], 0
	v_mfma_f32_16x16x32_bf16 v[26:29], v[66:69], v[196:199], 0
	v_mfma_f32_16x16x32_bf16 v[14:17], v[50:53], v[204:207], 0
	v_mfma_f32_16x16x32_bf16 v[10:13], v[66:69], v[204:207], 0
	v_mfma_f32_16x16x32_bf16 v[78:81], v[54:57], v[184:187], v[78:81]
	v_mfma_f32_16x16x32_bf16 v[74:77], v[70:73], v[184:187], v[74:77]
	v_mfma_f32_16x16x32_bf16 v[46:49], v[54:57], v[192:195], v[46:49]
	v_mfma_f32_16x16x32_bf16 v[42:45], v[70:73], v[192:195], v[42:45]
	v_mfma_f32_16x16x32_bf16 v[30:33], v[54:57], v[200:203], v[30:33]
	v_mfma_f32_16x16x32_bf16 v[26:29], v[70:73], v[200:203], v[26:29]
	v_mfma_f32_16x16x32_bf16 v[14:17], v[54:57], v[208:211], v[14:17]
	v_mfma_f32_16x16x32_bf16 v[10:13], v[70:73], v[208:211], v[10:13]
	v_mfma_f32_16x16x32_bf16 v[38:41], v[146:149], v[188:191], 0
	v_mfma_f32_16x16x32_bf16 v[34:37], v[172:175], v[188:191], 0
	v_mfma_f32_16x16x32_bf16 v[22:25], v[146:149], v[196:199], 0
	v_mfma_f32_16x16x32_bf16 v[18:21], v[172:175], v[196:199], 0
	v_mfma_f32_16x16x32_bf16 v[6:9], v[146:149], v[204:207], 0
	v_mfma_f32_16x16x32_bf16 v[2:5], v[172:175], v[204:207], 0
	v_mfma_f32_16x16x32_bf16 v[50:53], v[146:149], v[180:183], 0
	v_mfma_f32_16x16x32_bf16 v[54:57], v[172:175], v[180:183], 0
	v_mfma_f32_16x16x32_bf16 v[38:41], v[150:153], v[192:195], v[38:41]
	v_mfma_f32_16x16x32_bf16 v[34:37], v[176:179], v[192:195], v[34:37]
	v_mfma_f32_16x16x32_bf16 v[22:25], v[150:153], v[200:203], v[22:25]
	v_mfma_f32_16x16x32_bf16 v[18:21], v[176:179], v[200:203], v[18:21]
	v_mfma_f32_16x16x32_bf16 v[6:9], v[150:153], v[208:211], v[6:9]
	v_mfma_f32_16x16x32_bf16 v[2:5], v[176:179], v[208:211], v[2:5]
	v_mfma_f32_16x16x32_bf16 v[50:53], v[150:153], v[184:187], v[50:53]
	v_mfma_f32_16x16x32_bf16 v[54:57], v[176:179], v[184:187], v[54:57]
	s_setprio 0
	s_barrier
	s_branch .Lpz4_mid
.LBB0_838:
	ds_read_b128 v[50:53], v214
	ds_read_b128 v[54:57], v214 offset:1024
	ds_read_b128 v[66:69], v214 offset:2048
	ds_read_b128 v[70:73], v214 offset:3072
	ds_read_b128 v[146:149], v215
	ds_read_b128 v[150:153], v215 offset:1024
	ds_read_b128 v[172:175], v215 offset:2048
	ds_read_b128 v[176:179], v215 offset:3072
	s_add_u32 s6, s4, 0xfffc0080
	s_addc_u32 s7, s5, -1
	s_cmp_eq_u32 s41, 12
	s_cselect_b32 s37, s1, s7
	s_cselect_b32 s36, s29, s6
	s_cselect_b32 s7, s27, s40
	s_cselect_b32 s6, s38, s39
	v_lshl_add_u64 v[218:219], s[4:5], 0, v[164:165]
	s_add_i32 m0, s51, 0xc000
	ds_read_b128 v[180:183], v216
	ds_read_b128 v[184:187], v216 offset:1024
	ds_read_b128 v[188:191], v216 offset:2048
	ds_read_b128 v[192:195], v216 offset:3072
	ds_read_b128 v[196:199], v216 offset:4096
	ds_read_b128 v[200:203], v216 offset:5120
	ds_read_b128 v[204:207], v216 offset:6144
	ds_read_b128 v[208:211], v216 offset:7168
	global_load_lds_dwordx4 v[218:219], off
	v_lshl_add_u64 v[218:219], s[4:5], 0, v[166:167]
	s_add_i32 m0, s51, 0xe000
	s_nop 0
	global_load_lds_dwordx4 v[218:219], off
	s_waitcnt vmcnt(8) lgkmcnt(0)
	s_barrier
	s_setprio 1
	v_mfma_f32_16x16x32_bf16 v[142:145], v[50:53], v[180:183], v[142:145]
	v_mfma_f32_16x16x32_bf16 v[138:141], v[66:69], v[180:183], v[138:141]
	v_mfma_f32_16x16x32_bf16 v[126:129], v[50:53], v[188:191], v[126:129]
	v_mfma_f32_16x16x32_bf16 v[122:125], v[66:69], v[188:191], v[122:125]
	v_mfma_f32_16x16x32_bf16 v[110:113], v[50:53], v[196:199], v[110:113]
	v_mfma_f32_16x16x32_bf16 v[106:109], v[66:69], v[196:199], v[106:109]
	v_mfma_f32_16x16x32_bf16 v[94:97], v[50:53], v[204:207], v[94:97]
	v_mfma_f32_16x16x32_bf16 v[90:93], v[66:69], v[204:207], v[90:93]
	v_mfma_f32_16x16x32_bf16 v[142:145], v[54:57], v[184:187], v[142:145]
	v_mfma_f32_16x16x32_bf16 v[138:141], v[70:73], v[184:187], v[138:141]
	v_mfma_f32_16x16x32_bf16 v[126:129], v[54:57], v[192:195], v[126:129]
	v_mfma_f32_16x16x32_bf16 v[122:125], v[70:73], v[192:195], v[122:125]
	v_mfma_f32_16x16x32_bf16 v[110:113], v[54:57], v[200:203], v[110:113]
	v_mfma_f32_16x16x32_bf16 v[106:109], v[70:73], v[200:203], v[106:109]
	v_mfma_f32_16x16x32_bf16 v[94:97], v[54:57], v[208:211], v[94:97]
	v_mfma_f32_16x16x32_bf16 v[90:93], v[70:73], v[208:211], v[90:93]
	v_mfma_f32_16x16x32_bf16 v[134:137], v[146:149], v[180:183], v[134:137]
	v_mfma_f32_16x16x32_bf16 v[130:133], v[172:175], v[180:183], v[130:133]
	v_mfma_f32_16x16x32_bf16 v[118:121], v[146:149], v[188:191], v[118:121]
	v_mfma_f32_16x16x32_bf16 v[114:117], v[172:175], v[188:191], v[114:117]
	v_mfma_f32_16x16x32_bf16 v[102:105], v[146:149], v[196:199], v[102:105]
	v_mfma_f32_16x16x32_bf16 v[98:101], v[172:175], v[196:199], v[98:101]
	v_mfma_f32_16x16x32_bf16 v[86:89], v[146:149], v[204:207], v[86:89]
	v_mfma_f32_16x16x32_bf16 v[82:85], v[172:175], v[204:207], v[82:85]
	v_mfma_f32_16x16x32_bf16 v[134:137], v[150:153], v[184:187], v[134:137]
	v_mfma_f32_16x16x32_bf16 v[130:133], v[176:179], v[184:187], v[130:133]
	v_mfma_f32_16x16x32_bf16 v[118:121], v[150:153], v[192:195], v[118:121]
	v_mfma_f32_16x16x32_bf16 v[114:117], v[176:179], v[192:195], v[114:117]
	v_mfma_f32_16x16x32_bf16 v[102:105], v[150:153], v[200:203], v[102:105]
	v_mfma_f32_16x16x32_bf16 v[98:101], v[176:179], v[200:203], v[98:101]
	v_mfma_f32_16x16x32_bf16 v[86:89], v[150:153], v[208:211], v[86:89]
	v_mfma_f32_16x16x32_bf16 v[82:85], v[176:179], v[208:211], v[82:85]
	s_setprio 0
	s_barrier
; #define PG8_STAGE(bufoff, gbase, voff) do { _Pragma("unroll") for (int _i = 0; _i < 2; ++_i) \
;         __builtin_amdgcn_global_load_lds((const unsigned*)((const char*)(gbase) + (voff)[_i]), (PG8_LAS unsigned*)(lds + (bufoff) + ldsw + _i * 8192), 16, 0, 0); } while (0)
; #define PG8_LDA(dst, b, h) do { _Pragma("unroll") for (int m = 0; m < 4; ++m) _Pragma("unroll") for (int k = 0; k < 2; ++k) dst[m][k] = *(const PG8_LAS bf16x8*)(lds + PG8_SA(b, h) + aoff + m * 2048 + k * 1024); } while (0)
; #define PG8_LDB(dst, b, h) do { _Pragma("unroll") for (int n = 0; n < 2; ++n) _Pragma("unroll") for (int k = 0; k < 2; ++k) dst[n][k] = *(const PG8_LAS bf16x8*)(lds + PG8_SB(b, h) + boff + n * 2048 + k * 1024); } while (0)
; #define PG8_MMA(ai, bj, At, Bt) do { __builtin_amdgcn_s_setprio(1); _Pragma("unroll") for (int m = 0; m < 4; ++m) _Pragma("unroll") for (int n = 0; n < 2; ++n) _Pragma("unroll") for (int k = 0; k < 2; ++k) \
;         acc[ai][bj][m][n] = __builtin_amdgcn_mfma_f32_16x16x32_bf16(Bt[n][k], At[m][k], acc[ai][bj][m][n], 0, 0, 0); __builtin_amdgcn_s_setprio(0); } while (0)
; #define PG8_WAIT_V(n) asm volatile("s_waitcnt vmcnt(" #n ")" ::: "memory")
; #define PG8_WAIT_L(n) asm volatile("s_waitcnt lgkmcnt(" #n ")" ::: "memory")
; #define PG8_BAR __builtin_amdgcn_s_barrier()
; #define PG8_SCHED __builtin_amdgcn_sched_barrier(0)
; template <class Epi, class Sched, bool ALIGN_EPI = false, bool SP2 = false>
; __device__ __forceinline__ void gemm_phase(PG8_LAS unsigned char* lds, const Gemm g, const Sched& S, const Epi& E) {
;     ...
;             PG8_LDA(At, 0, 1); PG8_STAGE(PG8_SB(0, 0), b2, voffB); PG8_STAGE(PG8_SB(0, 1), b2 + hstep, voffB); PG8_STAGE(PG8_SA(0, 0), a2, voffA);
;             PG8_WAIT_V(8); PG8_WAIT_L(0); PG8_BAR; PG8_MMA(1, 0, At, B0); PG8_MMA(1, 1, At, B1); PG8_BAR; PG8_SCHED;
;             PG8_LDB(B0, 1, 0); PG8_LDB(B1, 1, 1); PG8_SCHED; PG8_LDA(At, 1, 0); PG8_STAGE(PG8_SA(0, 1), a2 + hstep, voffA);
;             PG8_WAIT_V(8); PG8_WAIT_L(0); PG8_BAR; PG8_MMA(0, 0, At, B0); PG8_MMA(0, 1, At, B1); PG8_BAR; PG8_SCHED;
	s_add_i32 s42, s68, s50
	v_lshl_add_u64 v[218:219], s[6:7], 0, v[156:157]
	s_mov_b32 m0, s42
	ds_read_b128 v[180:183], v216 offset:16384
	ds_read_b128 v[184:187], v216 offset:17408
	ds_read_b128 v[188:191], v216 offset:18432
	ds_read_b128 v[192:195], v216 offset:19456
	ds_read_b128 v[196:199], v216 offset:20480
	ds_read_b128 v[200:203], v216 offset:21504
	ds_read_b128 v[204:207], v216 offset:22528
	ds_read_b128 v[208:211], v216 offset:23552
	global_load_lds_dwordx4 v[218:219], off
	s_add_i32 m0, s42, 0x2000
	s_add_u32 s42, s6, 0x40000
	v_lshl_add_u64 v[222:223], s[6:7], 0, v[160:161]
	s_addc_u32 s43, s7, 0
	s_add_i32 s44, s69, s50
	global_load_lds_dwordx4 v[222:223], off
	v_lshl_add_u64 v[224:225], s[42:43], 0, v[156:157]
	s_mov_b32 m0, s44
	v_lshl_add_u64 v[226:227], s[36:37], 0, v[158:159]
	global_load_lds_dwordx4 v[224:225], off
	v_lshl_add_u64 v[224:225], s[42:43], 0, v[160:161]
	s_add_i32 m0, s44, 0x2000
	s_nop 0
	global_load_lds_dwordx4 v[224:225], off
	v_lshl_add_u64 v[224:225], s[36:37], 0, v[154:155]
	s_mov_b32 m0, s51
	s_nop 0
	global_load_lds_dwordx4 v[224:225], off
	s_mov_b32 m0, s52
	s_nop 0
	global_load_lds_dwordx4 v[226:227], off
	s_waitcnt vmcnt(8) lgkmcnt(0)
	s_barrier
	s_setprio 1
	v_mfma_f32_16x16x32_bf16 v[78:81], v[50:53], v[180:183], v[78:81]
	v_mfma_f32_16x16x32_bf16 v[74:77], v[66:69], v[180:183], v[74:77]
	v_mfma_f32_16x16x32_bf16 v[46:49], v[50:53], v[188:191], v[46:49]
	v_mfma_f32_16x16x32_bf16 v[42:45], v[66:69], v[188:191], v[42:45]
	v_mfma_f32_16x16x32_bf16 v[30:33], v[50:53], v[196:199], v[30:33]
	v_mfma_f32_16x16x32_bf16 v[26:29], v[66:69], v[196:199], v[26:29]
	v_mfma_f32_16x16x32_bf16 v[14:17], v[50:53], v[204:207], v[14:17]
	v_mfma_f32_16x16x32_bf16 v[10:13], v[66:69], v[204:207], v[10:13]
	v_mfma_f32_16x16x32_bf16 v[78:81], v[54:57], v[184:187], v[78:81]
	v_mfma_f32_16x16x32_bf16 v[74:77], v[70:73], v[184:187], v[74:77]
	v_mfma_f32_16x16x32_bf16 v[46:49], v[54:57], v[192:195], v[46:49]
	v_mfma_f32_16x16x32_bf16 v[42:45], v[70:73], v[192:195], v[42:45]
	v_mfma_f32_16x16x32_bf16 v[30:33], v[54:57], v[200:203], v[30:33]
	v_mfma_f32_16x16x32_bf16 v[26:29], v[70:73], v[200:203], v[26:29]
	v_mfma_f32_16x16x32_bf16 v[14:17], v[54:57], v[208:211], v[14:17]
	v_mfma_f32_16x16x32_bf16 v[10:13], v[70:73], v[208:211], v[10:13]
	v_mfma_f32_16x16x32_bf16 v[38:41], v[146:149], v[188:191], v[38:41]
	v_mfma_f32_16x16x32_bf16 v[34:37], v[172:175], v[188:191], v[34:37]
	v_mfma_f32_16x16x32_bf16 v[22:25], v[146:149], v[196:199], v[22:25]
	v_mfma_f32_16x16x32_bf16 v[18:21], v[172:175], v[196:199], v[18:21]
	v_mfma_f32_16x16x32_bf16 v[6:9], v[146:149], v[204:207], v[6:9]
	v_mfma_f32_16x16x32_bf16 v[2:5], v[172:175], v[204:207], v[2:5]
	v_mfma_f32_16x16x32_bf16 v[50:53], v[146:149], v[180:183], v[62:65]
	v_mfma_f32_16x16x32_bf16 v[54:57], v[172:175], v[180:183], v[58:61]
	v_mfma_f32_16x16x32_bf16 v[38:41], v[150:153], v[192:195], v[38:41]
	v_mfma_f32_16x16x32_bf16 v[34:37], v[176:179], v[192:195], v[34:37]
	v_mfma_f32_16x16x32_bf16 v[22:25], v[150:153], v[200:203], v[22:25]
	v_mfma_f32_16x16x32_bf16 v[18:21], v[176:179], v[200:203], v[18:21]
	v_mfma_f32_16x16x32_bf16 v[6:9], v[150:153], v[208:211], v[6:9]
	v_mfma_f32_16x16x32_bf16 v[2:5], v[176:179], v[208:211], v[2:5]
	v_mfma_f32_16x16x32_bf16 v[50:53], v[150:153], v[184:187], v[50:53]
	v_mfma_f32_16x16x32_bf16 v[54:57], v[176:179], v[184:187], v[54:57]
	s_setprio 0
	s_barrier
.Lpz4_mid:
	s_add_i32 s42, 0, 0x18000
	s_add_i32 s43, 0, 0x1c000
	v_add_u32_e32 v70, s42, v213
	v_add_u32_e32 v162, s43, v213
	ds_read_b128 v[58:61], v70
	ds_read_b128 v[62:65], v70 offset:1024
	ds_read_b128 v[66:69], v70 offset:2048
	ds_read_b128 v[70:73], v70 offset:3072
	ds_read_b128 v[146:149], v162
	ds_read_b128 v[150:153], v162 offset:1024
	ds_read_b128 v[172:175], v162 offset:2048
	ds_read_b128 v[176:179], v162 offset:3072
	s_add_u32 s36, s36, 0x40000
	s_addc_u32 s37, s37, 0
	s_mov_b32 m0, s53
	v_lshl_add_u64 v[228:229], s[36:37], 0, v[154:155]
	ds_read_b128 v[180:183], v216 offset:32768
	ds_read_b128 v[184:187], v216 offset:33792
	ds_read_b128 v[188:191], v216 offset:34816
	ds_read_b128 v[192:195], v216 offset:35840
	ds_read_b128 v[196:199], v216 offset:36864
	ds_read_b128 v[200:203], v216 offset:37888
	ds_read_b128 v[204:207], v216 offset:38912
	ds_read_b128 v[208:211], v216 offset:39936
	global_load_lds_dwordx4 v[228:229], off
	v_lshl_add_u64 v[228:229], s[36:37], 0, v[158:159]
	s_mov_b32 m0, s54
	s_nop 0
	global_load_lds_dwordx4 v[228:229], off
	s_waitcnt vmcnt(8) lgkmcnt(0)
	s_barrier
; #define PG8_STAGE(bufoff, gbase, voff) do { _Pragma("unroll") for (int _i = 0; _i < 2; ++_i) \
;         __builtin_amdgcn_global_load_lds((const unsigned*)((const char*)(gbase) + (voff)[_i]), (PG8_LAS unsigned*)(lds + (bufoff) + ldsw + _i * 8192), 16, 0, 0); } while (0)
; #define PG8_LDA(dst, b, h) do { _Pragma("unroll") for (int m = 0; m < 4; ++m) _Pragma("unroll") for (int k = 0; k < 2; ++k) dst[m][k] = *(const PG8_LAS bf16x8*)(lds + PG8_SA(b, h) + aoff + m * 2048 + k * 1024); } while (0)
; #define PG8_MMA(ai, bj, At, Bt) do { __builtin_amdgcn_s_setprio(1); _Pragma("unroll") for (int m = 0; m < 4; ++m) _Pragma("unroll") for (int n = 0; n < 2; ++n) _Pragma("unroll") for (int k = 0; k < 2; ++k) \
;         acc[ai][bj][m][n] = __builtin_amdgcn_mfma_f32_16x16x32_bf16(Bt[n][k], At[m][k], acc[ai][bj][m][n], 0, 0, 0); __builtin_amdgcn_s_setprio(0); } while (0)
; #define PG8_WAIT_V(n) asm volatile("s_waitcnt vmcnt(" #n ")" ::: "memory")
; #define PG8_WAIT_L(n) asm volatile("s_waitcnt lgkmcnt(" #n ")" ::: "memory")
; #define PG8_BAR __builtin_amdgcn_s_barrier()
; #define PG8_SCHED __builtin_amdgcn_sched_barrier(0)
; template <class Epi, class Sched, bool ALIGN_EPI = false, bool SP2 = false>
; __device__ __forceinline__ void gemm_phase(PG8_LAS unsigned char* lds, const Gemm g, const Sched& S, const Epi& E) {
;     ...
;             PG8_WAIT_V(8); PG8_WAIT_L(0); PG8_BAR; PG8_MMA(0, 0, At, B0); PG8_MMA(0, 1, At, B1); PG8_BAR; PG8_SCHED;
;             PG8_LDA(At, 1, 1); PG8_STAGE(PG8_SB(1, 0), b3, voffB); PG8_STAGE(PG8_SB(1, 1), b3 + hstep, voffB); PG8_STAGE(PG8_SA(1, 0), a3, voffA);
;             PG8_WAIT_V(8); PG8_WAIT_L(0); PG8_BAR; PG8_MMA(1, 0, At, B0); PG8_MMA(1, 1, At, B1); PG8_BAR; PG8_SCHED;
	s_setprio 1
	v_mfma_f32_16x16x32_bf16 v[142:145], v[58:61], v[180:183], v[142:145]
	v_mfma_f32_16x16x32_bf16 v[138:141], v[66:69], v[180:183], v[138:141]
	v_mfma_f32_16x16x32_bf16 v[126:129], v[58:61], v[188:191], v[126:129]
	v_mfma_f32_16x16x32_bf16 v[122:125], v[66:69], v[188:191], v[122:125]
	v_mfma_f32_16x16x32_bf16 v[110:113], v[58:61], v[196:199], v[110:113]
	v_mfma_f32_16x16x32_bf16 v[106:109], v[66:69], v[196:199], v[106:109]
	v_mfma_f32_16x16x32_bf16 v[94:97], v[58:61], v[204:207], v[94:97]
	v_mfma_f32_16x16x32_bf16 v[90:93], v[66:69], v[204:207], v[90:93]
	v_mfma_f32_16x16x32_bf16 v[142:145], v[62:65], v[184:187], v[142:145]
	v_mfma_f32_16x16x32_bf16 v[138:141], v[70:73], v[184:187], v[138:141]
	v_mfma_f32_16x16x32_bf16 v[126:129], v[62:65], v[192:195], v[126:129]
	v_mfma_f32_16x16x32_bf16 v[122:125], v[70:73], v[192:195], v[122:125]
	v_mfma_f32_16x16x32_bf16 v[110:113], v[62:65], v[200:203], v[110:113]
	v_mfma_f32_16x16x32_bf16 v[106:109], v[70:73], v[200:203], v[106:109]
	v_mfma_f32_16x16x32_bf16 v[94:97], v[62:65], v[208:211], v[94:97]
	v_mfma_f32_16x16x32_bf16 v[90:93], v[70:73], v[208:211], v[90:93]
	v_mfma_f32_16x16x32_bf16 v[134:137], v[146:149], v[180:183], v[134:137]
	v_mfma_f32_16x16x32_bf16 v[130:133], v[172:175], v[180:183], v[130:133]
	v_mfma_f32_16x16x32_bf16 v[118:121], v[146:149], v[188:191], v[118:121]
	v_mfma_f32_16x16x32_bf16 v[114:117], v[172:175], v[188:191], v[114:117]
	v_mfma_f32_16x16x32_bf16 v[102:105], v[146:149], v[196:199], v[102:105]
	v_mfma_f32_16x16x32_bf16 v[98:101], v[172:175], v[196:199], v[98:101]
	v_mfma_f32_16x16x32_bf16 v[86:89], v[146:149], v[204:207], v[86:89]
	v_mfma_f32_16x16x32_bf16 v[82:85], v[172:175], v[204:207], v[82:85]
	v_mfma_f32_16x16x32_bf16 v[134:137], v[150:153], v[184:187], v[134:137]
	v_mfma_f32_16x16x32_bf16 v[130:133], v[176:179], v[184:187], v[130:133]
	v_mfma_f32_16x16x32_bf16 v[118:121], v[150:153], v[192:195], v[118:121]
	v_mfma_f32_16x16x32_bf16 v[114:117], v[176:179], v[192:195], v[114:117]
	v_mfma_f32_16x16x32_bf16 v[102:105], v[150:153], v[200:203], v[102:105]
	v_mfma_f32_16x16x32_bf16 v[98:101], v[176:179], v[200:203], v[98:101]
	v_mfma_f32_16x16x32_bf16 v[86:89], v[150:153], v[208:211], v[86:89]
	v_mfma_f32_16x16x32_bf16 v[82:85], v[176:179], v[208:211], v[82:85]
	s_setprio 0
	s_barrier
	s_add_i32 s36, s42, s50
	v_lshl_add_u64 v[218:219], v[218:219], 0, s[20:21]
	s_mov_b32 m0, s36
	ds_read_b128 v[180:183], v216 offset:49152
	ds_read_b128 v[184:187], v216 offset:50176
	ds_read_b128 v[188:191], v216 offset:51200
	ds_read_b128 v[192:195], v216 offset:52224
	ds_read_b128 v[196:199], v216 offset:53248
	ds_read_b128 v[200:203], v216 offset:54272
	ds_read_b128 v[204:207], v216 offset:55296
	ds_read_b128 v[208:211], v216 offset:56320
	global_load_lds_dwordx4 v[218:219], off
	s_add_i32 m0, s36, 0x2000
	s_add_u32 s6, s6, 0x40080
	v_lshl_add_u64 v[218:219], v[222:223], 0, s[20:21]
	s_addc_u32 s7, s7, 0
	s_add_i32 s36, s43, s50
	global_load_lds_dwordx4 v[218:219], off
	v_lshl_add_u64 v[218:219], s[6:7], 0, v[156:157]
	s_mov_b32 m0, s36
	s_nop 0
	global_load_lds_dwordx4 v[218:219], off
	v_lshl_add_u64 v[218:219], s[6:7], 0, v[160:161]
	s_add_i32 m0, s36, 0x2000
	s_nop 0
	global_load_lds_dwordx4 v[218:219], off
	v_lshl_add_u64 v[218:219], v[224:225], 0, s[20:21]
	s_mov_b32 m0, s63
	s_nop 0
	global_load_lds_dwordx4 v[218:219], off
	v_lshl_add_u64 v[218:219], v[226:227], 0, s[20:21]
	s_mov_b32 m0, s64
	s_nop 0
	global_load_lds_dwordx4 v[218:219], off
	s_waitcnt vmcnt(8) lgkmcnt(0)
	s_barrier
	s_setprio 1
	v_mfma_f32_16x16x32_bf16 v[78:81], v[58:61], v[180:183], v[78:81]
	v_mfma_f32_16x16x32_bf16 v[74:77], v[66:69], v[180:183], v[74:77]
	v_mfma_f32_16x16x32_bf16 v[46:49], v[58:61], v[188:191], v[46:49]
	v_mfma_f32_16x16x32_bf16 v[42:45], v[66:69], v[188:191], v[42:45]
	v_mfma_f32_16x16x32_bf16 v[30:33], v[58:61], v[196:199], v[30:33]
	v_mfma_f32_16x16x32_bf16 v[26:29], v[66:69], v[196:199], v[26:29]
	v_mfma_f32_16x16x32_bf16 v[14:17], v[58:61], v[204:207], v[14:17]
	v_mfma_f32_16x16x32_bf16 v[10:13], v[66:69], v[204:207], v[10:13]
	v_mfma_f32_16x16x32_bf16 v[78:81], v[62:65], v[184:187], v[78:81]
	v_mfma_f32_16x16x32_bf16 v[74:77], v[70:73], v[184:187], v[74:77]
	v_mfma_f32_16x16x32_bf16 v[46:49], v[62:65], v[192:195], v[46:49]
	v_mfma_f32_16x16x32_bf16 v[42:45], v[70:73], v[192:195], v[42:45]
	v_mfma_f32_16x16x32_bf16 v[30:33], v[62:65], v[200:203], v[30:33]
	v_mfma_f32_16x16x32_bf16 v[26:29], v[70:73], v[200:203], v[26:29]
	v_mfma_f32_16x16x32_bf16 v[14:17], v[62:65], v[208:211], v[14:17]
	v_mfma_f32_16x16x32_bf16 v[10:13], v[70:73], v[208:211], v[10:13]
	v_mfma_f32_16x16x32_bf16 v[50:53], v[146:149], v[180:183], v[50:53]
	v_mfma_f32_16x16x32_bf16 v[62:65], v[150:153], v[184:187], v[50:53]
	v_mfma_f32_16x16x32_bf16 v[50:53], v[172:175], v[180:183], v[54:57]
	v_mfma_f32_16x16x32_bf16 v[38:41], v[146:149], v[188:191], v[38:41]
	v_mfma_f32_16x16x32_bf16 v[34:37], v[172:175], v[188:191], v[34:37]
	v_mfma_f32_16x16x32_bf16 v[22:25], v[146:149], v[196:199], v[22:25]
	v_mfma_f32_16x16x32_bf16 v[18:21], v[172:175], v[196:199], v[18:21]
	v_mfma_f32_16x16x32_bf16 v[6:9], v[146:149], v[204:207], v[6:9]
	v_mfma_f32_16x16x32_bf16 v[2:5], v[172:175], v[204:207], v[2:5]
	v_mfma_f32_16x16x32_bf16 v[58:61], v[176:179], v[184:187], v[50:53]
	v_mfma_f32_16x16x32_bf16 v[38:41], v[150:153], v[192:195], v[38:41]
	v_mfma_f32_16x16x32_bf16 v[34:37], v[176:179], v[192:195], v[34:37]
	v_mfma_f32_16x16x32_bf16 v[22:25], v[150:153], v[200:203], v[22:25]
	v_mfma_f32_16x16x32_bf16 v[18:21], v[176:179], v[200:203], v[18:21]
	v_mfma_f32_16x16x32_bf16 v[6:9], v[150:153], v[208:211], v[6:9]
	v_mfma_f32_16x16x32_bf16 v[2:5], v[176:179], v[208:211], v[2:5]
	s_setprio 0
	s_barrier
	s_add_i32 s41, s41, 2
	s_add_u32 s4, s4, 0x100
	s_addc_u32 s5, s5, 0
	s_add_u32 s39, s39, 0x100
	s_addc_u32 s40, s40, 0
	s_cmp_gt_u32 s41, 13
	s_cbranch_scc0 .LBB0_838
	s_and_b64 vcc, exec, s[22:23]
	s_cbranch_vccz .LBB0_841
	s_barrier

;     __host__ __device__ bool next(int i, Unit& u) const { if (!b.next(i >> 1, u)) return false; u.sel = i & 1; return true; }
; #define PG8_STAGE(bufoff, gbase, voff) do { _Pragma("unroll") for (int _i = 0; _i < 2; ++_i) \
;         __builtin_amdgcn_global_load_lds((const unsigned*)((const char*)(gbase) + (voff)[_i]), (PG8_LAS unsigned*)(lds + (bufoff) + ldsw + _i * 8192), 16, 0, 0); } while (0)
; #define PG8_LDA(dst, b, h) do { _Pragma("unroll") for (int m = 0; m < 4; ++m) _Pragma("unroll") for (int k = 0; k < 2; ++k) dst[m][k] = *(const PG8_LAS bf16x8*)(lds + PG8_SA(b, h) + aoff + m * 2048 + k * 1024); } while (0)
; #define PG8_WAIT_V(n) asm volatile("s_waitcnt vmcnt(" #n ")" ::: "memory")
;     __host__ __device__ bool next(int i, Unit& u) const {
;         const long L = (long)i * G + c; if (L >= nwg) return false;
;         int wgid = (int)L; { const int q = nwg / NXCD, r = nwg % NXCD, xcd = wgid % NXCD, off = wgid / NXCD; wgid = (xcd < r ? xcd * (q + 1) : r * (q + 1) + (xcd - r) * q) + off; }
;         const int nig = WGM * nN, gid = wgid / nig, fm = gid * WGM, gsz = (nM - fm) < WGM ? (nM - fm) : WGM;
;         u.pm = fm + ((wgid % nig) % gsz); u.pn = (wgid % nig) / gsz; u.sel = 0; return true;
; template <class Epi, class Sched, bool ALIGN_EPI = false, bool SP2 = false>
; __device__ __forceinline__ void gemm_phase(PG8_LAS unsigned char* lds, const Gemm g, const Sched& S, const Epi& E) {
;     ...
;         const bool has_next = S.next(ui + 1, nxt);
;         const char* nA = has_next ? PG8_ABASE(nxt) : cA; const char* nB = has_next ? PG8_BBASE(nxt) : cB;
;         for (int t = 0; t < nt; t += 2) {
;             const bool last = (t == nt - 2);
;             const char* a1 = cA + (size_t)(t + 1) * kstepA;
;             const char* a2 = last ? nA : cA + (size_t)(t + 2) * kstepA; const char* b2 = last ? nB : cB + (size_t)(t + 2) * kstep;
;             const char* a3 = a2 + kstepA; const char* b3 = b2 + kstep;
;             if (last && has_next) S.a_ready(nxt);
;             if constexpr (SP2) {
;             PG8_LDB(B0, 0, 0); PG8_LDB(B1, 0, 1); PG8_SCHED; PG8_LDA(At, 0, 0); PG8_STAGE(PG8_SA(1, 1), a1 + hstep, voffA);
;             PG8_WAIT_V(8); PG8_WAIT_L(0); PG8_BAR; PG8_MMA(0, 0, At, B0); PG8_MMA(0, 1, At, B1); PG8_BAR; PG8_SCHED;
;             if constexpr (Epi::PREFETCH) { if (t == tpf) E.prefetch(cur, wid, lane); }
.LBB0_982:
	s_ashr_i32 s29, s28, 31
	s_lshl_b32 s34, s34, 8
	s_lshl_b64 s[36:37], s[28:29], 14
	s_ashr_i32 s29, s28, 5
	s_ashr_i32 s35, s34, 31
	s_add_u32 s36, s10, s36
	s_mul_hi_i32 s38, s29, 0x5800
	s_mulk_i32 s29, 0x5800
	s_addc_u32 s37, s69, s37
	s_add_u32 s29, s62, s29
	s_addc_u32 s42, s63, s38
	s_lshl_b64 s[38:39], s[34:35], 2
	s_add_u32 s38, s29, s38
	s_addc_u32 s39, s42, s39
	s_add_u32 s29, s40, 0x100
	v_lshl_add_u64 v[188:189], s[30:31], 0, v[180:181]
	v_lshl_add_u64 v[190:191], s[30:31], 0, v[182:183]
	s_addc_u32 s35, s41, 0
	s_mov_b32 s83, 0
	s_mov_b64 s[40:41], 0
	ds_read_b128 v[154:157], v195
	ds_read_b128 v[158:161], v195 offset:1024
	ds_read_b128 v[162:165], v195 offset:2048
	ds_read_b128 v[166:169], v195 offset:3072
	ds_read_b128 v[138:141], v196
	ds_read_b128 v[142:145], v196 offset:1024
	ds_read_b128 v[146:149], v196 offset:2048
	ds_read_b128 v[150:153], v196 offset:3072
	v_lshl_add_u64 v[98:99], v[188:189], 0, s[40:41]
	s_add_i32 m0, s54, 0xc000
	ds_read_b128 v[200:203], v197
	ds_read_b128 v[204:207], v197 offset:1024
	ds_read_b128 v[208:211], v197 offset:2048
	ds_read_b128 v[212:215], v197 offset:3072
	ds_read_b128 v[216:219], v197 offset:4096
	ds_read_b128 v[220:223], v197 offset:5120
	ds_read_b128 v[224:227], v197 offset:6144
	ds_read_b128 v[228:231], v197 offset:7168
	global_load_lds_dwordx4 v[98:99], off
	v_lshl_add_u64 v[98:99], v[190:191], 0, s[40:41]
	s_add_i32 m0, s54, 0xe000
	s_nop 0
	global_load_lds_dwordx4 v[98:99], off
	s_add_i32 s11, s11, 1
	s_mul_i32 s2, s11, s68
	s_mul_hi_u32 s3, s11, s33
	s_add_i32 s3, s3, s2
	s_mul_i32 s2, s11, s33
	s_add_u32 s24, s2, s87
	s_addc_u32 s25, s3, s52
	v_cmp_lt_i64_e64 s[2:3], s[24:25], v[184:185]
	s_ashr_i32 s20, s24, 31
	s_lshr_b32 s20, s20, 29
	s_add_i32 s20, s24, s20
	s_ashr_i32 s21, s20, 3
	s_and_b32 s20, s20, -8
	s_sub_i32 s20, s24, s20
	s_cmp_lt_i32 s20, 0
	s_cselect_b32 s22, s53, 0x160
	s_mul_i32 s20, s20, s22
	s_add_i32 s20, s20, s21
	s_mul_hi_i32 s21, s20, 0x2e8ba2e9
	s_lshr_b32 s22, s21, 31
	s_ashr_i32 s21, s21, 3
	s_add_i32 s21, s21, s22
	s_lshl_b32 s22, s21, 1
	s_mul_i32 s21, s21, 44
	s_sub_i32 s21, s20, s21
	s_lshr_b32 s20, s21, 1
	s_and_b32 s21, s21, 1
	s_add_i32 s22, s22, s21
	s_ashr_i32 s23, s22, 31
	s_lshl_b64 s[24:25], s[22:23], 19
	s_add_u32 s24, s47, s24
	s_addc_u32 s25, s48, s25
	s_and_b64 s[26:27], s[2:3], exec
	s_cselect_b32 s23, s25, s48
	s_cselect_b32 s81, s24, s47
	s_ashr_i32 s21, s20, 31
	s_lshl_b64 s[26:27], s[20:21], 19
	s_add_u32 s26, s49, s26
	s_addc_u32 s27, s50, s27
	s_and_b64 s[98:99], s[2:3], exec
	s_cselect_b32 s21, s27, s50
	s_cselect_b32 s82, s26, s49
	s_waitcnt vmcnt(8) lgkmcnt(0)
	s_barrier
	s_setprio 1
	v_mfma_f32_16x16x32_bf16 v[98:101], v[154:157], v[200:203], 0
	v_mfma_f32_16x16x32_bf16 v[106:109], v[162:165], v[200:203], 0
	v_mfma_f32_16x16x32_bf16 v[118:121], v[154:157], v[208:211], 0
	v_mfma_f32_16x16x32_bf16 v[114:117], v[162:165], v[208:211], 0
	v_mfma_f32_16x16x32_bf16 v[94:97], v[154:157], v[216:219], 0
	v_mfma_f32_16x16x32_bf16 v[90:93], v[162:165], v[216:219], 0
	v_mfma_f32_16x16x32_bf16 v[78:81], v[154:157], v[224:227], 0
	v_mfma_f32_16x16x32_bf16 v[74:77], v[162:165], v[224:227], 0
	v_mfma_f32_16x16x32_bf16 v[98:101], v[158:161], v[204:207], v[98:101]
	v_mfma_f32_16x16x32_bf16 v[106:109], v[166:169], v[204:207], v[106:109]
	v_mfma_f32_16x16x32_bf16 v[118:121], v[158:161], v[212:215], v[118:121]
	v_mfma_f32_16x16x32_bf16 v[114:117], v[166:169], v[212:215], v[114:117]
	v_mfma_f32_16x16x32_bf16 v[94:97], v[158:161], v[220:223], v[94:97]
	v_mfma_f32_16x16x32_bf16 v[90:93], v[166:169], v[220:223], v[90:93]
	v_mfma_f32_16x16x32_bf16 v[78:81], v[158:161], v[228:231], v[78:81]
	v_mfma_f32_16x16x32_bf16 v[74:77], v[166:169], v[228:231], v[74:77]
	v_mfma_f32_16x16x32_bf16 v[126:129], v[138:141], v[200:203], 0
	v_mfma_f32_16x16x32_bf16 v[122:125], v[146:149], v[200:203], 0
	v_mfma_f32_16x16x32_bf16 v[110:113], v[138:141], v[208:211], 0
	v_mfma_f32_16x16x32_bf16 v[102:105], v[146:149], v[208:211], 0
	v_mfma_f32_16x16x32_bf16 v[86:89], v[138:141], v[216:219], 0
	v_mfma_f32_16x16x32_bf16 v[82:85], v[146:149], v[216:219], 0
	v_mfma_f32_16x16x32_bf16 v[70:73], v[138:141], v[224:227], 0
	v_mfma_f32_16x16x32_bf16 v[66:69], v[146:149], v[224:227], 0
	v_mfma_f32_16x16x32_bf16 v[126:129], v[142:145], v[204:207], v[126:129]
	v_mfma_f32_16x16x32_bf16 v[122:125], v[150:153], v[204:207], v[122:125]
	v_mfma_f32_16x16x32_bf16 v[110:113], v[142:145], v[212:215], v[110:113]
	v_mfma_f32_16x16x32_bf16 v[102:105], v[150:153], v[212:215], v[102:105]
	v_mfma_f32_16x16x32_bf16 v[86:89], v[142:145], v[220:223], v[86:89]
	v_mfma_f32_16x16x32_bf16 v[82:85], v[150:153], v[220:223], v[82:85]
	v_mfma_f32_16x16x32_bf16 v[70:73], v[142:145], v[228:231], v[70:73]
	v_mfma_f32_16x16x32_bf16 v[66:69], v[150:153], v[228:231], v[66:69]
	s_setprio 0
	s_barrier
	s_cmp_lg_u32 s46, s83
	s_cbranch_scc1 .Lpz5_a
	v_mov_b32_e32 v178, v194
	s_add_i32 m0, s79, 0x20000
	v_lshl_add_u64 v[130:131], s[36:37], 0, v[178:179]
	global_load_lds_dwordx4 v178, s[36:37]
	v_lshl_add_u64 v[130:131], v[130:131], 0, s[18:19]
	s_add_i32 m0, s79, 0x20400
	s_andn2_b64 vcc, exec, s[14:15]
	global_load_lds_dwordx4 v[130:131], off
	s_cbranch_vccnz .Lpz5_a
	v_lshl_add_u64 v[130:131], s[38:39], 0, v[178:179]
	s_add_i32 m0, 0, 0x24000
	s_nop 0
	global_load_lds_dwordx4 v[130:131], off
	s_branch .Lpz5_a
; #define PG8_STAGE(bufoff, gbase, voff) do { _Pragma("unroll") for (int _i = 0; _i < 2; ++_i) \
;         __builtin_amdgcn_global_load_lds((const unsigned*)((const char*)(gbase) + (voff)[_i]), (PG8_LAS unsigned*)(lds + (bufoff) + ldsw + _i * 8192), 16, 0, 0); } while (0)
; #define PG8_LDA(dst, b, h) do { _Pragma("unroll") for (int m = 0; m < 4; ++m) _Pragma("unroll") for (int k = 0; k < 2; ++k) dst[m][k] = *(const PG8_LAS bf16x8*)(lds + PG8_SA(b, h) + aoff + m * 2048 + k * 1024); } while (0)
; #define PG8_LDB(dst, b, h) do { _Pragma("unroll") for (int n = 0; n < 2; ++n) _Pragma("unroll") for (int k = 0; k < 2; ++k) dst[n][k] = *(const PG8_LAS bf16x8*)(lds + PG8_SB(b, h) + boff + n * 2048 + k * 1024); } while (0)
; #define PG8_MMA(ai, bj, At, Bt) do { __builtin_amdgcn_s_setprio(1); _Pragma("unroll") for (int m = 0; m < 4; ++m) _Pragma("unroll") for (int n = 0; n < 2; ++n) _Pragma("unroll") for (int k = 0; k < 2; ++k) \
;         acc[ai][bj][m][n] = __builtin_amdgcn_mfma_f32_16x16x32_bf16(Bt[n][k], At[m][k], acc[ai][bj][m][n], 0, 0, 0); __builtin_amdgcn_s_setprio(0); } while (0)
; #define PG8_WAIT_V(n) asm volatile("s_waitcnt vmcnt(" #n ")" ::: "memory")
; template <class Epi, class Sched, bool ALIGN_EPI = false, bool SP2 = false>
; __device__ __forceinline__ void gemm_phase(PG8_LAS unsigned char* lds, const Gemm g, const Sched& S, const Epi& E) {
;     ...
;             const bool last = (t == nt - 2);
;             const char* a1 = cA + (size_t)(t + 1) * kstepA;
;             const char* a2 = last ? nA : cA + (size_t)(t + 2) * kstepA; const char* b2 = last ? nB : cB + (size_t)(t + 2) * kstep;
;             const char* a3 = a2 + kstepA; const char* b3 = b2 + kstep;
;             if (last && has_next) S.a_ready(nxt);
;             if constexpr (SP2) {
;             PG8_LDB(B0, 0, 0); PG8_LDB(B1, 0, 1); PG8_SCHED; PG8_LDA(At, 0, 0); PG8_STAGE(PG8_SA(1, 1), a1 + hstep, voffA);
;             PG8_WAIT_V(8); PG8_WAIT_L(0); PG8_BAR; PG8_MMA(0, 0, At, B0); PG8_MMA(0, 1, At, B1); PG8_BAR; PG8_SCHED;
;             if constexpr (Epi::PREFETCH) { if (t == tpf) E.prefetch(cur, wid, lane); }
;             PG8_LDA(At, 0, 1); PG8_STAGE(PG8_SB(0, 0), b2, voffB); PG8_STAGE(PG8_SB(0, 1), b2 + hstep, voffB); PG8_STAGE(PG8_SA(0, 0), a2, voffA);
;             PG8_WAIT_V(8); PG8_WAIT_L(0); PG8_BAR; PG8_MMA(1, 0, At, B0); PG8_MMA(1, 1, At, B1); PG8_BAR; PG8_SCHED;
.Lpz5_a:
	s_add_u32 s42, s30, s40
	s_addc_u32 s43, s31, s41
	s_add_u32 s42, s42, 0x100
	s_addc_u32 s43, s43, 0
	s_add_u32 s84, s29, s40
	s_addc_u32 s85, s35, s41
	s_cmpk_eq_i32 s40, 0x700
	s_cselect_b32 s45, s23, s43
	s_cselect_b32 s44, s81, s42
	s_cselect_b32 s43, s21, s85
	s_cselect_b32 s42, s82, s84
	s_mov_b32 m0, s55
	v_lshl_add_u64 v[232:233], s[42:43], 0, v[174:175]
	s_add_u32 s84, s42, 0x40000
	ds_read_b128 v[130:133], v197 offset:16384
	ds_read_b128 v[134:137], v197 offset:17408
	ds_read_b128 v[200:203], v197 offset:18432
	ds_read_b128 v[204:207], v197 offset:19456
	ds_read_b128 v[208:211], v197 offset:20480
	ds_read_b128 v[212:215], v197 offset:21504
	ds_read_b128 v[216:219], v197 offset:22528
	ds_read_b128 v[220:223], v197 offset:23552
	global_load_lds_dwordx4 v[232:233], off
	v_lshl_add_u64 v[234:235], s[42:43], 0, v[170:171]
	s_mov_b32 m0, s56
	s_addc_u32 s85, s43, 0
	global_load_lds_dwordx4 v[234:235], off
	v_lshl_add_u64 v[224:225], s[84:85], 0, v[174:175]
	s_mov_b32 m0, s57
	v_lshl_add_u64 v[236:237], s[44:45], 0, v[176:177]
	global_load_lds_dwordx4 v[224:225], off
	v_lshl_add_u64 v[224:225], s[84:85], 0, v[170:171]
	s_mov_b32 m0, s58
	v_lshl_add_u64 v[238:239], s[44:45], 0, v[172:173]
	global_load_lds_dwordx4 v[224:225], off
	s_mov_b32 m0, s54
	s_nop 0
	global_load_lds_dwordx4 v[236:237], off
	s_mov_b32 m0, s59
	s_nop 0
	global_load_lds_dwordx4 v[238:239], off
	s_waitcnt vmcnt(8) lgkmcnt(0)
	s_barrier
	s_setprio 1
	v_mfma_f32_16x16x32_bf16 v[62:65], v[154:157], v[130:133], 0
	v_mfma_f32_16x16x32_bf16 v[58:61], v[162:165], v[130:133], 0
	v_mfma_f32_16x16x32_bf16 v[46:49], v[154:157], v[200:203], 0
	v_mfma_f32_16x16x32_bf16 v[42:45], v[162:165], v[200:203], 0
	v_mfma_f32_16x16x32_bf16 v[30:33], v[154:157], v[208:211], 0
	v_mfma_f32_16x16x32_bf16 v[26:29], v[162:165], v[208:211], 0
	v_mfma_f32_16x16x32_bf16 v[14:17], v[154:157], v[216:219], 0
	v_mfma_f32_16x16x32_bf16 v[10:13], v[162:165], v[216:219], 0
	v_mfma_f32_16x16x32_bf16 v[62:65], v[158:161], v[134:137], v[62:65]
	v_mfma_f32_16x16x32_bf16 v[58:61], v[166:169], v[134:137], v[58:61]
	v_mfma_f32_16x16x32_bf16 v[46:49], v[158:161], v[204:207], v[46:49]
	v_mfma_f32_16x16x32_bf16 v[42:45], v[166:169], v[204:207], v[42:45]
	v_mfma_f32_16x16x32_bf16 v[30:33], v[158:161], v[212:215], v[30:33]
	v_mfma_f32_16x16x32_bf16 v[26:29], v[166:169], v[212:215], v[26:29]
	v_mfma_f32_16x16x32_bf16 v[14:17], v[158:161], v[220:223], v[14:17]
	v_mfma_f32_16x16x32_bf16 v[10:13], v[166:169], v[220:223], v[10:13]
	v_mfma_f32_16x16x32_bf16 v[54:57], v[138:141], v[130:133], 0
	v_mfma_f32_16x16x32_bf16 v[50:53], v[146:149], v[130:133], 0
	v_mfma_f32_16x16x32_bf16 v[38:41], v[138:141], v[200:203], 0
	v_mfma_f32_16x16x32_bf16 v[34:37], v[146:149], v[200:203], 0
	v_mfma_f32_16x16x32_bf16 v[22:25], v[138:141], v[208:211], 0
	v_mfma_f32_16x16x32_bf16 v[18:21], v[146:149], v[208:211], 0
	v_mfma_f32_16x16x32_bf16 v[6:9], v[138:141], v[216:219], 0
	v_mfma_f32_16x16x32_bf16 v[2:5], v[146:149], v[216:219], 0
	v_mfma_f32_16x16x32_bf16 v[54:57], v[142:145], v[134:137], v[54:57]
	v_mfma_f32_16x16x32_bf16 v[50:53], v[150:153], v[134:137], v[50:53]
	v_mfma_f32_16x16x32_bf16 v[38:41], v[142:145], v[204:207], v[38:41]
	v_mfma_f32_16x16x32_bf16 v[34:37], v[150:153], v[204:207], v[34:37]
	v_mfma_f32_16x16x32_bf16 v[22:25], v[142:145], v[212:215], v[22:25]
	v_mfma_f32_16x16x32_bf16 v[18:21], v[150:153], v[212:215], v[18:21]
	v_mfma_f32_16x16x32_bf16 v[6:9], v[142:145], v[220:223], v[6:9]
	v_mfma_f32_16x16x32_bf16 v[2:5], v[150:153], v[220:223], v[2:5]
	s_setprio 0
	s_barrier
	s_branch .Lpz5_mid
.LBB0_985:
	s_add_u32 s42, s30, s40
	s_addc_u32 s43, s31, s41
	s_add_u32 s42, s42, 0x100
	s_addc_u32 s43, s43, 0
	s_add_u32 s84, s29, s40
	s_addc_u32 s85, s35, s41
	s_cmpk_eq_i32 s40, 0x700
	s_cselect_b32 s45, s23, s43
	s_cselect_b32 s44, s81, s42
	s_cselect_b32 s43, s21, s85
	s_cselect_b32 s42, s82, s84
	s_mov_b32 m0, s55
	v_lshl_add_u64 v[232:233], s[42:43], 0, v[174:175]
	s_add_u32 s84, s42, 0x40000
	ds_read_b128 v[130:133], v197 offset:16384
	ds_read_b128 v[134:137], v197 offset:17408
	ds_read_b128 v[200:203], v197 offset:18432
	ds_read_b128 v[204:207], v197 offset:19456
	ds_read_b128 v[208:211], v197 offset:20480
	ds_read_b128 v[212:215], v197 offset:21504
	ds_read_b128 v[216:219], v197 offset:22528
	ds_read_b128 v[220:223], v197 offset:23552
	global_load_lds_dwordx4 v[232:233], off
	v_lshl_add_u64 v[234:235], s[42:43], 0, v[170:171]
	s_mov_b32 m0, s56
	s_addc_u32 s85, s43, 0
	global_load_lds_dwordx4 v[234:235], off
	v_lshl_add_u64 v[224:225], s[84:85], 0, v[174:175]
	s_mov_b32 m0, s57
	v_lshl_add_u64 v[236:237], s[44:45], 0, v[176:177]
	global_load_lds_dwordx4 v[224:225], off
	v_lshl_add_u64 v[224:225], s[84:85], 0, v[170:171]
	s_mov_b32 m0, s58
	v_lshl_add_u64 v[238:239], s[44:45], 0, v[172:173]
	global_load_lds_dwordx4 v[224:225], off
	s_mov_b32 m0, s54
	s_nop 0
	global_load_lds_dwordx4 v[236:237], off
	s_mov_b32 m0, s59
	s_nop 0
	global_load_lds_dwordx4 v[238:239], off
	s_waitcnt vmcnt(8) lgkmcnt(0)
	s_barrier
; #define PG8_STAGE(bufoff, gbase, voff) do { _Pragma("unroll") for (int _i = 0; _i < 2; ++_i) \
;         __builtin_amdgcn_global_load_lds((const unsigned*)((const char*)(gbase) + (voff)[_i]), (PG8_LAS unsigned*)(lds + (bufoff) + ldsw + _i * 8192), 16, 0, 0); } while (0)
; #define PG8_LDA(dst, b, h) do { _Pragma("unroll") for (int m = 0; m < 4; ++m) _Pragma("unroll") for (int k = 0; k < 2; ++k) dst[m][k] = *(const PG8_LAS bf16x8*)(lds + PG8_SA(b, h) + aoff + m * 2048 + k * 1024); } while (0)
; #define PG8_LDB(dst, b, h) do { _Pragma("unroll") for (int n = 0; n < 2; ++n) _Pragma("unroll") for (int k = 0; k < 2; ++k) dst[n][k] = *(const PG8_LAS bf16x8*)(lds + PG8_SB(b, h) + boff + n * 2048 + k * 1024); } while (0)
; #define PG8_MMA(ai, bj, At, Bt) do { __builtin_amdgcn_s_setprio(1); _Pragma("unroll") for (int m = 0; m < 4; ++m) _Pragma("unroll") for (int n = 0; n < 2; ++n) _Pragma("unroll") for (int k = 0; k < 2; ++k) \
;         acc[ai][bj][m][n] = __builtin_amdgcn_mfma_f32_16x16x32_bf16(Bt[n][k], At[m][k], acc[ai][bj][m][n], 0, 0, 0); __builtin_amdgcn_s_setprio(0); } while (0)
; #define PG8_WAIT_V(n) asm volatile("s_waitcnt vmcnt(" #n ")" ::: "memory")
; #define PG8_WAIT_L(n) asm volatile("s_waitcnt lgkmcnt(" #n ")" ::: "memory")
; #define PG8_BAR __builtin_amdgcn_s_barrier()
; #define PG8_SCHED __builtin_amdgcn_sched_barrier(0)
; template <class Epi, class Sched, bool ALIGN_EPI = false, bool SP2 = false>
; __device__ __forceinline__ void gemm_phase(PG8_LAS unsigned char* lds, const Gemm g, const Sched& S, const Epi& E) {
;     ...
;             PG8_WAIT_V(8); PG8_WAIT_L(0); PG8_BAR; PG8_MMA(1, 0, At, B0); PG8_MMA(1, 1, At, B1); PG8_BAR; PG8_SCHED;
;             PG8_LDB(B0, 1, 0); PG8_LDB(B1, 1, 1); PG8_SCHED; PG8_LDA(At, 1, 0); PG8_STAGE(PG8_SA(0, 1), a2 + hstep, voffA);
;             PG8_WAIT_V(8); PG8_WAIT_L(0); PG8_BAR; PG8_MMA(0, 0, At, B0); PG8_MMA(0, 1, At, B1); PG8_BAR; PG8_SCHED;
	s_setprio 1
	v_mfma_f32_16x16x32_bf16 v[62:65], v[154:157], v[130:133], v[62:65]
	v_mfma_f32_16x16x32_bf16 v[58:61], v[162:165], v[130:133], v[58:61]
	v_mfma_f32_16x16x32_bf16 v[46:49], v[154:157], v[200:203], v[46:49]
	v_mfma_f32_16x16x32_bf16 v[42:45], v[162:165], v[200:203], v[42:45]
	v_mfma_f32_16x16x32_bf16 v[30:33], v[154:157], v[208:211], v[30:33]
	v_mfma_f32_16x16x32_bf16 v[26:29], v[162:165], v[208:211], v[26:29]
	v_mfma_f32_16x16x32_bf16 v[14:17], v[154:157], v[216:219], v[14:17]
	v_mfma_f32_16x16x32_bf16 v[10:13], v[162:165], v[216:219], v[10:13]
	v_mfma_f32_16x16x32_bf16 v[62:65], v[158:161], v[134:137], v[62:65]
	v_mfma_f32_16x16x32_bf16 v[58:61], v[166:169], v[134:137], v[58:61]
	v_mfma_f32_16x16x32_bf16 v[46:49], v[158:161], v[204:207], v[46:49]
	v_mfma_f32_16x16x32_bf16 v[42:45], v[166:169], v[204:207], v[42:45]
	v_mfma_f32_16x16x32_bf16 v[30:33], v[158:161], v[212:215], v[30:33]
	v_mfma_f32_16x16x32_bf16 v[26:29], v[166:169], v[212:215], v[26:29]
	v_mfma_f32_16x16x32_bf16 v[14:17], v[158:161], v[220:223], v[14:17]
	v_mfma_f32_16x16x32_bf16 v[10:13], v[166:169], v[220:223], v[10:13]
	v_mfma_f32_16x16x32_bf16 v[54:57], v[138:141], v[130:133], v[54:57]
	v_mfma_f32_16x16x32_bf16 v[50:53], v[146:149], v[130:133], v[50:53]
	v_mfma_f32_16x16x32_bf16 v[38:41], v[138:141], v[200:203], v[38:41]
	v_mfma_f32_16x16x32_bf16 v[34:37], v[146:149], v[200:203], v[34:37]
	v_mfma_f32_16x16x32_bf16 v[22:25], v[138:141], v[208:211], v[22:25]
	v_mfma_f32_16x16x32_bf16 v[18:21], v[146:149], v[208:211], v[18:21]
	v_mfma_f32_16x16x32_bf16 v[6:9], v[138:141], v[216:219], v[6:9]
	v_mfma_f32_16x16x32_bf16 v[2:5], v[146:149], v[216:219], v[2:5]
	v_mfma_f32_16x16x32_bf16 v[54:57], v[142:145], v[134:137], v[54:57]
	v_mfma_f32_16x16x32_bf16 v[50:53], v[150:153], v[134:137], v[50:53]
	v_mfma_f32_16x16x32_bf16 v[38:41], v[142:145], v[204:207], v[38:41]
	v_mfma_f32_16x16x32_bf16 v[34:37], v[150:153], v[204:207], v[34:37]
	v_mfma_f32_16x16x32_bf16 v[22:25], v[142:145], v[212:215], v[22:25]
	v_mfma_f32_16x16x32_bf16 v[18:21], v[150:153], v[212:215], v[18:21]
	v_mfma_f32_16x16x32_bf16 v[6:9], v[142:145], v[220:223], v[6:9]
	v_mfma_f32_16x16x32_bf16 v[2:5], v[150:153], v[220:223], v[2:5]
	s_setprio 0
	s_barrier
.Lpz5_mid:
	s_add_i32 s84, 0, 0x18000
	v_add_u32_e32 v130, s84, v193
	s_add_i32 s85, 0, 0x1c000
	ds_read_b128 v[138:141], v130
	ds_read_b128 v[142:145], v130 offset:1024
	ds_read_b128 v[146:149], v130 offset:2048
	ds_read_b128 v[150:153], v130 offset:3072
	v_add_u32_e32 v130, s85, v193
	ds_read_b128 v[154:157], v130
	ds_read_b128 v[158:161], v130 offset:1024
	ds_read_b128 v[162:165], v130 offset:2048
	ds_read_b128 v[166:169], v130 offset:3072
	s_add_u32 s44, s44, 0x40000
	s_addc_u32 s45, s45, 0
	s_mov_b32 m0, s60
	v_lshl_add_u64 v[130:131], s[44:45], 0, v[176:177]
	ds_read_b128 v[200:203], v197 offset:32768
	ds_read_b128 v[204:207], v197 offset:33792
	ds_read_b128 v[208:211], v197 offset:34816
	ds_read_b128 v[212:215], v197 offset:35840
	ds_read_b128 v[216:219], v197 offset:36864
	ds_read_b128 v[220:223], v197 offset:37888
	ds_read_b128 v[224:227], v197 offset:38912
	ds_read_b128 v[228:231], v197 offset:39936
	global_load_lds_dwordx4 v[130:131], off
	v_lshl_add_u64 v[130:131], s[44:45], 0, v[172:173]
	s_mov_b32 m0, s61
	s_nop 0
	global_load_lds_dwordx4 v[130:131], off
	s_waitcnt vmcnt(8) lgkmcnt(0)
	s_barrier
	s_setprio 1
	v_mfma_f32_16x16x32_bf16 v[98:101], v[138:141], v[200:203], v[98:101]
	v_mfma_f32_16x16x32_bf16 v[134:137], v[142:145], v[204:207], v[98:101]
	v_mfma_f32_16x16x32_bf16 v[98:101], v[146:149], v[200:203], v[106:109]
	v_mfma_f32_16x16x32_bf16 v[130:133], v[150:153], v[204:207], v[98:101]
	v_mfma_f32_16x16x32_bf16 v[98:101], v[138:141], v[208:211], v[118:121]
	v_mfma_f32_16x16x32_bf16 v[118:121], v[142:145], v[212:215], v[98:101]
	v_mfma_f32_16x16x32_bf16 v[98:101], v[146:149], v[208:211], v[114:117]
	v_mfma_f32_16x16x32_bf16 v[94:97], v[138:141], v[216:219], v[94:97]
	v_mfma_f32_16x16x32_bf16 v[90:93], v[146:149], v[216:219], v[90:93]
	v_mfma_f32_16x16x32_bf16 v[78:81], v[138:141], v[224:227], v[78:81]
	v_mfma_f32_16x16x32_bf16 v[74:77], v[146:149], v[224:227], v[74:77]
	v_mfma_f32_16x16x32_bf16 v[114:117], v[150:153], v[212:215], v[98:101]
	v_mfma_f32_16x16x32_bf16 v[94:97], v[142:145], v[220:223], v[94:97]
	v_mfma_f32_16x16x32_bf16 v[90:93], v[150:153], v[220:223], v[90:93]
	v_mfma_f32_16x16x32_bf16 v[78:81], v[142:145], v[228:231], v[78:81]
	v_mfma_f32_16x16x32_bf16 v[74:77], v[150:153], v[228:231], v[74:77]
	v_mfma_f32_16x16x32_bf16 v[98:101], v[154:157], v[200:203], v[126:129]
	v_mfma_f32_16x16x32_bf16 v[126:129], v[158:161], v[204:207], v[98:101]
	v_mfma_f32_16x16x32_bf16 v[98:101], v[162:165], v[200:203], v[122:125]
	v_mfma_f32_16x16x32_bf16 v[122:125], v[166:169], v[204:207], v[98:101]
	v_mfma_f32_16x16x32_bf16 v[98:101], v[154:157], v[208:211], v[110:113]
	v_mfma_f32_16x16x32_bf16 v[110:113], v[158:161], v[212:215], v[98:101]
	v_mfma_f32_16x16x32_bf16 v[98:101], v[162:165], v[208:211], v[102:105]
	v_mfma_f32_16x16x32_bf16 v[86:89], v[154:157], v[216:219], v[86:89]
	v_mfma_f32_16x16x32_bf16 v[82:85], v[162:165], v[216:219], v[82:85]
	v_mfma_f32_16x16x32_bf16 v[70:73], v[154:157], v[224:227], v[70:73]
	v_mfma_f32_16x16x32_bf16 v[66:69], v[162:165], v[224:227], v[66:69]
	v_mfma_f32_16x16x32_bf16 v[102:105], v[166:169], v[212:215], v[98:101]
	v_mfma_f32_16x16x32_bf16 v[86:89], v[158:161], v[220:223], v[86:89]
	v_mfma_f32_16x16x32_bf16 v[82:85], v[166:169], v[220:223], v[82:85]
	v_mfma_f32_16x16x32_bf16 v[70:73], v[158:161], v[228:231], v[70:73]
	v_mfma_f32_16x16x32_bf16 v[66:69], v[166:169], v[228:231], v[66:69]
	s_setprio 0
	s_barrier
; #define PG8_STAGE(bufoff, gbase, voff) do { _Pragma("unroll") for (int _i = 0; _i < 2; ++_i) \
;         __builtin_amdgcn_global_load_lds((const unsigned*)((const char*)(gbase) + (voff)[_i]), (PG8_LAS unsigned*)(lds + (bufoff) + ldsw + _i * 8192), 16, 0, 0); } while (0)
; #define PG8_LDA(dst, b, h) do { _Pragma("unroll") for (int m = 0; m < 4; ++m) _Pragma("unroll") for (int k = 0; k < 2; ++k) dst[m][k] = *(const PG8_LAS bf16x8*)(lds + PG8_SA(b, h) + aoff + m * 2048 + k * 1024); } while (0)
; #define PG8_MMA(ai, bj, At, Bt) do { __builtin_amdgcn_s_setprio(1); _Pragma("unroll") for (int m = 0; m < 4; ++m) _Pragma("unroll") for (int n = 0; n < 2; ++n) _Pragma("unroll") for (int k = 0; k < 2; ++k) \
;         acc[ai][bj][m][n] = __builtin_amdgcn_mfma_f32_16x16x32_bf16(Bt[n][k], At[m][k], acc[ai][bj][m][n], 0, 0, 0); __builtin_amdgcn_s_setprio(0); } while (0)
; #define PG8_WAIT_V(n) asm volatile("s_waitcnt vmcnt(" #n ")" ::: "memory")
; #define PG8_WAIT_L(n) asm volatile("s_waitcnt lgkmcnt(" #n ")" ::: "memory")
; #define PG8_BAR __builtin_amdgcn_s_barrier()
; #define PG8_SCHED __builtin_amdgcn_sched_barrier(0)
; template <class Epi, class Sched, bool ALIGN_EPI = false, bool SP2 = false>
; __device__ __forceinline__ void gemm_phase(PG8_LAS unsigned char* lds, const Gemm g, const Sched& S, const Epi& E) {
;     ...
;         for (int t = 0; t < nt; t += 2) {
;     ...
;             PG8_LDA(At, 1, 1); PG8_STAGE(PG8_SB(1, 0), b3, voffB); PG8_STAGE(PG8_SB(1, 1), b3 + hstep, voffB); PG8_STAGE(PG8_SA(1, 0), a3, voffA);
;             PG8_WAIT_V(8); PG8_WAIT_L(0); PG8_BAR; PG8_MMA(1, 0, At, B0); PG8_MMA(1, 1, At, B1); PG8_BAR; PG8_SCHED;
	s_add_i32 s44, s84, s51
	v_lshl_add_u64 v[224:225], v[232:233], 0, s[8:9]
	s_mov_b32 m0, s44
	ds_read_b128 v[98:101], v197 offset:49152
	ds_read_b128 v[106:109], v197 offset:50176
	ds_read_b128 v[200:203], v197 offset:51200
	ds_read_b128 v[204:207], v197 offset:52224
	ds_read_b128 v[208:211], v197 offset:53248
	ds_read_b128 v[212:215], v197 offset:54272
	ds_read_b128 v[216:219], v197 offset:55296
	ds_read_b128 v[220:223], v197 offset:56320
	global_load_lds_dwordx4 v[224:225], off
	s_add_i32 m0, s44, 0x2000
	s_add_u32 s42, s42, 0x40080
	v_lshl_add_u64 v[224:225], v[234:235], 0, s[8:9]
	s_addc_u32 s43, s43, 0
	s_add_i32 s44, s85, s51
	global_load_lds_dwordx4 v[224:225], off
	v_lshl_add_u64 v[224:225], s[42:43], 0, v[174:175]
	s_mov_b32 m0, s44
	s_nop 0
	global_load_lds_dwordx4 v[224:225], off
	v_lshl_add_u64 v[224:225], s[42:43], 0, v[170:171]
	s_add_i32 m0, s44, 0x2000
	s_nop 0
	global_load_lds_dwordx4 v[224:225], off
	v_lshl_add_u64 v[224:225], v[236:237], 0, s[8:9]
	s_mov_b32 m0, s65
	s_nop 0
	global_load_lds_dwordx4 v[224:225], off
	v_lshl_add_u64 v[224:225], v[238:239], 0, s[8:9]
	s_mov_b32 m0, s66
	s_nop 0
	global_load_lds_dwordx4 v[224:225], off
	s_waitcnt vmcnt(8) lgkmcnt(0)
	s_barrier
	s_setprio 1
	v_mfma_f32_16x16x32_bf16 v[62:65], v[138:141], v[98:101], v[62:65]
	v_mfma_f32_16x16x32_bf16 v[58:61], v[146:149], v[98:101], v[58:61]
	v_mfma_f32_16x16x32_bf16 v[46:49], v[138:141], v[200:203], v[46:49]
	v_mfma_f32_16x16x32_bf16 v[42:45], v[146:149], v[200:203], v[42:45]
	v_mfma_f32_16x16x32_bf16 v[30:33], v[138:141], v[208:211], v[30:33]
	v_mfma_f32_16x16x32_bf16 v[26:29], v[146:149], v[208:211], v[26:29]
	v_mfma_f32_16x16x32_bf16 v[14:17], v[138:141], v[216:219], v[14:17]
	v_mfma_f32_16x16x32_bf16 v[10:13], v[146:149], v[216:219], v[10:13]
	v_mfma_f32_16x16x32_bf16 v[62:65], v[142:145], v[106:109], v[62:65]
	v_mfma_f32_16x16x32_bf16 v[58:61], v[150:153], v[106:109], v[58:61]
	v_mfma_f32_16x16x32_bf16 v[46:49], v[142:145], v[204:207], v[46:49]
	v_mfma_f32_16x16x32_bf16 v[42:45], v[150:153], v[204:207], v[42:45]
	v_mfma_f32_16x16x32_bf16 v[30:33], v[142:145], v[212:215], v[30:33]
	v_mfma_f32_16x16x32_bf16 v[26:29], v[150:153], v[212:215], v[26:29]
	v_mfma_f32_16x16x32_bf16 v[14:17], v[142:145], v[220:223], v[14:17]
	v_mfma_f32_16x16x32_bf16 v[10:13], v[150:153], v[220:223], v[10:13]
	v_mfma_f32_16x16x32_bf16 v[54:57], v[154:157], v[98:101], v[54:57]
	v_mfma_f32_16x16x32_bf16 v[50:53], v[162:165], v[98:101], v[50:53]
	v_mfma_f32_16x16x32_bf16 v[38:41], v[154:157], v[200:203], v[38:41]
	v_mfma_f32_16x16x32_bf16 v[34:37], v[162:165], v[200:203], v[34:37]
	v_mfma_f32_16x16x32_bf16 v[22:25], v[154:157], v[208:211], v[22:25]
	v_mfma_f32_16x16x32_bf16 v[18:21], v[162:165], v[208:211], v[18:21]
	v_mfma_f32_16x16x32_bf16 v[6:9], v[154:157], v[216:219], v[6:9]
	v_mfma_f32_16x16x32_bf16 v[2:5], v[162:165], v[216:219], v[2:5]
	v_mfma_f32_16x16x32_bf16 v[54:57], v[158:161], v[106:109], v[54:57]
	v_mfma_f32_16x16x32_bf16 v[50:53], v[166:169], v[106:109], v[50:53]
	v_mfma_f32_16x16x32_bf16 v[38:41], v[158:161], v[204:207], v[38:41]
	v_mfma_f32_16x16x32_bf16 v[34:37], v[166:169], v[204:207], v[34:37]
	v_mfma_f32_16x16x32_bf16 v[22:25], v[158:161], v[212:215], v[22:25]
	v_mfma_f32_16x16x32_bf16 v[18:21], v[166:169], v[212:215], v[18:21]
	v_mfma_f32_16x16x32_bf16 v[6:9], v[158:161], v[220:223], v[6:9]
	v_mfma_f32_16x16x32_bf16 v[2:5], v[166:169], v[220:223], v[2:5]
	s_setprio 0
	s_barrier
	s_add_i32 s42, s83, 2
	s_add_u32 s40, s40, 0x100
	s_addc_u32 s41, s41, 0
	s_cmp_gt_u32 s83, 13
	s_mov_b32 s83, s42
	s_cbranch_scc1 .LBB0_989
; #define PG8_STAGE(bufoff, gbase, voff) do { _Pragma("unroll") for (int _i = 0; _i < 2; ++_i) \
;         __builtin_amdgcn_global_load_lds((const unsigned*)((const char*)(gbase) + (voff)[_i]), (PG8_LAS unsigned*)(lds + (bufoff) + ldsw + _i * 8192), 16, 0, 0); } while (0)
; #define PG8_LDA(dst, b, h) do { _Pragma("unroll") for (int m = 0; m < 4; ++m) _Pragma("unroll") for (int k = 0; k < 2; ++k) dst[m][k] = *(const PG8_LAS bf16x8*)(lds + PG8_SA(b, h) + aoff + m * 2048 + k * 1024); } while (0)
; #define PG8_LDB(dst, b, h) do { _Pragma("unroll") for (int n = 0; n < 2; ++n) _Pragma("unroll") for (int k = 0; k < 2; ++k) dst[n][k] = *(const PG8_LAS bf16x8*)(lds + PG8_SB(b, h) + boff + n * 2048 + k * 1024); } while (0)
; #define PG8_MMA(ai, bj, At, Bt) do { __builtin_amdgcn_s_setprio(1); _Pragma("unroll") for (int m = 0; m < 4; ++m) _Pragma("unroll") for (int n = 0; n < 2; ++n) _Pragma("unroll") for (int k = 0; k < 2; ++k) \
;         acc[ai][bj][m][n] = __builtin_amdgcn_mfma_f32_16x16x32_bf16(Bt[n][k], At[m][k], acc[ai][bj][m][n], 0, 0, 0); __builtin_amdgcn_s_setprio(0); } while (0)
; #define PG8_WAIT_V(n) asm volatile("s_waitcnt vmcnt(" #n ")" ::: "memory")
; #define PG8_WAIT_L(n) asm volatile("s_waitcnt lgkmcnt(" #n ")" ::: "memory")
; #define PG8_BAR __builtin_amdgcn_s_barrier()
; #define PG8_SCHED __builtin_amdgcn_sched_barrier(0)
;     __device__ __forceinline__ void prefetch(const Unit& u, int wid, int lane) const { epi_prefetch(scr, ssq, bias + (size_t)(u.pm >> 5) * NGU + u.pn * BM, u, wid, lane); }
;     __device__ __forceinline__ void prefetch(const Unit& u, int wid, int lane) const { epi_prefetch(scr, ssq, bias + (size_t)(u.pm >> 5) * DIN + u.pn * BM, u, wid, lane); }
; template <class Epi, class Sched, bool ALIGN_EPI = false, bool SP2 = false>
; __device__ __forceinline__ void gemm_phase(PG8_LAS unsigned char* lds, const Gemm g, const Sched& S, const Epi& E) {
;     ...
;             PG8_LDB(B0, 0, 0); PG8_LDB(B1, 0, 1); PG8_SCHED; PG8_LDA(At, 0, 0); PG8_STAGE(PG8_SA(1, 1), a1 + hstep, voffA);
;             PG8_WAIT_V(8); PG8_WAIT_L(0); PG8_BAR; PG8_MMA(0, 0, At, B0); PG8_MMA(0, 1, At, B1); PG8_BAR; PG8_SCHED;
;             if constexpr (Epi::PREFETCH) { if (t == tpf) E.prefetch(cur, wid, lane); }
.LBB0_986:
	ds_read_b128 v[154:157], v195
	ds_read_b128 v[158:161], v195 offset:1024
	ds_read_b128 v[162:165], v195 offset:2048
	ds_read_b128 v[166:169], v195 offset:3072
	ds_read_b128 v[138:141], v196
	ds_read_b128 v[142:145], v196 offset:1024
	ds_read_b128 v[146:149], v196 offset:2048
	ds_read_b128 v[150:153], v196 offset:3072
	v_lshl_add_u64 v[98:99], v[188:189], 0, s[40:41]
	s_add_i32 m0, s54, 0xc000
	ds_read_b128 v[200:203], v197
	ds_read_b128 v[204:207], v197 offset:1024
	ds_read_b128 v[208:211], v197 offset:2048
	ds_read_b128 v[212:215], v197 offset:3072
	ds_read_b128 v[216:219], v197 offset:4096
	ds_read_b128 v[220:223], v197 offset:5120
	ds_read_b128 v[224:227], v197 offset:6144
	ds_read_b128 v[228:231], v197 offset:7168
	global_load_lds_dwordx4 v[98:99], off
	v_lshl_add_u64 v[98:99], v[190:191], 0, s[40:41]
	s_add_i32 m0, s54, 0xe000
	s_nop 0
	global_load_lds_dwordx4 v[98:99], off
	s_waitcnt vmcnt(8) lgkmcnt(0)
	s_barrier
	s_setprio 1
	v_mfma_f32_16x16x32_bf16 v[98:101], v[154:157], v[200:203], v[134:137]
	v_mfma_f32_16x16x32_bf16 v[106:109], v[162:165], v[200:203], v[130:133]
	v_mfma_f32_16x16x32_bf16 v[118:121], v[154:157], v[208:211], v[118:121]
	v_mfma_f32_16x16x32_bf16 v[114:117], v[162:165], v[208:211], v[114:117]
	v_mfma_f32_16x16x32_bf16 v[94:97], v[154:157], v[216:219], v[94:97]
	v_mfma_f32_16x16x32_bf16 v[90:93], v[162:165], v[216:219], v[90:93]
	v_mfma_f32_16x16x32_bf16 v[78:81], v[154:157], v[224:227], v[78:81]
	v_mfma_f32_16x16x32_bf16 v[74:77], v[162:165], v[224:227], v[74:77]
	v_mfma_f32_16x16x32_bf16 v[98:101], v[158:161], v[204:207], v[98:101]
	v_mfma_f32_16x16x32_bf16 v[106:109], v[166:169], v[204:207], v[106:109]
	v_mfma_f32_16x16x32_bf16 v[118:121], v[158:161], v[212:215], v[118:121]
	v_mfma_f32_16x16x32_bf16 v[114:117], v[166:169], v[212:215], v[114:117]
	v_mfma_f32_16x16x32_bf16 v[94:97], v[158:161], v[220:223], v[94:97]
	v_mfma_f32_16x16x32_bf16 v[90:93], v[166:169], v[220:223], v[90:93]
	v_mfma_f32_16x16x32_bf16 v[78:81], v[158:161], v[228:231], v[78:81]
	v_mfma_f32_16x16x32_bf16 v[74:77], v[166:169], v[228:231], v[74:77]
	v_mfma_f32_16x16x32_bf16 v[126:129], v[138:141], v[200:203], v[126:129]
	v_mfma_f32_16x16x32_bf16 v[122:125], v[146:149], v[200:203], v[122:125]
	v_mfma_f32_16x16x32_bf16 v[110:113], v[138:141], v[208:211], v[110:113]
	v_mfma_f32_16x16x32_bf16 v[102:105], v[146:149], v[208:211], v[102:105]
	v_mfma_f32_16x16x32_bf16 v[86:89], v[138:141], v[216:219], v[86:89]
	v_mfma_f32_16x16x32_bf16 v[82:85], v[146:149], v[216:219], v[82:85]
	v_mfma_f32_16x16x32_bf16 v[70:73], v[138:141], v[224:227], v[70:73]
	v_mfma_f32_16x16x32_bf16 v[66:69], v[146:149], v[224:227], v[66:69]
	v_mfma_f32_16x16x32_bf16 v[126:129], v[142:145], v[204:207], v[126:129]
	v_mfma_f32_16x16x32_bf16 v[122:125], v[150:153], v[204:207], v[122:125]
	v_mfma_f32_16x16x32_bf16 v[110:113], v[142:145], v[212:215], v[110:113]
	v_mfma_f32_16x16x32_bf16 v[102:105], v[150:153], v[212:215], v[102:105]
	v_mfma_f32_16x16x32_bf16 v[86:89], v[142:145], v[220:223], v[86:89]
	v_mfma_f32_16x16x32_bf16 v[82:85], v[150:153], v[220:223], v[82:85]
	v_mfma_f32_16x16x32_bf16 v[70:73], v[142:145], v[228:231], v[70:73]
	v_mfma_f32_16x16x32_bf16 v[66:69], v[150:153], v[228:231], v[66:69]
	s_setprio 0
	s_barrier
	s_cmp_lg_u32 s46, s83
	s_cbranch_scc1 .LBB0_985
	v_mov_b32_e32 v178, v194
	s_add_i32 m0, s79, 0x20000
	v_lshl_add_u64 v[130:131], s[36:37], 0, v[178:179]
	global_load_lds_dwordx4 v178, s[36:37]
	v_lshl_add_u64 v[130:131], v[130:131], 0, s[18:19]
	s_add_i32 m0, s79, 0x20400
	s_andn2_b64 vcc, exec, s[14:15]
	global_load_lds_dwordx4 v[130:131], off
	s_cbranch_vccnz .LBB0_985
	v_lshl_add_u64 v[130:131], s[38:39], 0, v[178:179]
	s_add_i32 m0, 0, 0x24000
	s_nop 0
	global_load_lds_dwordx4 v[130:131], off
	s_branch .LBB0_985

; #define PG8_STAGE(bufoff, gbase, voff) do { _Pragma("unroll") for (int _i = 0; _i < 2; ++_i) \
;         __builtin_amdgcn_global_load_lds((const unsigned*)((const char*)(gbase) + (voff)[_i]), (PG8_LAS unsigned*)(lds + (bufoff) + ldsw + _i * 8192), 16, 0, 0); } while (0)
; #define PG8_LDA(dst, b, h) do { _Pragma("unroll") for (int m = 0; m < 4; ++m) _Pragma("unroll") for (int k = 0; k < 2; ++k) dst[m][k] = *(const PG8_LAS bf16x8*)(lds + PG8_SA(b, h) + aoff + m * 2048 + k * 1024); } while (0)
; #define PG8_LDB(dst, b, h) do { _Pragma("unroll") for (int n = 0; n < 2; ++n) _Pragma("unroll") for (int k = 0; k < 2; ++k) dst[n][k] = *(const PG8_LAS bf16x8*)(lds + PG8_SB(b, h) + boff + n * 2048 + k * 1024); } while (0)
; #define PG8_MMA(ai, bj, At, Bt) do { __builtin_amdgcn_s_setprio(1); _Pragma("unroll") for (int m = 0; m < 4; ++m) _Pragma("unroll") for (int n = 0; n < 2; ++n) _Pragma("unroll") for (int k = 0; k < 2; ++k) \
;         acc[ai][bj][m][n] = __builtin_amdgcn_mfma_f32_16x16x32_bf16(Bt[n][k], At[m][k], acc[ai][bj][m][n], 0, 0, 0); __builtin_amdgcn_s_setprio(0); } while (0)
; #define PG8_WAIT_V(n) asm volatile("s_waitcnt vmcnt(" #n ")" ::: "memory")
; template <class Epi, class Sched, bool ALIGN_EPI = false, bool SP2 = false>
; __device__ __forceinline__ void gemm_phase(PG8_LAS unsigned char* lds, const Gemm g, const Sched& S, const Epi& E) {
;     ...
;             const bool last = (t == nt - 2);
;             const char* a1 = cA + (size_t)(t + 1) * kstepA;
;             const char* a2 = last ? nA : cA + (size_t)(t + 2) * kstepA; const char* b2 = last ? nB : cB + (size_t)(t + 2) * kstep;
;             const char* a3 = a2 + kstepA; const char* b3 = b2 + kstep;
;             if (last && has_next) S.a_ready(nxt);
;             if constexpr (SP2) {
;             PG8_LDB(B0, 0, 0); PG8_LDB(B1, 0, 1); PG8_SCHED; PG8_LDA(At, 0, 0); PG8_STAGE(PG8_SA(1, 1), a1 + hstep, voffA);
;             PG8_WAIT_V(8); PG8_WAIT_L(0); PG8_BAR; PG8_MMA(0, 0, At, B0); PG8_MMA(0, 1, At, B1); PG8_BAR; PG8_SCHED;
;             if constexpr (Epi::PREFETCH) { if (t == tpf) E.prefetch(cur, wid, lane); }
;             PG8_LDA(At, 0, 1); PG8_STAGE(PG8_SB(0, 0), b2, voffB); PG8_STAGE(PG8_SB(0, 1), b2 + hstep, voffB); PG8_STAGE(PG8_SA(0, 0), a2, voffA);
;             PG8_WAIT_V(8); PG8_WAIT_L(0); PG8_BAR; PG8_MMA(1, 0, At, B0); PG8_MMA(1, 1, At, B1); PG8_BAR; PG8_SCHED;
.LBB0_1068:
	s_add_u32 s35, s6, 0x100
	s_addc_u32 s36, s7, 0
	s_mov_b32 s37, -2
	s_waitcnt lgkmcnt(0)
	ds_read_b128 v[130:133], v192
	ds_read_b128 v[134:137], v192 offset:1024
	ds_read_b128 v[156:159], v192 offset:2048
	ds_read_b128 v[160:163], v192 offset:3072
	ds_read_b128 v[164:167], v193
	ds_read_b128 v[168:171], v193 offset:1024
	ds_read_b128 v[172:175], v193 offset:2048
	ds_read_b128 v[176:179], v193 offset:3072
	s_add_u32 s0, s4, 0x200
	s_addc_u32 s1, s5, 0
	s_cmp_eq_u32 s37, 40
	s_cselect_b32 s31, s27, s1
	s_cselect_b32 s30, s26, s0
	s_cselect_b32 s7, s29, s36
	s_cselect_b32 s6, s28, s35
	v_lshl_add_u64 v[188:189], s[4:5], 0, v[148:149]
	s_add_i32 m0, s45, 0xc000
	ds_read_b128 v[180:183], v194
	ds_read_b128 v[184:187], v194 offset:1024
	ds_read_b128 v[196:199], v194 offset:2048
	ds_read_b128 v[200:203], v194 offset:3072
	ds_read_b128 v[204:207], v194 offset:4096
	ds_read_b128 v[208:211], v194 offset:5120
	ds_read_b128 v[212:215], v194 offset:6144
	ds_read_b128 v[216:219], v194 offset:7168
	global_load_lds_dwordx4 v[188:189], off
	v_lshl_add_u64 v[188:189], s[4:5], 0, v[150:151]
	s_add_i32 m0, s45, 0xe000
	s_nop 0
	global_load_lds_dwordx4 v[188:189], off
	s_waitcnt vmcnt(8) lgkmcnt(0)
	s_barrier
	s_setprio 1
	v_mfma_f32_16x16x32_bf16 v[126:129], v[130:133], v[180:183], 0
	v_mfma_f32_16x16x32_bf16 v[122:125], v[156:159], v[180:183], 0
	v_mfma_f32_16x16x32_bf16 v[110:113], v[130:133], v[196:199], 0
	v_mfma_f32_16x16x32_bf16 v[106:109], v[156:159], v[196:199], 0
	v_mfma_f32_16x16x32_bf16 v[94:97], v[130:133], v[204:207], 0
	v_mfma_f32_16x16x32_bf16 v[90:93], v[156:159], v[204:207], 0
	v_mfma_f32_16x16x32_bf16 v[78:81], v[130:133], v[212:215], 0
	v_mfma_f32_16x16x32_bf16 v[74:77], v[156:159], v[212:215], 0
	v_mfma_f32_16x16x32_bf16 v[126:129], v[134:137], v[184:187], v[126:129]
	v_mfma_f32_16x16x32_bf16 v[122:125], v[160:163], v[184:187], v[122:125]
	v_mfma_f32_16x16x32_bf16 v[110:113], v[134:137], v[200:203], v[110:113]
	v_mfma_f32_16x16x32_bf16 v[106:109], v[160:163], v[200:203], v[106:109]
	v_mfma_f32_16x16x32_bf16 v[94:97], v[134:137], v[208:211], v[94:97]
	v_mfma_f32_16x16x32_bf16 v[90:93], v[160:163], v[208:211], v[90:93]
	v_mfma_f32_16x16x32_bf16 v[78:81], v[134:137], v[216:219], v[78:81]
	v_mfma_f32_16x16x32_bf16 v[74:77], v[160:163], v[216:219], v[74:77]
	v_mfma_f32_16x16x32_bf16 v[118:121], v[164:167], v[180:183], 0
	v_mfma_f32_16x16x32_bf16 v[114:117], v[172:175], v[180:183], 0
	v_mfma_f32_16x16x32_bf16 v[102:105], v[164:167], v[196:199], 0
	v_mfma_f32_16x16x32_bf16 v[98:101], v[172:175], v[196:199], 0
	v_mfma_f32_16x16x32_bf16 v[86:89], v[164:167], v[204:207], 0
	v_mfma_f32_16x16x32_bf16 v[82:85], v[172:175], v[204:207], 0
	v_mfma_f32_16x16x32_bf16 v[70:73], v[164:167], v[212:215], 0
	v_mfma_f32_16x16x32_bf16 v[66:69], v[172:175], v[212:215], 0
	v_mfma_f32_16x16x32_bf16 v[118:121], v[168:171], v[184:187], v[118:121]
	v_mfma_f32_16x16x32_bf16 v[114:117], v[176:179], v[184:187], v[114:117]
	v_mfma_f32_16x16x32_bf16 v[102:105], v[168:171], v[200:203], v[102:105]
	v_mfma_f32_16x16x32_bf16 v[98:101], v[176:179], v[200:203], v[98:101]
	v_mfma_f32_16x16x32_bf16 v[86:89], v[168:171], v[208:211], v[86:89]
	v_mfma_f32_16x16x32_bf16 v[82:85], v[176:179], v[208:211], v[82:85]
	v_mfma_f32_16x16x32_bf16 v[70:73], v[168:171], v[216:219], v[70:73]
	v_mfma_f32_16x16x32_bf16 v[66:69], v[176:179], v[216:219], v[66:69]
	s_setprio 0
	s_barrier
	s_add_i32 s4, s61, s44
	v_lshl_add_u64 v[188:189], s[6:7], 0, v[140:141]
	s_mov_b32 m0, s4
	ds_read_b128 v[180:183], v194 offset:16384
	ds_read_b128 v[184:187], v194 offset:17408
	ds_read_b128 v[196:199], v194 offset:18432
	ds_read_b128 v[200:203], v194 offset:19456
	ds_read_b128 v[204:207], v194 offset:20480
	ds_read_b128 v[208:211], v194 offset:21504
	ds_read_b128 v[212:215], v194 offset:22528
	ds_read_b128 v[216:219], v194 offset:23552
	global_load_lds_dwordx4 v[188:189], off
	s_add_i32 m0, s4, 0x2000
	s_add_u32 s4, s6, 0xb0000
	v_lshl_add_u64 v[220:221], s[6:7], 0, v[144:145]
	s_addc_u32 s5, s7, 0
	s_add_i32 s38, s62, s44
	global_load_lds_dwordx4 v[220:221], off
	v_lshl_add_u64 v[222:223], s[4:5], 0, v[140:141]
	s_mov_b32 m0, s38
	v_lshl_add_u64 v[224:225], s[30:31], 0, v[142:143]
	global_load_lds_dwordx4 v[222:223], off
	v_lshl_add_u64 v[222:223], s[4:5], 0, v[144:145]
	s_add_i32 m0, s38, 0x2000
	s_nop 0
	global_load_lds_dwordx4 v[222:223], off
	v_lshl_add_u64 v[222:223], s[30:31], 0, v[138:139]
	s_mov_b32 m0, s45
	s_nop 0
	global_load_lds_dwordx4 v[222:223], off
	s_mov_b32 m0, s46
	s_nop 0
	global_load_lds_dwordx4 v[224:225], off
	s_waitcnt vmcnt(8) lgkmcnt(0)
	s_barrier
	s_setprio 1
	v_mfma_f32_16x16x32_bf16 v[62:65], v[130:133], v[180:183], 0
	v_mfma_f32_16x16x32_bf16 v[58:61], v[156:159], v[180:183], 0
	v_mfma_f32_16x16x32_bf16 v[46:49], v[130:133], v[196:199], 0
	v_mfma_f32_16x16x32_bf16 v[42:45], v[156:159], v[196:199], 0
	v_mfma_f32_16x16x32_bf16 v[30:33], v[130:133], v[204:207], 0
	v_mfma_f32_16x16x32_bf16 v[26:29], v[156:159], v[204:207], 0
	v_mfma_f32_16x16x32_bf16 v[14:17], v[130:133], v[212:215], 0
	v_mfma_f32_16x16x32_bf16 v[10:13], v[156:159], v[212:215], 0
	v_mfma_f32_16x16x32_bf16 v[62:65], v[134:137], v[184:187], v[62:65]
	v_mfma_f32_16x16x32_bf16 v[58:61], v[160:163], v[184:187], v[58:61]
	v_mfma_f32_16x16x32_bf16 v[46:49], v[134:137], v[200:203], v[46:49]
	v_mfma_f32_16x16x32_bf16 v[42:45], v[160:163], v[200:203], v[42:45]
	v_mfma_f32_16x16x32_bf16 v[30:33], v[134:137], v[208:211], v[30:33]
	v_mfma_f32_16x16x32_bf16 v[26:29], v[160:163], v[208:211], v[26:29]
	v_mfma_f32_16x16x32_bf16 v[14:17], v[134:137], v[216:219], v[14:17]
	v_mfma_f32_16x16x32_bf16 v[10:13], v[160:163], v[216:219], v[10:13]
	v_mfma_f32_16x16x32_bf16 v[54:57], v[164:167], v[180:183], 0
	v_mfma_f32_16x16x32_bf16 v[50:53], v[172:175], v[180:183], 0
	v_mfma_f32_16x16x32_bf16 v[38:41], v[164:167], v[196:199], 0
	v_mfma_f32_16x16x32_bf16 v[34:37], v[172:175], v[196:199], 0
	v_mfma_f32_16x16x32_bf16 v[22:25], v[164:167], v[204:207], 0
	v_mfma_f32_16x16x32_bf16 v[18:21], v[172:175], v[204:207], 0
	v_mfma_f32_16x16x32_bf16 v[6:9], v[164:167], v[212:215], 0
	v_mfma_f32_16x16x32_bf16 v[2:5], v[172:175], v[212:215], 0
	v_mfma_f32_16x16x32_bf16 v[54:57], v[168:171], v[184:187], v[54:57]
	v_mfma_f32_16x16x32_bf16 v[50:53], v[176:179], v[184:187], v[50:53]
	v_mfma_f32_16x16x32_bf16 v[38:41], v[168:171], v[200:203], v[38:41]
	v_mfma_f32_16x16x32_bf16 v[34:37], v[176:179], v[200:203], v[34:37]
	v_mfma_f32_16x16x32_bf16 v[22:25], v[168:171], v[208:211], v[22:25]
	v_mfma_f32_16x16x32_bf16 v[18:21], v[176:179], v[208:211], v[18:21]
	v_mfma_f32_16x16x32_bf16 v[6:9], v[168:171], v[216:219], v[6:9]
	v_mfma_f32_16x16x32_bf16 v[2:5], v[176:179], v[216:219], v[2:5]
	s_setprio 0
	s_barrier
	s_branch .Lpz6_mid
; #define PG8_STAGE(bufoff, gbase, voff) do { _Pragma("unroll") for (int _i = 0; _i < 2; ++_i) \
;         __builtin_amdgcn_global_load_lds((const unsigned*)((const char*)(gbase) + (voff)[_i]), (PG8_LAS unsigned*)(lds + (bufoff) + ldsw + _i * 8192), 16, 0, 0); } while (0)
; #define PG8_LDA(dst, b, h) do { _Pragma("unroll") for (int m = 0; m < 4; ++m) _Pragma("unroll") for (int k = 0; k < 2; ++k) dst[m][k] = *(const PG8_LAS bf16x8*)(lds + PG8_SA(b, h) + aoff + m * 2048 + k * 1024); } while (0)
; #define PG8_LDB(dst, b, h) do { _Pragma("unroll") for (int n = 0; n < 2; ++n) _Pragma("unroll") for (int k = 0; k < 2; ++k) dst[n][k] = *(const PG8_LAS bf16x8*)(lds + PG8_SB(b, h) + boff + n * 2048 + k * 1024); } while (0)
; #define PG8_MMA(ai, bj, At, Bt) do { __builtin_amdgcn_s_setprio(1); _Pragma("unroll") for (int m = 0; m < 4; ++m) _Pragma("unroll") for (int n = 0; n < 2; ++n) _Pragma("unroll") for (int k = 0; k < 2; ++k) \
;         acc[ai][bj][m][n] = __builtin_amdgcn_mfma_f32_16x16x32_bf16(Bt[n][k], At[m][k], acc[ai][bj][m][n], 0, 0, 0); __builtin_amdgcn_s_setprio(0); } while (0)
; #define PG8_WAIT_V(n) asm volatile("s_waitcnt vmcnt(" #n ")" ::: "memory")
; #define PG8_WAIT_L(n) asm volatile("s_waitcnt lgkmcnt(" #n ")" ::: "memory")
; #define PG8_BAR __builtin_amdgcn_s_barrier()
; #define PG8_SCHED __builtin_amdgcn_sched_barrier(0)
;     __device__ __forceinline__ void prefetch(const Unit& u, int wid, int lane) const { epi_prefetch(scr, ssq, bias + (size_t)(u.pm >> 5) * NGU + u.pn * BM, u, wid, lane); }
; template <class Epi, class Sched, bool ALIGN_EPI = false, bool SP2 = false>
; __device__ __forceinline__ void gemm_phase(PG8_LAS unsigned char* lds, const Gemm g, const Sched& S, const Epi& E) {
;     ...
;             PG8_LDB(B0, 0, 0); PG8_LDB(B1, 0, 1); PG8_SCHED; PG8_LDA(At, 0, 0); PG8_STAGE(PG8_SA(1, 1), a1 + hstep, voffA);
;             PG8_WAIT_V(8); PG8_WAIT_L(0); PG8_BAR; PG8_MMA(0, 0, At, B0); PG8_MMA(0, 1, At, B1); PG8_BAR; PG8_SCHED;
;             if constexpr (Epi::PREFETCH) { if (t == tpf) E.prefetch(cur, wid, lane); }
;             PG8_LDA(At, 0, 1); PG8_STAGE(PG8_SB(0, 0), b2, voffB); PG8_STAGE(PG8_SB(0, 1), b2 + hstep, voffB); PG8_STAGE(PG8_SA(0, 0), a2, voffA);
;             PG8_WAIT_V(8); PG8_WAIT_L(0); PG8_BAR; PG8_MMA(1, 0, At, B0); PG8_MMA(1, 1, At, B1); PG8_BAR; PG8_SCHED;
.LBB0_1069:
	ds_read_b128 v[130:133], v192
	ds_read_b128 v[134:137], v192 offset:1024
	ds_read_b128 v[156:159], v192 offset:2048
	ds_read_b128 v[160:163], v192 offset:3072
	ds_read_b128 v[164:167], v193
	ds_read_b128 v[168:171], v193 offset:1024
	ds_read_b128 v[172:175], v193 offset:2048
	ds_read_b128 v[176:179], v193 offset:3072
	s_add_u32 s0, s4, 0x200
	s_addc_u32 s1, s5, 0
	s_cmp_eq_u32 s37, 40
	s_cselect_b32 s31, s27, s1
	s_cselect_b32 s30, s26, s0
	s_cselect_b32 s7, s29, s36
	s_cselect_b32 s6, s28, s35
	v_lshl_add_u64 v[188:189], s[4:5], 0, v[148:149]
	s_add_i32 m0, s45, 0xc000
	ds_read_b128 v[180:183], v194
	ds_read_b128 v[184:187], v194 offset:1024
	ds_read_b128 v[196:199], v194 offset:2048
	ds_read_b128 v[200:203], v194 offset:3072
	ds_read_b128 v[204:207], v194 offset:4096
	ds_read_b128 v[208:211], v194 offset:5120
	ds_read_b128 v[212:215], v194 offset:6144
	ds_read_b128 v[216:219], v194 offset:7168
	global_load_lds_dwordx4 v[188:189], off
	v_lshl_add_u64 v[188:189], s[4:5], 0, v[150:151]
	s_add_i32 m0, s45, 0xe000
	s_nop 0
	global_load_lds_dwordx4 v[188:189], off
	s_waitcnt vmcnt(8) lgkmcnt(0)
	s_barrier
	s_setprio 1
	v_mfma_f32_16x16x32_bf16 v[126:129], v[130:133], v[180:183], v[126:129]
	v_mfma_f32_16x16x32_bf16 v[122:125], v[156:159], v[180:183], v[122:125]
	v_mfma_f32_16x16x32_bf16 v[110:113], v[130:133], v[196:199], v[110:113]
	v_mfma_f32_16x16x32_bf16 v[106:109], v[156:159], v[196:199], v[106:109]
	v_mfma_f32_16x16x32_bf16 v[94:97], v[130:133], v[204:207], v[94:97]
	v_mfma_f32_16x16x32_bf16 v[90:93], v[156:159], v[204:207], v[90:93]
	v_mfma_f32_16x16x32_bf16 v[78:81], v[130:133], v[212:215], v[78:81]
	v_mfma_f32_16x16x32_bf16 v[74:77], v[156:159], v[212:215], v[74:77]
	v_mfma_f32_16x16x32_bf16 v[126:129], v[134:137], v[184:187], v[126:129]
	v_mfma_f32_16x16x32_bf16 v[122:125], v[160:163], v[184:187], v[122:125]
	v_mfma_f32_16x16x32_bf16 v[110:113], v[134:137], v[200:203], v[110:113]
	v_mfma_f32_16x16x32_bf16 v[106:109], v[160:163], v[200:203], v[106:109]
	v_mfma_f32_16x16x32_bf16 v[94:97], v[134:137], v[208:211], v[94:97]
	v_mfma_f32_16x16x32_bf16 v[90:93], v[160:163], v[208:211], v[90:93]
	v_mfma_f32_16x16x32_bf16 v[78:81], v[134:137], v[216:219], v[78:81]
	v_mfma_f32_16x16x32_bf16 v[74:77], v[160:163], v[216:219], v[74:77]
	v_mfma_f32_16x16x32_bf16 v[118:121], v[164:167], v[180:183], v[118:121]
	v_mfma_f32_16x16x32_bf16 v[114:117], v[172:175], v[180:183], v[114:117]
	v_mfma_f32_16x16x32_bf16 v[102:105], v[164:167], v[196:199], v[102:105]
	v_mfma_f32_16x16x32_bf16 v[98:101], v[172:175], v[196:199], v[98:101]
	v_mfma_f32_16x16x32_bf16 v[86:89], v[164:167], v[204:207], v[86:89]
	v_mfma_f32_16x16x32_bf16 v[82:85], v[172:175], v[204:207], v[82:85]
	v_mfma_f32_16x16x32_bf16 v[70:73], v[164:167], v[212:215], v[70:73]
	v_mfma_f32_16x16x32_bf16 v[66:69], v[172:175], v[212:215], v[66:69]
	v_mfma_f32_16x16x32_bf16 v[118:121], v[168:171], v[184:187], v[118:121]
	v_mfma_f32_16x16x32_bf16 v[114:117], v[176:179], v[184:187], v[114:117]
	v_mfma_f32_16x16x32_bf16 v[102:105], v[168:171], v[200:203], v[102:105]
	v_mfma_f32_16x16x32_bf16 v[98:101], v[176:179], v[200:203], v[98:101]
	v_mfma_f32_16x16x32_bf16 v[86:89], v[168:171], v[208:211], v[86:89]
	v_mfma_f32_16x16x32_bf16 v[82:85], v[176:179], v[208:211], v[82:85]
	v_mfma_f32_16x16x32_bf16 v[70:73], v[168:171], v[216:219], v[70:73]
	v_mfma_f32_16x16x32_bf16 v[66:69], v[176:179], v[216:219], v[66:69]
	s_setprio 0
	s_barrier
	s_add_i32 s4, s61, s44
	v_lshl_add_u64 v[188:189], s[6:7], 0, v[140:141]
	s_mov_b32 m0, s4
	ds_read_b128 v[180:183], v194 offset:16384
	ds_read_b128 v[184:187], v194 offset:17408
	ds_read_b128 v[196:199], v194 offset:18432
	ds_read_b128 v[200:203], v194 offset:19456
	ds_read_b128 v[204:207], v194 offset:20480
	ds_read_b128 v[208:211], v194 offset:21504
	ds_read_b128 v[212:215], v194 offset:22528
	ds_read_b128 v[216:219], v194 offset:23552
	global_load_lds_dwordx4 v[188:189], off
	s_add_i32 m0, s4, 0x2000
	s_add_u32 s4, s6, 0xb0000
	v_lshl_add_u64 v[220:221], s[6:7], 0, v[144:145]
	s_addc_u32 s5, s7, 0
	s_add_i32 s38, s62, s44
	global_load_lds_dwordx4 v[220:221], off
	v_lshl_add_u64 v[222:223], s[4:5], 0, v[140:141]
	s_mov_b32 m0, s38
	v_lshl_add_u64 v[224:225], s[30:31], 0, v[142:143]
	global_load_lds_dwordx4 v[222:223], off
	v_lshl_add_u64 v[222:223], s[4:5], 0, v[144:145]
	s_add_i32 m0, s38, 0x2000
	s_nop 0
	global_load_lds_dwordx4 v[222:223], off
	v_lshl_add_u64 v[222:223], s[30:31], 0, v[138:139]
	s_mov_b32 m0, s45
	s_nop 0
	global_load_lds_dwordx4 v[222:223], off
	s_mov_b32 m0, s46
	s_nop 0
	global_load_lds_dwordx4 v[224:225], off
	s_waitcnt vmcnt(8) lgkmcnt(0)
	s_barrier
	s_setprio 1
	v_mfma_f32_16x16x32_bf16 v[62:65], v[130:133], v[180:183], v[62:65]
	v_mfma_f32_16x16x32_bf16 v[58:61], v[156:159], v[180:183], v[58:61]
	v_mfma_f32_16x16x32_bf16 v[46:49], v[130:133], v[196:199], v[46:49]
	v_mfma_f32_16x16x32_bf16 v[42:45], v[156:159], v[196:199], v[42:45]
	v_mfma_f32_16x16x32_bf16 v[30:33], v[130:133], v[204:207], v[30:33]
	v_mfma_f32_16x16x32_bf16 v[26:29], v[156:159], v[204:207], v[26:29]
	v_mfma_f32_16x16x32_bf16 v[14:17], v[130:133], v[212:215], v[14:17]
	v_mfma_f32_16x16x32_bf16 v[10:13], v[156:159], v[212:215], v[10:13]
	v_mfma_f32_16x16x32_bf16 v[62:65], v[134:137], v[184:187], v[62:65]
	v_mfma_f32_16x16x32_bf16 v[58:61], v[160:163], v[184:187], v[58:61]
	v_mfma_f32_16x16x32_bf16 v[46:49], v[134:137], v[200:203], v[46:49]
	v_mfma_f32_16x16x32_bf16 v[42:45], v[160:163], v[200:203], v[42:45]
	v_mfma_f32_16x16x32_bf16 v[30:33], v[134:137], v[208:211], v[30:33]
	v_mfma_f32_16x16x32_bf16 v[26:29], v[160:163], v[208:211], v[26:29]
	v_mfma_f32_16x16x32_bf16 v[14:17], v[134:137], v[216:219], v[14:17]
	v_mfma_f32_16x16x32_bf16 v[10:13], v[160:163], v[216:219], v[10:13]
	v_mfma_f32_16x16x32_bf16 v[54:57], v[164:167], v[180:183], v[54:57]
	v_mfma_f32_16x16x32_bf16 v[50:53], v[172:175], v[180:183], v[50:53]
	v_mfma_f32_16x16x32_bf16 v[38:41], v[164:167], v[196:199], v[38:41]
	v_mfma_f32_16x16x32_bf16 v[34:37], v[172:175], v[196:199], v[34:37]
	v_mfma_f32_16x16x32_bf16 v[22:25], v[164:167], v[204:207], v[22:25]
	v_mfma_f32_16x16x32_bf16 v[18:21], v[172:175], v[204:207], v[18:21]
	v_mfma_f32_16x16x32_bf16 v[6:9], v[164:167], v[212:215], v[6:9]
	v_mfma_f32_16x16x32_bf16 v[2:5], v[172:175], v[212:215], v[2:5]
	v_mfma_f32_16x16x32_bf16 v[54:57], v[168:171], v[184:187], v[54:57]
	v_mfma_f32_16x16x32_bf16 v[50:53], v[176:179], v[184:187], v[50:53]
	v_mfma_f32_16x16x32_bf16 v[38:41], v[168:171], v[200:203], v[38:41]
	v_mfma_f32_16x16x32_bf16 v[34:37], v[176:179], v[200:203], v[34:37]
	v_mfma_f32_16x16x32_bf16 v[22:25], v[168:171], v[208:211], v[22:25]
	v_mfma_f32_16x16x32_bf16 v[18:21], v[176:179], v[208:211], v[18:21]
	v_mfma_f32_16x16x32_bf16 v[6:9], v[168:171], v[216:219], v[6:9]
	v_mfma_f32_16x16x32_bf16 v[2:5], v[176:179], v[216:219], v[2:5]
	s_setprio 0
	s_barrier
; #define PG8_STAGE(bufoff, gbase, voff) do { _Pragma("unroll") for (int _i = 0; _i < 2; ++_i) \
;         __builtin_amdgcn_global_load_lds((const unsigned*)((const char*)(gbase) + (voff)[_i]), (PG8_LAS unsigned*)(lds + (bufoff) + ldsw + _i * 8192), 16, 0, 0); } while (0)
; #define PG8_LDA(dst, b, h) do { _Pragma("unroll") for (int m = 0; m < 4; ++m) _Pragma("unroll") for (int k = 0; k < 2; ++k) dst[m][k] = *(const PG8_LAS bf16x8*)(lds + PG8_SA(b, h) + aoff + m * 2048 + k * 1024); } while (0)
; #define PG8_LDB(dst, b, h) do { _Pragma("unroll") for (int n = 0; n < 2; ++n) _Pragma("unroll") for (int k = 0; k < 2; ++k) dst[n][k] = *(const PG8_LAS bf16x8*)(lds + PG8_SB(b, h) + boff + n * 2048 + k * 1024); } while (0)
; #define PG8_MMA(ai, bj, At, Bt) do { __builtin_amdgcn_s_setprio(1); _Pragma("unroll") for (int m = 0; m < 4; ++m) _Pragma("unroll") for (int n = 0; n < 2; ++n) _Pragma("unroll") for (int k = 0; k < 2; ++k) \
;         acc[ai][bj][m][n] = __builtin_amdgcn_mfma_f32_16x16x32_bf16(Bt[n][k], At[m][k], acc[ai][bj][m][n], 0, 0, 0); __builtin_amdgcn_s_setprio(0); } while (0)
; #define PG8_WAIT_V(n) asm volatile("s_waitcnt vmcnt(" #n ")" ::: "memory")
; #define PG8_WAIT_L(n) asm volatile("s_waitcnt lgkmcnt(" #n ")" ::: "memory")
; #define PG8_BAR __builtin_amdgcn_s_barrier()
; #define PG8_SCHED __builtin_amdgcn_sched_barrier(0)
; template <class Epi, class Sched, bool ALIGN_EPI = false, bool SP2 = false>
; __device__ __forceinline__ void gemm_phase(PG8_LAS unsigned char* lds, const Gemm g, const Sched& S, const Epi& E) {
;     ...
;             PG8_LDB(B0, 1, 0); PG8_LDB(B1, 1, 1); PG8_SCHED; PG8_LDA(At, 1, 0); PG8_STAGE(PG8_SA(0, 1), a2 + hstep, voffA);
;             PG8_WAIT_V(8); PG8_WAIT_L(0); PG8_BAR; PG8_MMA(0, 0, At, B0); PG8_MMA(0, 1, At, B1); PG8_BAR; PG8_SCHED;
.Lpz6_mid:
	s_add_i32 s38, 0, 0x18000
	v_add_u32_e32 v146, s38, v191
	s_add_i32 s39, 0, 0x1c000
	ds_read_b128 v[130:133], v146
	ds_read_b128 v[134:137], v146 offset:1024
	ds_read_b128 v[156:159], v146 offset:2048
	ds_read_b128 v[160:163], v146 offset:3072
	v_add_u32_e32 v146, s39, v191
	ds_read_b128 v[164:167], v146
	ds_read_b128 v[168:171], v146 offset:1024
	ds_read_b128 v[172:175], v146 offset:2048
	ds_read_b128 v[176:179], v146 offset:3072
	s_add_u32 s4, s30, 0xb0000
	s_addc_u32 s5, s31, 0
	s_mov_b32 m0, s47
	v_lshl_add_u64 v[226:227], s[4:5], 0, v[138:139]
	ds_read_b128 v[180:183], v194 offset:32768
	ds_read_b128 v[184:187], v194 offset:33792
	ds_read_b128 v[196:199], v194 offset:34816
	ds_read_b128 v[200:203], v194 offset:35840
	ds_read_b128 v[204:207], v194 offset:36864
	ds_read_b128 v[208:211], v194 offset:37888
	ds_read_b128 v[212:215], v194 offset:38912
	ds_read_b128 v[216:219], v194 offset:39936
	global_load_lds_dwordx4 v[226:227], off
	v_lshl_add_u64 v[226:227], s[4:5], 0, v[142:143]
	s_mov_b32 m0, s48
	s_nop 0
	global_load_lds_dwordx4 v[226:227], off
	s_waitcnt vmcnt(8) lgkmcnt(0)
	s_barrier
	s_setprio 1
	v_mfma_f32_16x16x32_bf16 v[126:129], v[130:133], v[180:183], v[126:129]
	v_mfma_f32_16x16x32_bf16 v[122:125], v[156:159], v[180:183], v[122:125]
	v_mfma_f32_16x16x32_bf16 v[110:113], v[130:133], v[196:199], v[110:113]
	v_mfma_f32_16x16x32_bf16 v[106:109], v[156:159], v[196:199], v[106:109]
	v_mfma_f32_16x16x32_bf16 v[94:97], v[130:133], v[204:207], v[94:97]
	v_mfma_f32_16x16x32_bf16 v[90:93], v[156:159], v[204:207], v[90:93]
	v_mfma_f32_16x16x32_bf16 v[78:81], v[130:133], v[212:215], v[78:81]
	v_mfma_f32_16x16x32_bf16 v[74:77], v[156:159], v[212:215], v[74:77]
	v_mfma_f32_16x16x32_bf16 v[126:129], v[134:137], v[184:187], v[126:129]
	v_mfma_f32_16x16x32_bf16 v[122:125], v[160:163], v[184:187], v[122:125]
	v_mfma_f32_16x16x32_bf16 v[110:113], v[134:137], v[200:203], v[110:113]
	v_mfma_f32_16x16x32_bf16 v[106:109], v[160:163], v[200:203], v[106:109]
	v_mfma_f32_16x16x32_bf16 v[94:97], v[134:137], v[208:211], v[94:97]
	v_mfma_f32_16x16x32_bf16 v[90:93], v[160:163], v[208:211], v[90:93]
	v_mfma_f32_16x16x32_bf16 v[78:81], v[134:137], v[216:219], v[78:81]
	v_mfma_f32_16x16x32_bf16 v[74:77], v[160:163], v[216:219], v[74:77]
	v_mfma_f32_16x16x32_bf16 v[118:121], v[164:167], v[180:183], v[118:121]
	v_mfma_f32_16x16x32_bf16 v[114:117], v[172:175], v[180:183], v[114:117]
	v_mfma_f32_16x16x32_bf16 v[102:105], v[164:167], v[196:199], v[102:105]
	v_mfma_f32_16x16x32_bf16 v[98:101], v[172:175], v[196:199], v[98:101]
	v_mfma_f32_16x16x32_bf16 v[86:89], v[164:167], v[204:207], v[86:89]
	v_mfma_f32_16x16x32_bf16 v[82:85], v[172:175], v[204:207], v[82:85]
	v_mfma_f32_16x16x32_bf16 v[70:73], v[164:167], v[212:215], v[70:73]
	v_mfma_f32_16x16x32_bf16 v[66:69], v[172:175], v[212:215], v[66:69]
	v_mfma_f32_16x16x32_bf16 v[118:121], v[168:171], v[184:187], v[118:121]
	v_mfma_f32_16x16x32_bf16 v[114:117], v[176:179], v[184:187], v[114:117]
	v_mfma_f32_16x16x32_bf16 v[102:105], v[168:171], v[200:203], v[102:105]
	v_mfma_f32_16x16x32_bf16 v[98:101], v[176:179], v[200:203], v[98:101]
	v_mfma_f32_16x16x32_bf16 v[86:89], v[168:171], v[208:211], v[86:89]
	v_mfma_f32_16x16x32_bf16 v[82:85], v[176:179], v[208:211], v[82:85]
	v_mfma_f32_16x16x32_bf16 v[70:73], v[168:171], v[216:219], v[70:73]
	v_mfma_f32_16x16x32_bf16 v[66:69], v[176:179], v[216:219], v[66:69]
	s_setprio 0
	s_barrier
; #define PG8_STAGE(bufoff, gbase, voff) do { _Pragma("unroll") for (int _i = 0; _i < 2; ++_i) \
;         __builtin_amdgcn_global_load_lds((const unsigned*)((const char*)(gbase) + (voff)[_i]), (PG8_LAS unsigned*)(lds + (bufoff) + ldsw + _i * 8192), 16, 0, 0); } while (0)
; #define PG8_LDA(dst, b, h) do { _Pragma("unroll") for (int m = 0; m < 4; ++m) _Pragma("unroll") for (int k = 0; k < 2; ++k) dst[m][k] = *(const PG8_LAS bf16x8*)(lds + PG8_SA(b, h) + aoff + m * 2048 + k * 1024); } while (0)
; #define PG8_MMA(ai, bj, At, Bt) do { __builtin_amdgcn_s_setprio(1); _Pragma("unroll") for (int m = 0; m < 4; ++m) _Pragma("unroll") for (int n = 0; n < 2; ++n) _Pragma("unroll") for (int k = 0; k < 2; ++k) \
;         acc[ai][bj][m][n] = __builtin_amdgcn_mfma_f32_16x16x32_bf16(Bt[n][k], At[m][k], acc[ai][bj][m][n], 0, 0, 0); __builtin_amdgcn_s_setprio(0); } while (0)
; #define PG8_WAIT_V(n) asm volatile("s_waitcnt vmcnt(" #n ")" ::: "memory")
; #define PG8_WAIT_L(n) asm volatile("s_waitcnt lgkmcnt(" #n ")" ::: "memory")
; #define PG8_BAR __builtin_amdgcn_s_barrier()
; #define PG8_SCHED __builtin_amdgcn_sched_barrier(0)
; template <class Epi, class Sched, bool ALIGN_EPI = false, bool SP2 = false>
; __device__ __forceinline__ void gemm_phase(PG8_LAS unsigned char* lds, const Gemm g, const Sched& S, const Epi& E) {
;     ...
;             PG8_LDA(At, 1, 1); PG8_STAGE(PG8_SB(1, 0), b3, voffB); PG8_STAGE(PG8_SB(1, 1), b3 + hstep, voffB); PG8_STAGE(PG8_SA(1, 0), a3, voffA);
;             PG8_WAIT_V(8); PG8_WAIT_L(0); PG8_BAR; PG8_MMA(1, 0, At, B0); PG8_MMA(1, 1, At, B1); PG8_BAR; PG8_SCHED;
;     ...
;         }
;         if constexpr (ALIGN_EPI) { if (wr == 0) PG8_BAR; }
	s_add_i32 s4, s38, s44
	v_lshl_add_u64 v[188:189], v[188:189], 0, s[18:19]
	s_mov_b32 m0, s4
	ds_read_b128 v[180:183], v194 offset:49152
	ds_read_b128 v[184:187], v194 offset:50176
	ds_read_b128 v[196:199], v194 offset:51200
	ds_read_b128 v[200:203], v194 offset:52224
	ds_read_b128 v[204:207], v194 offset:53248
	ds_read_b128 v[208:211], v194 offset:54272
	ds_read_b128 v[212:215], v194 offset:55296
	ds_read_b128 v[216:219], v194 offset:56320
	global_load_lds_dwordx4 v[188:189], off
	s_add_i32 m0, s4, 0x2000
	s_add_u32 s4, s6, 0xb0080
	v_lshl_add_u64 v[188:189], v[220:221], 0, s[18:19]
	s_addc_u32 s5, s7, 0
	s_add_i32 s6, s39, s44
	global_load_lds_dwordx4 v[188:189], off
	v_lshl_add_u64 v[188:189], s[4:5], 0, v[140:141]
	s_mov_b32 m0, s6
	s_nop 0
	global_load_lds_dwordx4 v[188:189], off
	v_lshl_add_u64 v[188:189], s[4:5], 0, v[144:145]
	s_add_i32 m0, s6, 0x2000
	s_nop 0
	global_load_lds_dwordx4 v[188:189], off
	v_lshl_add_u64 v[188:189], v[222:223], 0, s[20:21]
	s_mov_b32 m0, s55
	s_nop 0
	global_load_lds_dwordx4 v[188:189], off
	v_lshl_add_u64 v[188:189], v[224:225], 0, s[20:21]
	s_mov_b32 m0, s56
	s_nop 0
	global_load_lds_dwordx4 v[188:189], off
	s_waitcnt vmcnt(8) lgkmcnt(0)
	s_barrier
	s_setprio 1
	v_mfma_f32_16x16x32_bf16 v[62:65], v[130:133], v[180:183], v[62:65]
	v_mfma_f32_16x16x32_bf16 v[58:61], v[156:159], v[180:183], v[58:61]
	v_mfma_f32_16x16x32_bf16 v[46:49], v[130:133], v[196:199], v[46:49]
	v_mfma_f32_16x16x32_bf16 v[42:45], v[156:159], v[196:199], v[42:45]
	v_mfma_f32_16x16x32_bf16 v[30:33], v[130:133], v[204:207], v[30:33]
	v_mfma_f32_16x16x32_bf16 v[26:29], v[156:159], v[204:207], v[26:29]
	v_mfma_f32_16x16x32_bf16 v[14:17], v[130:133], v[212:215], v[14:17]
	v_mfma_f32_16x16x32_bf16 v[10:13], v[156:159], v[212:215], v[10:13]
	v_mfma_f32_16x16x32_bf16 v[62:65], v[134:137], v[184:187], v[62:65]
	v_mfma_f32_16x16x32_bf16 v[58:61], v[160:163], v[184:187], v[58:61]
	v_mfma_f32_16x16x32_bf16 v[46:49], v[134:137], v[200:203], v[46:49]
	v_mfma_f32_16x16x32_bf16 v[42:45], v[160:163], v[200:203], v[42:45]
	v_mfma_f32_16x16x32_bf16 v[30:33], v[134:137], v[208:211], v[30:33]
	v_mfma_f32_16x16x32_bf16 v[26:29], v[160:163], v[208:211], v[26:29]
	v_mfma_f32_16x16x32_bf16 v[14:17], v[134:137], v[216:219], v[14:17]
	v_mfma_f32_16x16x32_bf16 v[10:13], v[160:163], v[216:219], v[10:13]
	v_mfma_f32_16x16x32_bf16 v[54:57], v[164:167], v[180:183], v[54:57]
	v_mfma_f32_16x16x32_bf16 v[50:53], v[172:175], v[180:183], v[50:53]
	v_mfma_f32_16x16x32_bf16 v[38:41], v[164:167], v[196:199], v[38:41]
	v_mfma_f32_16x16x32_bf16 v[34:37], v[172:175], v[196:199], v[34:37]
	v_mfma_f32_16x16x32_bf16 v[22:25], v[164:167], v[204:207], v[22:25]
	v_mfma_f32_16x16x32_bf16 v[18:21], v[172:175], v[204:207], v[18:21]
	v_mfma_f32_16x16x32_bf16 v[6:9], v[164:167], v[212:215], v[6:9]
	v_mfma_f32_16x16x32_bf16 v[2:5], v[172:175], v[212:215], v[2:5]
	v_mfma_f32_16x16x32_bf16 v[54:57], v[168:171], v[184:187], v[54:57]
	v_mfma_f32_16x16x32_bf16 v[50:53], v[176:179], v[184:187], v[50:53]
	v_mfma_f32_16x16x32_bf16 v[38:41], v[168:171], v[200:203], v[38:41]
	v_mfma_f32_16x16x32_bf16 v[34:37], v[176:179], v[200:203], v[34:37]
	v_mfma_f32_16x16x32_bf16 v[22:25], v[168:171], v[208:211], v[22:25]
	v_mfma_f32_16x16x32_bf16 v[18:21], v[176:179], v[208:211], v[18:21]
	v_mfma_f32_16x16x32_bf16 v[6:9], v[168:171], v[216:219], v[6:9]
	v_mfma_f32_16x16x32_bf16 v[2:5], v[176:179], v[216:219], v[2:5]
	s_setprio 0
	s_barrier
	s_add_i32 s37, s37, 2
	s_add_u32 s35, s35, 0x100
	s_addc_u32 s36, s36, 0
	s_cmp_gt_u32 s37, 41
	s_mov_b64 s[4:5], s[0:1]
	s_cbranch_scc0 .LBB0_1069
	s_and_b64 vcc, exec, s[22:23]
	s_cbranch_vccz .LBB0_1072
	s_barrier
